# nt (non-temporal) on the once-read f32 weight loads of the layer-0 and in-kernel next-layer bf16 conversions
# baseline (speedup 1.0000x reference)
; #define LAS __attribute__((address_space(3)))
; template <int MODE>
; __device__ __forceinline__ void p0_item(const float* W, int K, int N, bf16u* WT, const float* ks, LAS float* scr, int item, int lane) {
;     const int nblk = N / 64, kb = item / nblk, nb = item - kb * nblk, k0 = 64 * kb, n0 = 64 * nb;
;     int nn = n0 + lane;
;     if (MODE == 1) {
;         if (nn < 2048) { const int p = nn & 63; if (p < 16) nn = (nn & ~15) | (p & 3) | ((p & 4) << 1) | ((p & 8) >> 1); }
;         else if (nn >= 4096) { const int sec = nn >= 6144 ? 6144 : 4096, r = nn - sec, q = r & 255; nn = sec + ((q >> 7) << 10) + 128 * (r >> 8) + (q & 127); }
;     }
;     int drow = n0;
;     if (MODE == 2) drow = 256 * (n0 >> 7) + (n0 & 127);
;     if (MODE == 3) drow = 256 * (n0 >> 7) + 128 + (n0 & 127);
;     const float* src = W + (size_t)k0 * N + nn;
;     float v[64];
; #pragma unroll
;     for (int kk = 0; kk < 64; ++kk) v[kk] = src[(size_t)kk * N];
.LBB0_10:
	s_add_i32 s14, s23, 0xdc0
	s_cmpk_gt_i32 s14, 0x7ff
	s_mov_b64 s[12:13], -1
	s_cbranch_scc0 .LBB0_36
	s_cmpk_gt_u32 s14, 0x8ff
	s_cbranch_scc0 .LBB0_33
	s_cmpk_gt_u32 s14, 0x9ff
	s_cbranch_scc0 .LBB0_30
	s_cmpk_gt_u32 s14, 0xaff
	s_cbranch_scc0 .LBB0_27
	s_cmpk_gt_u32 s14, 0xdbf
	s_cbranch_scc0 .LBB0_22
	s_cmpk_gt_u32 s14, 0x107f
	s_cbranch_scc0 .LBB0_17
	v_readlane_b32 s0, v253, 18
	v_readlane_b32 s1, v253, 19
	s_mov_b32 vcc_lo, s72
	s_mov_b32 s88, s74
	s_load_dwordx8 s[72:79], s[0:1], 0x80
	s_add_i32 s10, s18, 0xffffbe00
	s_add_i32 s12, s17, s80
	s_and_b32 s10, s10, 0xfc0
	s_add_i32 s12, s12, 0xfffbe000
	s_and_b32 s12, s12, 0x3c0
	s_lshl_b32 s13, s10, 12
	v_or_b32_e32 v2, s12, v1
	s_waitcnt lgkmcnt(0)
	s_mov_b32 s74, s88
	s_add_u32 s88, s72, s13
	s_addc_u32 s89, s73, 0
	v_lshlrev_b32_e32 v2, 2, v2
	v_lshl_add_u64 v[16:17], s[88:89], 0, v[2:3]
	s_mov_b32 s72, vcc_lo
	v_add_co_u32_e32 v18, vcc, s30, v16
	s_lshl_b32 s10, s10, 1
	s_nop 0
	v_addc_co_u32_e32 v19, vcc, 0, v17, vcc
	v_add_co_u32_e32 v20, vcc, s31, v16
	s_mov_b32 s1, 0xb000
	s_nop 0
	v_addc_co_u32_e32 v21, vcc, 0, v17, vcc
	v_add_co_u32_e32 v22, vcc, s35, v16
	s_movk_i32 s0, 0x5000
	s_nop 0
	v_addc_co_u32_e32 v23, vcc, 0, v17, vcc
	global_load_dword v2, v2, s[88:89] nt
	s_nop 0
	global_load_dword v26, v[18:19], off offset:-4096 nt
	global_load_dword v27, v[18:19], off nt
	global_load_dword v28, v[20:21], off offset:-4096 nt
	global_load_dword v29, v[20:21], off nt
	global_load_dword v30, v[22:23], off offset:-4096 nt
	global_load_dword v31, v[22:23], off nt
	v_add_co_u32_e32 v18, vcc, s36, v16
	s_mov_b32 s79, 0x29000
	s_nop 0
	v_addc_co_u32_e32 v19, vcc, 0, v17, vcc
	v_add_co_u32_e32 v20, vcc, s37, v16
	s_mov_b32 s78, 0x23000
	s_nop 0
	v_addc_co_u32_e32 v21, vcc, 0, v17, vcc
	v_add_co_u32_e32 v22, vcc, s39, v16
	s_mov_b32 s77, 0x21000
	s_nop 0
	v_addc_co_u32_e32 v23, vcc, 0, v17, vcc
	v_add_co_u32_e32 v24, vcc, s41, v16
	s_mov_b32 s76, 0x1b000
	s_nop 0
	v_addc_co_u32_e32 v25, vcc, 0, v17, vcc
	global_load_dword v32, v[18:19], off offset:-4096 nt
	global_load_dword v33, v[18:19], off nt
	global_load_dword v34, v[20:21], off offset:-4096 nt
	global_load_dword v35, v[20:21], off nt
	global_load_dword v36, v[22:23], off offset:-4096 nt
	global_load_dword v37, v[22:23], off nt
	global_load_dword v38, v[24:25], off offset:-4096 nt
	global_load_dword v39, v[24:25], off nt
	v_add_co_u32_e32 v18, vcc, s42, v16
	s_mov_b32 s75, 0x13000
	s_nop 0
	v_addc_co_u32_e32 v19, vcc, 0, v17, vcc
	v_add_co_u32_e32 v20, vcc, s43, v16
	s_mov_b32 s73, 0xd000
	s_nop 0
	v_addc_co_u32_e32 v21, vcc, 0, v17, vcc
	v_add_co_u32_e32 v22, vcc, s45, v16
	s_nop 1
	v_addc_co_u32_e32 v23, vcc, 0, v17, vcc
	v_add_co_u32_e32 v24, vcc, s46, v16
	s_nop 1
	v_addc_co_u32_e32 v25, vcc, 0, v17, vcc
	global_load_dword v40, v[18:19], off offset:-4096 nt
	global_load_dword v41, v[18:19], off nt
	global_load_dword v42, v[20:21], off offset:-4096 nt
	global_load_dword v43, v[20:21], off nt
	global_load_dword v44, v[22:23], off offset:-4096 nt
	global_load_dword v45, v[22:23], off nt
	global_load_dword v46, v[24:25], off offset:-4096 nt
	global_load_dword v47, v[24:25], off nt
	v_add_co_u32_e32 v18, vcc, s47, v16
	s_nop 1
	v_addc_co_u32_e32 v19, vcc, 0, v17, vcc
	v_add_co_u32_e32 v20, vcc, s95, v16
	s_nop 1
	v_addc_co_u32_e32 v21, vcc, 0, v17, vcc
	v_add_co_u32_e32 v22, vcc, s33, v16
	s_nop 1
	v_addc_co_u32_e32 v23, vcc, 0, v17, vcc
	v_add_co_u32_e32 v24, vcc, s38, v16
	s_nop 1
	v_addc_co_u32_e32 v25, vcc, 0, v17, vcc
	global_load_dword v48, v[18:19], off offset:-4096 nt
	global_load_dword v49, v[18:19], off nt
	global_load_dword v50, v[20:21], off offset:-4096 nt
	global_load_dword v51, v[20:21], off nt
	global_load_dword v52, v[22:23], off offset:-4096 nt
	global_load_dword v53, v[22:23], off nt
	global_load_dword v54, v[24:25], off offset:-4096 nt
	global_load_dword v55, v[24:25], off nt
	v_add_co_u32_e32 v18, vcc, s40, v16
	s_nop 1
	v_addc_co_u32_e32 v19, vcc, 0, v17, vcc
	v_add_co_u32_e32 v20, vcc, s44, v16
	s_nop 1
	v_addc_co_u32_e32 v21, vcc, 0, v17, vcc
	v_add_co_u32_e32 v22, vcc, s64, v16
	s_nop 1
	v_addc_co_u32_e32 v23, vcc, 0, v17, vcc
	v_add_co_u32_e32 v24, vcc, s68, v16
	s_nop 1
	v_addc_co_u32_e32 v25, vcc, 0, v17, vcc
	global_load_dword v56, v[18:19], off offset:-4096 nt
	global_load_dword v57, v[18:19], off nt
	global_load_dword v58, v[20:21], off offset:-4096 nt
	global_load_dword v59, v[20:21], off nt
	global_load_dword v60, v[22:23], off offset:-4096 nt
	global_load_dword v61, v[22:23], off nt
	global_load_dword v62, v[24:25], off offset:-4096 nt
	global_load_dword v63, v[24:25], off nt
	v_add_co_u32_e32 v18, vcc, s70, v16
	s_nop 1
	v_addc_co_u32_e32 v19, vcc, 0, v17, vcc
	v_add_co_u32_e32 v20, vcc, s85, v16
	s_nop 1
	v_addc_co_u32_e32 v21, vcc, 0, v17, vcc
	v_add_co_u32_e32 v22, vcc, s87, v16
	s_nop 1
	v_addc_co_u32_e32 v23, vcc, 0, v17, vcc
	v_add_co_u32_e32 v24, vcc, s90, v16
	s_nop 1
	v_addc_co_u32_e32 v25, vcc, 0, v17, vcc
	global_load_dword v64, v[18:19], off offset:-4096 nt
	global_load_dword v65, v[18:19], off nt
	global_load_dword v66, v[20:21], off offset:-4096 nt
	global_load_dword v67, v[20:21], off nt
	global_load_dword v68, v[22:23], off offset:-4096 nt
	global_load_dword v69, v[22:23], off nt
	global_load_dword v70, v[24:25], off offset:-4096 nt
	global_load_dword v71, v[24:25], off nt
	v_add_co_u32_e32 v18, vcc, s92, v16
	s_nop 1
	v_addc_co_u32_e32 v19, vcc, 0, v17, vcc
	v_add_co_u32_e32 v20, vcc, s65, v16
	s_nop 1
	v_addc_co_u32_e32 v21, vcc, 0, v17, vcc
	v_add_co_u32_e32 v22, vcc, s66, v16
	s_nop 1
	v_addc_co_u32_e32 v23, vcc, 0, v17, vcc
	v_add_co_u32_e32 v24, vcc, s67, v16
	s_nop 1
	v_addc_co_u32_e32 v25, vcc, 0, v17, vcc
	global_load_dword v72, v[18:19], off offset:-4096 nt
	global_load_dword v73, v[18:19], off nt
	global_load_dword v74, v[20:21], off offset:-4096 nt
	global_load_dword v75, v[20:21], off nt
	global_load_dword v76, v[22:23], off offset:-4096 nt
	global_load_dword v77, v[22:23], off nt
	global_load_dword v78, v[24:25], off offset:-4096 nt
	global_load_dword v79, v[24:25], off nt
	v_add_co_u32_e32 v18, vcc, s69, v16
	s_nop 1
	v_addc_co_u32_e32 v19, vcc, 0, v17, vcc
	v_add_co_u32_e32 v20, vcc, s71, v16
	s_nop 1
	v_addc_co_u32_e32 v21, vcc, 0, v17, vcc
	v_add_co_u32_e32 v22, vcc, s81, v16
	s_nop 1
	v_addc_co_u32_e32 v23, vcc, 0, v17, vcc
	v_add_co_u32_e32 v24, vcc, s82, v16
	s_nop 1
	v_addc_co_u32_e32 v25, vcc, 0, v17, vcc
	global_load_dword v111, v[18:19], off offset:-4096 nt
	s_nop 0
	global_load_dword v18, v[18:19], off nt
	s_nop 0
	global_load_dword v19, v[20:21], off offset:-4096 nt
	s_nop 0
	global_load_dword v20, v[20:21], off nt
	s_nop 0
	global_load_dword v21, v[22:23], off offset:-4096 nt
	s_nop 0
	global_load_dword v22, v[22:23], off nt
	s_nop 0
	global_load_dword v23, v[24:25], off offset:-4096 nt
	s_nop 0
	global_load_dword v24, v[24:25], off nt
	v_add_co_u32_e32 v16, vcc, s84, v16
	s_nop 1
	v_addc_co_u32_e32 v17, vcc, 0, v17, vcc
	global_load_dword v16, v[16:17], off nt
	s_waitcnt vmcnt(62)
; #define LAS __attribute__((address_space(3)))
; __device__ __forceinline__ unsigned pk2(float lo, float hi) { return pg8::cvt_pk_bf16(lo, hi); }
; template <int MODE>
; __device__ __forceinline__ void p0_item(const float* W, int K, int N, bf16u* WT, const float* ks, LAS float* scr, int item, int lane) {
;     ...
;     for (int kk = 0; kk < 64; ++kk) scr[kk * 65 + lane] = v[kk];
;     asm volatile("s_waitcnt lgkmcnt(0)" ::: "memory");
;     const int c = lane & 7;
; #pragma unroll
;     for (int j = 0; j < 8; ++j) { const int n = (lane >> 3) + 8 * j; const LAS float* s = scr + (8 * c) * 65 + n;
;         v4u o; o.x = pk2(s[0 * 65], s[1 * 65]); o.y = pk2(s[2 * 65], s[3 * 65]); o.z = pk2(s[4 * 65], s[5 * 65]); o.w = pk2(s[6 * 65], s[7 * 65]);
;         *(v4u*)(WT + (size_t)(drow + n) * K + k0 + 8 * c) = o; }
;     asm volatile("s_waitcnt lgkmcnt(0)" ::: "memory");
	ds_write2_b32 v80, v2, v26 offset1:65
	s_waitcnt vmcnt(60)
	ds_write2_b32 v80, v27, v28 offset0:130 offset1:195
	s_waitcnt vmcnt(58)
	ds_write2_b32 v95, v29, v30 offset0:4 offset1:69
	s_waitcnt vmcnt(56)
	ds_write2_b32 v95, v31, v32 offset0:134 offset1:199
	s_waitcnt vmcnt(54)
	ds_write2_b32 v96, v33, v34 offset0:8 offset1:73
	s_waitcnt vmcnt(52)
	ds_write2_b32 v96, v35, v36 offset0:138 offset1:203
	s_waitcnt vmcnt(50)
	ds_write2_b32 v97, v37, v38 offset0:12 offset1:77
	s_waitcnt vmcnt(48)
	ds_write2_b32 v97, v39, v40 offset0:142 offset1:207
	s_waitcnt vmcnt(46)
	ds_write2_b32 v98, v41, v42 offset0:16 offset1:81
	s_waitcnt vmcnt(44)
	ds_write2_b32 v98, v43, v44 offset0:146 offset1:211
	s_waitcnt vmcnt(42)
	ds_write2_b32 v99, v45, v46 offset0:20 offset1:85
	s_waitcnt vmcnt(40)
	ds_write2_b32 v99, v47, v48 offset0:150 offset1:215
	s_waitcnt vmcnt(38)
	ds_write2_b32 v100, v49, v50 offset0:24 offset1:89
	s_waitcnt vmcnt(36)
	ds_write2_b32 v100, v51, v52 offset0:154 offset1:219
	s_waitcnt vmcnt(34)
	ds_write2_b32 v101, v53, v54 offset0:28 offset1:93
	s_waitcnt vmcnt(32)
	ds_write2_b32 v101, v55, v56 offset0:158 offset1:223
	s_waitcnt vmcnt(30)
	ds_write2_b32 v102, v57, v58 offset0:32 offset1:97
	s_waitcnt vmcnt(28)
	ds_write2_b32 v102, v59, v60 offset0:162 offset1:227
	s_waitcnt vmcnt(26)
	ds_write2_b32 v103, v61, v62 offset0:36 offset1:101
	s_waitcnt vmcnt(24)
	ds_write2_b32 v103, v63, v64 offset0:166 offset1:231
	s_waitcnt vmcnt(22)
	ds_write2_b32 v104, v65, v66 offset0:40 offset1:105
	s_waitcnt vmcnt(20)
	ds_write2_b32 v104, v67, v68 offset0:170 offset1:235
	s_waitcnt vmcnt(18)
	ds_write2_b32 v105, v69, v70 offset0:44 offset1:109
	s_waitcnt vmcnt(16)
	ds_write2_b32 v105, v71, v72 offset0:174 offset1:239
	s_waitcnt vmcnt(14)
	ds_write2_b32 v106, v73, v74 offset0:48 offset1:113
	s_waitcnt vmcnt(12)
	ds_write2_b32 v106, v75, v76 offset0:178 offset1:243
	s_waitcnt vmcnt(10)
	ds_write2_b32 v107, v77, v78 offset0:52 offset1:117
	s_waitcnt vmcnt(8)
	ds_write2_b32 v107, v79, v111 offset0:182 offset1:247
	s_waitcnt vmcnt(6)
	ds_write2_b32 v108, v18, v19 offset0:56 offset1:121
	s_waitcnt vmcnt(4)
	ds_write2_b32 v108, v20, v21 offset0:186 offset1:251
	s_waitcnt vmcnt(2)
	ds_write2_b32 v109, v22, v23 offset0:60 offset1:125
	s_waitcnt vmcnt(0)
	ds_write2_b32 v109, v24, v16 offset0:190 offset1:255
	s_waitcnt lgkmcnt(0)
	ds_read2_b32 v[20:21], v82 offset0:65 offset1:73
	ds_read2_b32 v[22:23], v82 offset1:8
	ds_read2_b32 v[24:25], v82 offset0:130 offset1:138
	ds_read2_b32 v[26:27], v82 offset0:195 offset1:203
	ds_read2_b32 v[28:29], v110 offset0:4 offset1:12
	ds_read2_b32 v[30:31], v110 offset0:69 offset1:77
	ds_read2_b32 v[32:33], v110 offset0:134 offset1:142
	ds_read2_b32 v[34:35], v110 offset0:199 offset1:207
	v_or_b32_e32 v2, s12, v81
	v_mul_u32_u24_e32 v2, 0xb00, v2
	v_lshl_add_u64 v[36:37], v[4:5], 0, s[10:11]
	v_lshlrev_b32_e32 v2, 1, v2
	s_waitcnt lgkmcnt(6)
	v_cvt_pk_bf16_f32 v16, v22, v20
	s_waitcnt lgkmcnt(4)
	v_cvt_pk_bf16_f32 v17, v24, v26
	s_waitcnt lgkmcnt(2)
	v_cvt_pk_bf16_f32 v18, v28, v30
	s_waitcnt lgkmcnt(0)
	v_cvt_pk_bf16_f32 v19, v32, v34
	v_lshl_add_u64 v[38:39], v[36:37], 0, v[2:3]
	global_store_dwordx4 v[38:39], v[16:19], off
	v_or_b32_e32 v2, s12, v83
	v_mul_u32_u24_e32 v2, 0xb00, v2
	v_cvt_pk_bf16_f32 v16, v23, v21
	v_cvt_pk_bf16_f32 v17, v25, v27
	v_cvt_pk_bf16_f32 v18, v29, v31
	v_cvt_pk_bf16_f32 v19, v33, v35
	ds_read2_b32 v[22:23], v82 offset0:16 offset1:24
	ds_read2_b32 v[24:25], v82 offset0:81 offset1:89
	ds_read2_b32 v[26:27], v82 offset0:146 offset1:154
	ds_read2_b32 v[28:29], v82 offset0:211 offset1:219
	ds_read2_b32 v[30:31], v110 offset0:20 offset1:28
	ds_read2_b32 v[32:33], v110 offset0:85 offset1:93
	ds_read2_b32 v[34:35], v110 offset0:150 offset1:158
	ds_read2_b32 v[38:39], v110 offset0:215 offset1:223
	v_lshlrev_b32_e32 v2, 1, v2
	v_lshl_add_u64 v[20:21], v[36:37], 0, v[2:3]
	v_or_b32_e32 v2, s12, v84
	v_mul_u32_u24_e32 v2, 0xb00, v2
	v_lshlrev_b32_e32 v2, 1, v2
	global_store_dwordx4 v[20:21], v[16:19], off
	v_lshl_add_u64 v[20:21], v[36:37], 0, v[2:3]
	v_or_b32_e32 v2, s12, v85
	s_waitcnt lgkmcnt(6)
	v_cvt_pk_bf16_f32 v16, v22, v24
	s_waitcnt lgkmcnt(4)
	v_cvt_pk_bf16_f32 v17, v26, v28
	s_waitcnt lgkmcnt(2)
	v_cvt_pk_bf16_f32 v18, v30, v32
	s_waitcnt lgkmcnt(0)
	v_cvt_pk_bf16_f32 v19, v34, v38
	global_store_dwordx4 v[20:21], v[16:19], off
	v_mul_u32_u24_e32 v2, 0xb00, v2
	v_lshlrev_b32_e32 v2, 1, v2
	v_cvt_pk_bf16_f32 v16, v23, v25
	v_cvt_pk_bf16_f32 v17, v27, v29
	v_cvt_pk_bf16_f32 v18, v31, v33
	v_cvt_pk_bf16_f32 v19, v35, v39
	ds_read2_b32 v[22:23], v82 offset0:32 offset1:40
	ds_read2_b32 v[24:25], v82 offset0:97 offset1:105
	ds_read2_b32 v[26:27], v82 offset0:162 offset1:170
	ds_read2_b32 v[28:29], v82 offset0:227 offset1:235
	ds_read2_b32 v[30:31], v110 offset0:36 offset1:44
	ds_read2_b32 v[32:33], v110 offset0:101 offset1:109
	ds_read2_b32 v[34:35], v110 offset0:166 offset1:174
	ds_read2_b32 v[38:39], v110 offset0:231 offset1:239
	v_lshl_add_u64 v[20:21], v[36:37], 0, v[2:3]
	v_or_b32_e32 v2, s12, v86
	v_mul_u32_u24_e32 v2, 0xb00, v2
	v_lshlrev_b32_e32 v2, 1, v2
	global_store_dwordx4 v[20:21], v[16:19], off
	v_lshl_add_u64 v[20:21], v[36:37], 0, v[2:3]
	v_or_b32_e32 v2, s12, v87
	s_waitcnt lgkmcnt(6)
	v_cvt_pk_bf16_f32 v16, v22, v24
	s_waitcnt lgkmcnt(4)
	v_cvt_pk_bf16_f32 v17, v26, v28
	s_waitcnt lgkmcnt(2)
	v_cvt_pk_bf16_f32 v18, v30, v32
	s_waitcnt lgkmcnt(0)
	v_cvt_pk_bf16_f32 v19, v34, v38
	v_mul_u32_u24_e32 v2, 0xb00, v2
	global_store_dwordx4 v[20:21], v[16:19], off
	v_lshlrev_b32_e32 v2, 1, v2
	v_lshl_add_u64 v[20:21], v[36:37], 0, v[2:3]
	v_cvt_pk_bf16_f32 v16, v23, v25
	v_cvt_pk_bf16_f32 v17, v27, v29
	v_cvt_pk_bf16_f32 v18, v31, v33
	v_cvt_pk_bf16_f32 v19, v35, v39
	ds_read2_b32 v[22:23], v82 offset0:48 offset1:56
	ds_read2_b32 v[24:25], v82 offset0:113 offset1:121
	ds_read2_b32 v[26:27], v82 offset0:178 offset1:186
	ds_read2_b32 v[28:29], v82 offset0:243 offset1:251
	ds_read2_b32 v[30:31], v110 offset0:52 offset1:60
	ds_read2_b32 v[32:33], v110 offset0:117 offset1:125
	ds_read2_b32 v[34:35], v110 offset0:182 offset1:190
	ds_read2_b32 v[38:39], v110 offset0:247 offset1:255
	v_or_b32_e32 v2, s12, v88
	v_mul_u32_u24_e32 v2, 0xb00, v2
	v_lshlrev_b32_e32 v2, 1, v2
	global_store_dwordx4 v[20:21], v[16:19], off
	v_lshl_add_u64 v[20:21], v[36:37], 0, v[2:3]
	v_or_b32_e32 v2, s12, v89
	v_mul_u32_u24_e32 v2, 0xb00, v2
	s_waitcnt lgkmcnt(6)
	v_cvt_pk_bf16_f32 v16, v22, v24
	s_waitcnt lgkmcnt(4)
	v_cvt_pk_bf16_f32 v17, v26, v28
	s_waitcnt lgkmcnt(2)
	v_cvt_pk_bf16_f32 v18, v30, v32
	s_waitcnt lgkmcnt(0)
	v_cvt_pk_bf16_f32 v19, v34, v38
	v_lshlrev_b32_e32 v2, 1, v2
	global_store_dwordx4 v[20:21], v[16:19], off
	v_lshl_add_u64 v[20:21], v[36:37], 0, v[2:3]
	s_mov_b64 s[12:13], 0
	v_cvt_pk_bf16_f32 v16, v23, v25
	v_cvt_pk_bf16_f32 v17, v27, v29
	v_cvt_pk_bf16_f32 v18, v31, v33
	v_cvt_pk_bf16_f32 v19, v35, v39
	global_store_dwordx4 v[20:21], v[16:19], off
	s_waitcnt lgkmcnt(0)
; template <int MODE>
; __device__ __forceinline__ void p0_item(const float* W, int K, int N, bf16u* WT, const float* ks, LAS float* scr, int item, int lane) {
;     const int nblk = N / 64, kb = item / nblk, nb = item - kb * nblk, k0 = 64 * kb, n0 = 64 * nb;
;     int nn = n0 + lane;
;     if (MODE == 1) {
;         if (nn < 2048) { const int p = nn & 63; if (p < 16) nn = (nn & ~15) | (p & 3) | ((p & 4) << 1) | ((p & 8) >> 1); }
;         else if (nn >= 4096) { const int sec = nn >= 6144 ? 6144 : 4096, r = nn - sec, q = r & 255; nn = sec + ((q >> 7) << 10) + 128 * (r >> 8) + (q & 127); }
;     }
;     int drow = n0;
;     if (MODE == 2) drow = 256 * (n0 >> 7) + (n0 & 127);
;     if (MODE == 3) drow = 256 * (n0 >> 7) + 128 + (n0 & 127);
;     const float* src = W + (size_t)k0 * N + nn;
;     float v[64];
; #pragma unroll
;     for (int kk = 0; kk < 64; ++kk) v[kk] = src[(size_t)kk * N];
.LBB0_17:
	s_andn2_b64 vcc, exec, s[12:13]
	s_cbranch_vccnz .LBB0_21
	s_and_b32 s10, s23, 0xffff
	s_mul_hi_u32 s12, s10, 0x5d1745e
	s_mul_i32 s10, s10, 0xba2f
	s_mul_i32 s13, s12, 0xb00
	s_lshr_b32 s15, s10, 21
	v_readlane_b32 s48, v253, 20
	v_subrev_u32_e32 v2, s13, v92
	s_lshl_b32 s10, s15, 6
	s_mul_i32 s15, s15, 0xb0000
	v_readlane_b32 s62, v253, 34
	v_add_u32_e32 v16, s80, v2
	v_readlane_b32 s63, v253, 35
	s_add_u32 s88, s62, s15
	s_addc_u32 s89, s63, 0
	v_ashrrev_i32_e32 v17, 31, v16
	v_lshl_add_u64 v[72:73], v[16:17], 2, s[88:89]
	v_add_co_u32_e32 v18, vcc, s30, v72
	s_mov_b32 s15, 0x31000
	s_nop 0
	v_addc_co_u32_e32 v19, vcc, 0, v73, vcc
	v_add_co_u32_e32 v20, vcc, s0, v72
	v_readlane_b32 s58, v253, 30
	s_nop 0
	v_addc_co_u32_e32 v21, vcc, 0, v73, vcc
	v_add_co_u32_e32 v22, vcc, s36, v72
	v_readlane_b32 s59, v253, 31
	s_nop 0
	v_addc_co_u32_e32 v23, vcc, 0, v73, vcc
	v_add_co_u32_e32 v24, vcc, s1, v72
	v_readlane_b32 s49, v253, 21
	s_nop 0
	v_addc_co_u32_e32 v25, vcc, 0, v73, vcc
	v_add_co_u32_e32 v26, vcc, s73, v72
	v_readlane_b32 s50, v253, 22
	s_nop 0
	v_addc_co_u32_e32 v27, vcc, 0, v73, vcc
	v_add_co_u32_e32 v28, vcc, s42, v72
	v_readlane_b32 s51, v253, 23
	s_nop 0
	v_addc_co_u32_e32 v29, vcc, 0, v73, vcc
	v_add_co_u32_e32 v30, vcc, s75, v72
	v_readlane_b32 s52, v253, 24
	s_nop 0
	v_addc_co_u32_e32 v31, vcc, 0, v73, vcc
	global_load_dword v16, v[72:73], off nt
	global_load_dword v17, v[18:19], off offset:3072 nt
	s_nop 0
	global_load_dword v18, v[20:21], off offset:2048 nt
	global_load_dword v19, v[22:23], off offset:1024 nt
	s_nop 0
	global_load_dword v20, v[24:25], off nt
	global_load_dword v21, v[26:27], off offset:3072 nt
	global_load_dword v22, v[28:29], off offset:2048 nt
	global_load_dword v23, v[30:31], off offset:1024 nt
	v_add_co_u32_e32 v24, vcc, s46, v72
	v_readlane_b32 s53, v253, 25
	s_nop 0
	v_addc_co_u32_e32 v25, vcc, 0, v73, vcc
	v_add_co_u32_e32 v26, vcc, s47, v72
	v_readlane_b32 s54, v253, 26
	s_nop 0
	v_addc_co_u32_e32 v27, vcc, 0, v73, vcc
	v_add_co_u32_e32 v28, vcc, s76, v72
	v_readlane_b32 s55, v253, 27
	s_nop 0
	v_addc_co_u32_e32 v29, vcc, 0, v73, vcc
	v_add_co_u32_e32 v30, vcc, s38, v72
	v_readlane_b32 s56, v253, 28
	s_nop 0
	v_addc_co_u32_e32 v31, vcc, 0, v73, vcc
	v_add_co_u32_e32 v32, vcc, s77, v72
	v_readlane_b32 s57, v253, 29
	s_nop 0
	v_addc_co_u32_e32 v33, vcc, 0, v73, vcc
	v_add_co_u32_e32 v34, vcc, s78, v72
	v_readlane_b32 s60, v253, 32
	s_nop 0
	v_addc_co_u32_e32 v35, vcc, 0, v73, vcc
	v_add_co_u32_e32 v36, vcc, s68, v72
	v_readlane_b32 s61, v253, 33
	s_nop 0
	v_addc_co_u32_e32 v37, vcc, 0, v73, vcc
	v_add_co_u32_e32 v38, vcc, s79, v72
	s_nop 1
	v_addc_co_u32_e32 v39, vcc, 0, v73, vcc
	global_load_dword v24, v[24:25], off nt
	s_nop 0
	global_load_dword v25, v[26:27], off offset:3072 nt
	s_nop 0
	global_load_dword v26, v[28:29], off offset:2048 nt
	global_load_dword v27, v[30:31], off offset:1024 nt
	s_nop 0
	global_load_dword v28, v[32:33], off nt
	global_load_dword v29, v[34:35], off offset:3072 nt
	global_load_dword v30, v[36:37], off offset:2048 nt
	global_load_dword v31, v[38:39], off offset:1024 nt
	v_add_co_u32_e32 v32, vcc, s87, v72
	s_nop 1
	v_addc_co_u32_e32 v33, vcc, 0, v73, vcc
	v_add_co_u32_e32 v34, vcc, s90, v72
	s_nop 1
	v_addc_co_u32_e32 v35, vcc, 0, v73, vcc
	v_add_co_u32_e32 v36, vcc, s15, v72
	s_mov_b32 s15, 0x37000
	s_nop 0
	v_addc_co_u32_e32 v37, vcc, 0, v73, vcc
	v_add_co_u32_e32 v38, vcc, s66, v72
	s_nop 1
	v_addc_co_u32_e32 v39, vcc, 0, v73, vcc
	v_add_co_u32_e32 v40, vcc, s15, v72
	s_mov_b32 s15, 0x39000
	s_nop 0
	v_addc_co_u32_e32 v41, vcc, 0, v73, vcc
	v_add_co_u32_e32 v42, vcc, s15, v72
	s_mov_b32 s15, 0x42000
	s_nop 0
	v_addc_co_u32_e32 v43, vcc, 0, v73, vcc
	v_add_co_u32_e32 v44, vcc, s81, v72
	s_nop 1
	v_addc_co_u32_e32 v45, vcc, 0, v73, vcc
	v_add_co_u32_e32 v46, vcc, s84, v72
	s_nop 1
	v_addc_co_u32_e32 v47, vcc, 0, v73, vcc
	global_load_dword v32, v[32:33], off nt
	s_nop 0
	global_load_dword v33, v[34:35], off offset:3072 nt
	s_nop 0
	global_load_dword v34, v[36:37], off offset:2048 nt
	global_load_dword v35, v[38:39], off offset:1024 nt
	s_nop 0
	global_load_dword v36, v[40:41], off nt
	global_load_dword v37, v[42:43], off offset:3072 nt
	global_load_dword v38, v[44:45], off offset:2048 nt
	global_load_dword v39, v[46:47], off offset:1024 nt
	v_add_co_u32_e32 v40, vcc, s15, v72
	s_mov_b32 s15, 0x44000
	s_nop 0
	v_addc_co_u32_e32 v41, vcc, 0, v73, vcc
	v_add_co_u32_e32 v42, vcc, s15, v72
	s_mov_b32 s15, 0x47000
	s_nop 0
	v_addc_co_u32_e32 v43, vcc, 0, v73, vcc
	v_add_co_u32_e32 v44, vcc, s15, v72
	s_mov_b32 s15, 0x4a000
	s_nop 0
	v_addc_co_u32_e32 v45, vcc, 0, v73, vcc
	v_add_co_u32_e32 v46, vcc, s15, v72
	s_mov_b32 s15, 0x4d000
	s_nop 0
	v_addc_co_u32_e32 v47, vcc, 0, v73, vcc
	v_add_co_u32_e32 v48, vcc, s15, v72
	s_mov_b32 s15, 0x4f000
	s_nop 0
	v_addc_co_u32_e32 v49, vcc, 0, v73, vcc
	v_add_co_u32_e32 v50, vcc, s15, v72
	s_mov_b32 s15, 0x52000
	s_nop 0
	v_addc_co_u32_e32 v51, vcc, 0, v73, vcc
	v_add_co_u32_e32 v52, vcc, s15, v72
	s_mov_b32 s15, 0x55000
	s_nop 0
	v_addc_co_u32_e32 v53, vcc, 0, v73, vcc
	v_add_co_u32_e32 v54, vcc, s15, v72
	s_mov_b32 s15, 0x5a000
	s_nop 0
	v_addc_co_u32_e32 v55, vcc, 0, v73, vcc
	global_load_dword v40, v[40:41], off nt
	s_nop 0
	global_load_dword v41, v[42:43], off offset:3072 nt
	s_nop 0
	global_load_dword v42, v[44:45], off offset:2048 nt
	global_load_dword v43, v[46:47], off offset:1024 nt
	s_nop 0
	global_load_dword v44, v[48:49], off nt
	global_load_dword v45, v[50:51], off offset:3072 nt
	global_load_dword v46, v[52:53], off offset:2048 nt
	global_load_dword v47, v[54:55], off offset:1024 nt
	v_add_co_u32_e32 v48, vcc, s83, v72
; template <int MODE>
; __device__ __forceinline__ void p0_item(const float* W, int K, int N, bf16u* WT, const float* ks, LAS float* scr, int item, int lane) {
;     ...
;     const float* src = W + (size_t)k0 * N + nn;
;     float v[64];
; #pragma unroll
;     for (int kk = 0; kk < 64; ++kk) v[kk] = src[(size_t)kk * N];
	s_nop 1
	v_addc_co_u32_e32 v49, vcc, 0, v73, vcc
	v_add_co_u32_e32 v50, vcc, s15, v72
	s_mov_b32 s15, 0x5d000
	s_nop 0
	v_addc_co_u32_e32 v51, vcc, 0, v73, vcc
	v_add_co_u32_e32 v52, vcc, s15, v72
	s_mov_b32 s15, 0x63000
	s_nop 0
	v_addc_co_u32_e32 v53, vcc, 0, v73, vcc
	v_add_co_u32_e32 v54, vcc, s86, v72
	s_nop 1
	v_addc_co_u32_e32 v55, vcc, 0, v73, vcc
	v_add_co_u32_e32 v56, vcc, s15, v72
	s_mov_b32 s15, 0x65000
	s_nop 0
	v_addc_co_u32_e32 v57, vcc, 0, v73, vcc
	v_add_co_u32_e32 v58, vcc, s15, v72
	s_mov_b32 s15, 0x6b000
	s_nop 0
	v_addc_co_u32_e32 v59, vcc, 0, v73, vcc
	v_add_co_u32_e32 v60, vcc, s91, v72
	s_nop 1
	v_addc_co_u32_e32 v61, vcc, 0, v73, vcc
	v_add_co_u32_e32 v62, vcc, s15, v72
	s_mov_b32 s15, 0x6e000
	s_nop 0
	v_addc_co_u32_e32 v63, vcc, 0, v73, vcc
	global_load_dword v48, v[48:49], off nt
	s_nop 0
	global_load_dword v49, v[50:51], off offset:3072 nt
	s_nop 0
	global_load_dword v50, v[52:53], off offset:2048 nt
	global_load_dword v51, v[54:55], off offset:1024 nt
	s_nop 0
	global_load_dword v52, v[56:57], off nt
	global_load_dword v53, v[58:59], off offset:3072 nt
	global_load_dword v54, v[60:61], off offset:2048 nt
	global_load_dword v55, v[62:63], off offset:1024 nt
	v_add_co_u32_e32 v56, vcc, s15, v72
	s_mov_b32 s15, 0x73000
	s_nop 0
	v_addc_co_u32_e32 v57, vcc, 0, v73, vcc
	v_add_co_u32_e32 v58, vcc, s94, v72
	s_nop 1
	v_addc_co_u32_e32 v59, vcc, 0, v73, vcc
	v_add_co_u32_e32 v60, vcc, s15, v72
	s_mov_b32 s15, 0x76000
	s_nop 0
	v_addc_co_u32_e32 v61, vcc, 0, v73, vcc
	v_add_co_u32_e32 v62, vcc, s15, v72
	s_mov_b32 s15, 0x79000
	s_nop 0
	v_addc_co_u32_e32 v63, vcc, 0, v73, vcc
	v_add_co_u32_e32 v64, vcc, s15, v72
	s_mov_b32 s15, 0x7b000
	s_nop 0
	v_addc_co_u32_e32 v65, vcc, 0, v73, vcc
	v_add_co_u32_e32 v66, vcc, s15, v72
	s_mov_b32 s15, 0x7e000
	s_nop 0
	v_addc_co_u32_e32 v67, vcc, 0, v73, vcc
	v_add_co_u32_e32 v68, vcc, s15, v72
	s_mov_b32 s15, 0x81000
	s_nop 0
	v_addc_co_u32_e32 v69, vcc, 0, v73, vcc
	v_add_co_u32_e32 v70, vcc, s15, v72
	s_mov_b32 s15, 0x84000
	s_nop 0
	v_addc_co_u32_e32 v71, vcc, 0, v73, vcc
	global_load_dword v56, v[56:57], off nt
	s_nop 0
	global_load_dword v57, v[58:59], off offset:3072 nt
	s_nop 0
	global_load_dword v58, v[60:61], off offset:2048 nt
	global_load_dword v59, v[62:63], off offset:1024 nt
	s_nop 0
	global_load_dword v60, v[64:65], off nt
	global_load_dword v61, v[66:67], off offset:3072 nt
	global_load_dword v62, v[68:69], off offset:2048 nt
	global_load_dword v63, v[70:71], off offset:1024 nt
	v_add_co_u32_e32 v64, vcc, s15, v72
	s_mov_b32 s15, 0x86000
	s_nop 0
	v_addc_co_u32_e32 v65, vcc, 0, v73, vcc
	v_add_co_u32_e32 v66, vcc, s15, v72
	s_mov_b32 s15, 0x89000
	s_nop 0
	v_addc_co_u32_e32 v67, vcc, 0, v73, vcc
	v_add_co_u32_e32 v68, vcc, s15, v72
	s_mov_b32 s15, 0x8c000
	s_nop 0
	v_addc_co_u32_e32 v69, vcc, 0, v73, vcc
	v_add_co_u32_e32 v70, vcc, s15, v72
	s_mov_b32 s15, 0x8f000
	s_nop 0
	v_addc_co_u32_e32 v71, vcc, 0, v73, vcc
	v_add_co_u32_e32 v74, vcc, s15, v72
	s_mov_b32 s15, 0x91000
	s_nop 0
	v_addc_co_u32_e32 v75, vcc, 0, v73, vcc
	v_add_co_u32_e32 v76, vcc, s15, v72
	s_mov_b32 s15, 0x94000
	s_nop 0
	v_addc_co_u32_e32 v77, vcc, 0, v73, vcc
	v_add_co_u32_e32 v78, vcc, s15, v72
	s_mov_b32 s15, 0x97000
	s_nop 0
	v_addc_co_u32_e32 v79, vcc, 0, v73, vcc
	v_add_co_u32_e32 v112, vcc, s15, v72
	s_mov_b32 s15, 0x9a000
	s_nop 0
	v_addc_co_u32_e32 v113, vcc, 0, v73, vcc
	global_load_dword v64, v[64:65], off nt
	s_nop 0
	global_load_dword v65, v[66:67], off offset:3072 nt
	s_nop 0
	global_load_dword v66, v[68:69], off offset:2048 nt
	global_load_dword v67, v[70:71], off offset:1024 nt
	s_nop 0
	global_load_dword v68, v[74:75], off nt
	global_load_dword v69, v[76:77], off offset:3072 nt
	global_load_dword v70, v[78:79], off offset:2048 nt
	global_load_dword v71, v[112:113], off offset:1024 nt
	v_add_co_u32_e32 v74, vcc, s15, v72
	s_mov_b32 s15, 0x9c000
	s_nop 0
	v_addc_co_u32_e32 v75, vcc, 0, v73, vcc
	v_add_co_u32_e32 v76, vcc, s15, v72
	s_mov_b32 s15, 0x9f000
	s_nop 0
	v_addc_co_u32_e32 v77, vcc, 0, v73, vcc
	v_add_co_u32_e32 v78, vcc, s15, v72
	s_mov_b32 s15, 0xa2000
	s_nop 0
	v_addc_co_u32_e32 v79, vcc, 0, v73, vcc
	v_add_co_u32_e32 v112, vcc, s15, v72
	s_nop 1
	v_addc_co_u32_e32 v113, vcc, 0, v73, vcc
	v_add_co_u32_e32 v114, vcc, s93, v72
	s_nop 1
	v_addc_co_u32_e32 v115, vcc, 0, v73, vcc
	v_add_co_u32_e32 v116, vcc, 0xa7000, v72
	s_nop 1
	v_addc_co_u32_e32 v117, vcc, 0, v73, vcc
	v_add_co_u32_e32 v118, vcc, 0xaa000, v72
	s_nop 1
	v_addc_co_u32_e32 v119, vcc, 0, v73, vcc
	v_add_co_u32_e32 v120, vcc, 0xad000, v72
	s_nop 1
	v_addc_co_u32_e32 v121, vcc, 0, v73, vcc
	global_load_dword v72, v[74:75], off nt
	global_load_dword v73, v[76:77], off offset:3072 nt
	s_nop 0
	global_load_dword v74, v[78:79], off offset:2048 nt
	global_load_dword v75, v[112:113], off offset:1024 nt
	global_load_dword v76, v[114:115], off nt
	global_load_dword v77, v[116:117], off offset:3072 nt
	s_nop 0
	global_load_dword v78, v[118:119], off offset:2048 nt
	global_load_dword v79, v[120:121], off offset:1024 nt
	s_andn2_b64 vcc, exec, s[6:7]
	s_cbranch_vccnz .LBB0_20
; template <int MODE>
; __device__ __forceinline__ void p0_item(const float* W, int K, int N, bf16u* WT, const float* ks, LAS float* scr, int item, int lane) {
;     ...
;     if (ks) {
; #pragma unroll
;         for (int kk = 0; kk < 64; ++kk) v[kk] *= ks[k0 + kk];
;     }
	s_lshl_b32 s15, s10, 2
	v_mov_b32_e32 v2, s15
	global_load_dwordx4 v[112:115], v2, s[58:59] offset:48 nt
	global_load_dwordx4 v[116:119], v2, s[58:59] offset:32 nt
	global_load_dwordx4 v[120:123], v2, s[58:59] offset:16 nt
	global_load_dwordx4 v[124:127], v2, s[58:59] nt
	s_waitcnt vmcnt(3)
	v_pk_mul_f32 v[28:29], v[28:29], v[112:113]
	s_waitcnt vmcnt(2)
	v_pk_mul_f32 v[24:25], v[24:25], v[116:117]
	s_waitcnt vmcnt(1)
	v_pk_mul_f32 v[20:21], v[20:21], v[120:121]
	s_waitcnt vmcnt(0)
	v_pk_mul_f32 v[16:17], v[16:17], v[124:125]
	v_pk_mul_f32 v[18:19], v[18:19], v[126:127]
	v_pk_mul_f32 v[22:23], v[22:23], v[122:123]
	v_pk_mul_f32 v[26:27], v[26:27], v[118:119]
	v_pk_mul_f32 v[30:31], v[30:31], v[114:115]
	global_load_dwordx4 v[112:115], v2, s[58:59] offset:112 nt
	global_load_dwordx4 v[116:119], v2, s[58:59] offset:96 nt
	global_load_dwordx4 v[120:123], v2, s[58:59] offset:80 nt
	global_load_dwordx4 v[124:127], v2, s[58:59] offset:64 nt
	s_waitcnt vmcnt(3)
	v_pk_mul_f32 v[44:45], v[44:45], v[112:113]
	s_waitcnt vmcnt(2)
	v_pk_mul_f32 v[40:41], v[40:41], v[116:117]
	s_waitcnt vmcnt(1)
	v_pk_mul_f32 v[36:37], v[36:37], v[120:121]
	s_waitcnt vmcnt(0)
	v_pk_mul_f32 v[32:33], v[32:33], v[124:125]
	v_pk_mul_f32 v[34:35], v[34:35], v[126:127]
	v_pk_mul_f32 v[38:39], v[38:39], v[122:123]
	v_pk_mul_f32 v[42:43], v[42:43], v[118:119]
	v_pk_mul_f32 v[46:47], v[46:47], v[114:115]
	global_load_dwordx4 v[112:115], v2, s[58:59] offset:176 nt
	global_load_dwordx4 v[116:119], v2, s[58:59] offset:160 nt
	global_load_dwordx4 v[120:123], v2, s[58:59] offset:144 nt
	global_load_dwordx4 v[124:127], v2, s[58:59] offset:128 nt
	s_waitcnt vmcnt(3)
	v_pk_mul_f32 v[60:61], v[60:61], v[112:113]
	s_waitcnt vmcnt(2)
	v_pk_mul_f32 v[56:57], v[56:57], v[116:117]
	s_waitcnt vmcnt(1)
	v_pk_mul_f32 v[52:53], v[52:53], v[120:121]
	s_waitcnt vmcnt(0)
	v_pk_mul_f32 v[48:49], v[48:49], v[124:125]
	v_pk_mul_f32 v[50:51], v[50:51], v[126:127]
	v_pk_mul_f32 v[54:55], v[54:55], v[122:123]
	v_pk_mul_f32 v[58:59], v[58:59], v[118:119]
	v_pk_mul_f32 v[62:63], v[62:63], v[114:115]
	global_load_dwordx4 v[112:115], v2, s[58:59] offset:240 nt
	global_load_dwordx4 v[116:119], v2, s[58:59] offset:224 nt
	global_load_dwordx4 v[120:123], v2, s[58:59] offset:208 nt
	global_load_dwordx4 v[124:127], v2, s[58:59] offset:192 nt
	s_waitcnt vmcnt(3)
	v_pk_mul_f32 v[76:77], v[76:77], v[112:113]
	s_waitcnt vmcnt(2)
	v_pk_mul_f32 v[72:73], v[72:73], v[116:117]
	s_waitcnt vmcnt(1)
	v_pk_mul_f32 v[68:69], v[68:69], v[120:121]
	s_waitcnt vmcnt(0)
	v_pk_mul_f32 v[64:65], v[64:65], v[124:125]
	v_pk_mul_f32 v[66:67], v[66:67], v[126:127]
	v_pk_mul_f32 v[70:71], v[70:71], v[122:123]
	v_pk_mul_f32 v[74:75], v[74:75], v[118:119]
	v_pk_mul_f32 v[78:79], v[78:79], v[114:115]

; template <int MODE>
; __device__ __forceinline__ void p0_item(const float* W, int K, int N, bf16u* WT, const float* ks, LAS float* scr, int item, int lane) {
;     const int nblk = N / 64, kb = item / nblk, nb = item - kb * nblk, k0 = 64 * kb, n0 = 64 * nb;
;     int nn = n0 + lane;
;     if (MODE == 1) {
;         if (nn < 2048) { const int p = nn & 63; if (p < 16) nn = (nn & ~15) | (p & 3) | ((p & 4) << 1) | ((p & 8) >> 1); }
;         else if (nn >= 4096) { const int sec = nn >= 6144 ? 6144 : 4096, r = nn - sec, q = r & 255; nn = sec + ((q >> 7) << 10) + 128 * (r >> 8) + (q & 127); }
;     }
;     int drow = n0;
;     if (MODE == 2) drow = 256 * (n0 >> 7) + (n0 & 127);
;     if (MODE == 3) drow = 256 * (n0 >> 7) + 128 + (n0 & 127);
;     const float* src = W + (size_t)k0 * N + nn;
;     float v[64];
; #pragma unroll
;     for (int kk = 0; kk < 64; ++kk) v[kk] = src[(size_t)kk * N];
.LBB0_22:
	s_andn2_b64 vcc, exec, s[12:13]
	s_cbranch_vccnz .LBB0_26
	s_and_b32 s10, 0xffff, s26
	s_mul_hi_u32 s12, s10, 0x5d1745e
	s_mul_i32 s10, s12, 0xb00
	s_sub_i32 s13, s27, s10
	s_mul_i32 s10, s23, 0xba2f
	s_add_i32 s10, s10, 0x2000140
	s_lshr_b32 s15, s10, 21
	v_readlane_b32 s48, v253, 20
	s_lshl_b32 s10, s15, 6
	s_add_i32 s13, s13, s80
	s_mul_i32 s15, s15, 0xb0000
	v_readlane_b32 s60, v253, 32
	v_add_u32_e32 v16, s13, v1
	v_readlane_b32 s61, v253, 33
	s_add_u32 s88, s60, s15
	s_addc_u32 s89, s61, 0
	v_ashrrev_i32_e32 v17, 31, v16
	v_lshl_add_u64 v[72:73], v[16:17], 2, s[88:89]
	v_add_co_u32_e32 v18, vcc, s30, v72
	s_mov_b32 s15, 0x31000
	s_nop 0
	v_addc_co_u32_e32 v19, vcc, 0, v73, vcc
	v_add_co_u32_e32 v20, vcc, s0, v72
	v_readlane_b32 s58, v253, 30
	s_nop 0
	v_addc_co_u32_e32 v21, vcc, 0, v73, vcc
	v_add_co_u32_e32 v22, vcc, s36, v72
	v_readlane_b32 s59, v253, 31
	s_nop 0
	v_addc_co_u32_e32 v23, vcc, 0, v73, vcc
	v_add_co_u32_e32 v24, vcc, s1, v72
	v_readlane_b32 s49, v253, 21
	s_nop 0
	v_addc_co_u32_e32 v25, vcc, 0, v73, vcc
	v_add_co_u32_e32 v26, vcc, s73, v72
	v_readlane_b32 s50, v253, 22
	s_nop 0
	v_addc_co_u32_e32 v27, vcc, 0, v73, vcc
	v_add_co_u32_e32 v28, vcc, s42, v72
	v_readlane_b32 s51, v253, 23
	s_nop 0
	v_addc_co_u32_e32 v29, vcc, 0, v73, vcc
	v_add_co_u32_e32 v30, vcc, s75, v72
	v_readlane_b32 s52, v253, 24
	s_nop 0
	v_addc_co_u32_e32 v31, vcc, 0, v73, vcc
	global_load_dword v16, v[72:73], off nt
	global_load_dword v17, v[18:19], off offset:3072 nt
	s_nop 0
	global_load_dword v18, v[20:21], off offset:2048 nt
	global_load_dword v19, v[22:23], off offset:1024 nt
	s_nop 0
	global_load_dword v20, v[24:25], off nt
	global_load_dword v21, v[26:27], off offset:3072 nt
	global_load_dword v22, v[28:29], off offset:2048 nt
	global_load_dword v23, v[30:31], off offset:1024 nt
	v_add_co_u32_e32 v24, vcc, s46, v72
	v_readlane_b32 s53, v253, 25
	s_nop 0
	v_addc_co_u32_e32 v25, vcc, 0, v73, vcc
	v_add_co_u32_e32 v26, vcc, s47, v72
	v_readlane_b32 s54, v253, 26
	s_nop 0
	v_addc_co_u32_e32 v27, vcc, 0, v73, vcc
	v_add_co_u32_e32 v28, vcc, s76, v72
	v_readlane_b32 s55, v253, 27
	s_nop 0
	v_addc_co_u32_e32 v29, vcc, 0, v73, vcc
	v_add_co_u32_e32 v30, vcc, s38, v72
	v_readlane_b32 s56, v253, 28
	s_nop 0
	v_addc_co_u32_e32 v31, vcc, 0, v73, vcc
	v_add_co_u32_e32 v32, vcc, s77, v72
	v_readlane_b32 s57, v253, 29
	s_nop 0
	v_addc_co_u32_e32 v33, vcc, 0, v73, vcc
	v_add_co_u32_e32 v34, vcc, s78, v72
	v_readlane_b32 s62, v253, 34
	s_nop 0
	v_addc_co_u32_e32 v35, vcc, 0, v73, vcc
	v_add_co_u32_e32 v36, vcc, s68, v72
	v_readlane_b32 s63, v253, 35
	s_nop 0
	v_addc_co_u32_e32 v37, vcc, 0, v73, vcc
	v_add_co_u32_e32 v38, vcc, s79, v72
	s_nop 1
	v_addc_co_u32_e32 v39, vcc, 0, v73, vcc
	global_load_dword v24, v[24:25], off nt
	s_nop 0
	global_load_dword v25, v[26:27], off offset:3072 nt
	s_nop 0
	global_load_dword v26, v[28:29], off offset:2048 nt
	global_load_dword v27, v[30:31], off offset:1024 nt
	s_nop 0
	global_load_dword v28, v[32:33], off nt
	global_load_dword v29, v[34:35], off offset:3072 nt
	global_load_dword v30, v[36:37], off offset:2048 nt
	global_load_dword v31, v[38:39], off offset:1024 nt
	v_add_co_u32_e32 v32, vcc, s87, v72
	s_nop 1
	v_addc_co_u32_e32 v33, vcc, 0, v73, vcc
	v_add_co_u32_e32 v34, vcc, s90, v72
	s_nop 1
	v_addc_co_u32_e32 v35, vcc, 0, v73, vcc
	v_add_co_u32_e32 v36, vcc, s15, v72
	s_mov_b32 s15, 0x37000
	s_nop 0
	v_addc_co_u32_e32 v37, vcc, 0, v73, vcc
	v_add_co_u32_e32 v38, vcc, s66, v72
	s_nop 1
	v_addc_co_u32_e32 v39, vcc, 0, v73, vcc
	v_add_co_u32_e32 v40, vcc, s15, v72
	s_mov_b32 s15, 0x39000
	s_nop 0
	v_addc_co_u32_e32 v41, vcc, 0, v73, vcc
	v_add_co_u32_e32 v42, vcc, s15, v72
	s_mov_b32 s15, 0x42000
	s_nop 0
	v_addc_co_u32_e32 v43, vcc, 0, v73, vcc
	v_add_co_u32_e32 v44, vcc, s81, v72
	s_nop 1
	v_addc_co_u32_e32 v45, vcc, 0, v73, vcc
	v_add_co_u32_e32 v46, vcc, s84, v72
	s_nop 1
	v_addc_co_u32_e32 v47, vcc, 0, v73, vcc
	global_load_dword v32, v[32:33], off nt
	s_nop 0
	global_load_dword v33, v[34:35], off offset:3072 nt
	s_nop 0
	global_load_dword v34, v[36:37], off offset:2048 nt
	global_load_dword v35, v[38:39], off offset:1024 nt
	s_nop 0
	global_load_dword v36, v[40:41], off nt
	global_load_dword v37, v[42:43], off offset:3072 nt
	global_load_dword v38, v[44:45], off offset:2048 nt
	global_load_dword v39, v[46:47], off offset:1024 nt
	v_add_co_u32_e32 v40, vcc, s15, v72
	s_mov_b32 s15, 0x44000
	s_nop 0
	v_addc_co_u32_e32 v41, vcc, 0, v73, vcc
	v_add_co_u32_e32 v42, vcc, s15, v72
	s_mov_b32 s15, 0x47000
	s_nop 0
	v_addc_co_u32_e32 v43, vcc, 0, v73, vcc
	v_add_co_u32_e32 v44, vcc, s15, v72
	s_mov_b32 s15, 0x4a000
	s_nop 0
	v_addc_co_u32_e32 v45, vcc, 0, v73, vcc
	v_add_co_u32_e32 v46, vcc, s15, v72
	s_mov_b32 s15, 0x4d000
	s_nop 0
	v_addc_co_u32_e32 v47, vcc, 0, v73, vcc
	v_add_co_u32_e32 v48, vcc, s15, v72
	s_mov_b32 s15, 0x4f000
	s_nop 0
	v_addc_co_u32_e32 v49, vcc, 0, v73, vcc
	v_add_co_u32_e32 v50, vcc, s15, v72
	s_mov_b32 s15, 0x52000
	s_nop 0
	v_addc_co_u32_e32 v51, vcc, 0, v73, vcc
	v_add_co_u32_e32 v52, vcc, s15, v72
	s_mov_b32 s15, 0x55000
	s_nop 0
	v_addc_co_u32_e32 v53, vcc, 0, v73, vcc
	v_add_co_u32_e32 v54, vcc, s15, v72
	s_mov_b32 s15, 0x5a000
	s_nop 0
	v_addc_co_u32_e32 v55, vcc, 0, v73, vcc
	global_load_dword v40, v[40:41], off nt
	s_nop 0
	global_load_dword v41, v[42:43], off offset:3072 nt
	s_nop 0
	global_load_dword v42, v[44:45], off offset:2048 nt
	global_load_dword v43, v[46:47], off offset:1024 nt
	s_nop 0
	global_load_dword v44, v[48:49], off nt
	global_load_dword v45, v[50:51], off offset:3072 nt
	global_load_dword v46, v[52:53], off offset:2048 nt
	global_load_dword v47, v[54:55], off offset:1024 nt
; template <int MODE>
; __device__ __forceinline__ void p0_item(const float* W, int K, int N, bf16u* WT, const float* ks, LAS float* scr, int item, int lane) {
;     ...
;     const float* src = W + (size_t)k0 * N + nn;
;     float v[64];
; #pragma unroll
;     for (int kk = 0; kk < 64; ++kk) v[kk] = src[(size_t)kk * N];
	v_add_co_u32_e32 v48, vcc, s83, v72
	s_nop 1
	v_addc_co_u32_e32 v49, vcc, 0, v73, vcc
	v_add_co_u32_e32 v50, vcc, s15, v72
	s_mov_b32 s15, 0x5d000
	s_nop 0
	v_addc_co_u32_e32 v51, vcc, 0, v73, vcc
	v_add_co_u32_e32 v52, vcc, s15, v72
	s_mov_b32 s15, 0x63000
	s_nop 0
	v_addc_co_u32_e32 v53, vcc, 0, v73, vcc
	v_add_co_u32_e32 v54, vcc, s86, v72
	s_nop 1
	v_addc_co_u32_e32 v55, vcc, 0, v73, vcc
	v_add_co_u32_e32 v56, vcc, s15, v72
	s_mov_b32 s15, 0x65000
	s_nop 0
	v_addc_co_u32_e32 v57, vcc, 0, v73, vcc
	v_add_co_u32_e32 v58, vcc, s15, v72
	s_mov_b32 s15, 0x6b000
	s_nop 0
	v_addc_co_u32_e32 v59, vcc, 0, v73, vcc
	v_add_co_u32_e32 v60, vcc, s91, v72
	s_nop 1
	v_addc_co_u32_e32 v61, vcc, 0, v73, vcc
	v_add_co_u32_e32 v62, vcc, s15, v72
	s_mov_b32 s15, 0x6e000
	s_nop 0
	v_addc_co_u32_e32 v63, vcc, 0, v73, vcc
	global_load_dword v48, v[48:49], off nt
	s_nop 0
	global_load_dword v49, v[50:51], off offset:3072 nt
	s_nop 0
	global_load_dword v50, v[52:53], off offset:2048 nt
	global_load_dword v51, v[54:55], off offset:1024 nt
	s_nop 0
	global_load_dword v52, v[56:57], off nt
	global_load_dword v53, v[58:59], off offset:3072 nt
	global_load_dword v54, v[60:61], off offset:2048 nt
	global_load_dword v55, v[62:63], off offset:1024 nt
	v_add_co_u32_e32 v56, vcc, s15, v72
	s_mov_b32 s15, 0x73000
	s_nop 0
	v_addc_co_u32_e32 v57, vcc, 0, v73, vcc
	v_add_co_u32_e32 v58, vcc, s94, v72
	s_nop 1
	v_addc_co_u32_e32 v59, vcc, 0, v73, vcc
	v_add_co_u32_e32 v60, vcc, s15, v72
	s_mov_b32 s15, 0x76000
	s_nop 0
	v_addc_co_u32_e32 v61, vcc, 0, v73, vcc
	v_add_co_u32_e32 v62, vcc, s15, v72
	s_mov_b32 s15, 0x79000
	s_nop 0
	v_addc_co_u32_e32 v63, vcc, 0, v73, vcc
	v_add_co_u32_e32 v64, vcc, s15, v72
	s_mov_b32 s15, 0x7b000
	s_nop 0
	v_addc_co_u32_e32 v65, vcc, 0, v73, vcc
	v_add_co_u32_e32 v66, vcc, s15, v72
	s_mov_b32 s15, 0x7e000
	s_nop 0
	v_addc_co_u32_e32 v67, vcc, 0, v73, vcc
	v_add_co_u32_e32 v68, vcc, s15, v72
	s_mov_b32 s15, 0x81000
	s_nop 0
	v_addc_co_u32_e32 v69, vcc, 0, v73, vcc
	v_add_co_u32_e32 v70, vcc, s15, v72
	s_mov_b32 s15, 0x84000
	s_nop 0
	v_addc_co_u32_e32 v71, vcc, 0, v73, vcc
	global_load_dword v56, v[56:57], off nt
	s_nop 0
	global_load_dword v57, v[58:59], off offset:3072 nt
	s_nop 0
	global_load_dword v58, v[60:61], off offset:2048 nt
	global_load_dword v59, v[62:63], off offset:1024 nt
	s_nop 0
	global_load_dword v60, v[64:65], off nt
	global_load_dword v61, v[66:67], off offset:3072 nt
	global_load_dword v62, v[68:69], off offset:2048 nt
	global_load_dword v63, v[70:71], off offset:1024 nt
	v_add_co_u32_e32 v64, vcc, s15, v72
	s_mov_b32 s15, 0x86000
	s_nop 0
	v_addc_co_u32_e32 v65, vcc, 0, v73, vcc
	v_add_co_u32_e32 v66, vcc, s15, v72
	s_mov_b32 s15, 0x89000
	s_nop 0
	v_addc_co_u32_e32 v67, vcc, 0, v73, vcc
	v_add_co_u32_e32 v68, vcc, s15, v72
	s_mov_b32 s15, 0x8c000
	s_nop 0
	v_addc_co_u32_e32 v69, vcc, 0, v73, vcc
	v_add_co_u32_e32 v70, vcc, s15, v72
	s_mov_b32 s15, 0x8f000
	s_nop 0
	v_addc_co_u32_e32 v71, vcc, 0, v73, vcc
	v_add_co_u32_e32 v74, vcc, s15, v72
	s_mov_b32 s15, 0x91000
	s_nop 0
	v_addc_co_u32_e32 v75, vcc, 0, v73, vcc
	v_add_co_u32_e32 v76, vcc, s15, v72
	s_mov_b32 s15, 0x94000
	s_nop 0
	v_addc_co_u32_e32 v77, vcc, 0, v73, vcc
	v_add_co_u32_e32 v78, vcc, s15, v72
	s_mov_b32 s15, 0x97000
	s_nop 0
	v_addc_co_u32_e32 v79, vcc, 0, v73, vcc
	v_add_co_u32_e32 v112, vcc, s15, v72
	s_mov_b32 s15, 0x9a000
	s_nop 0
	v_addc_co_u32_e32 v113, vcc, 0, v73, vcc
	global_load_dword v64, v[64:65], off nt
	s_nop 0
	global_load_dword v65, v[66:67], off offset:3072 nt
	s_nop 0
	global_load_dword v66, v[68:69], off offset:2048 nt
	global_load_dword v67, v[70:71], off offset:1024 nt
	s_nop 0
	global_load_dword v68, v[74:75], off nt
	global_load_dword v69, v[76:77], off offset:3072 nt
	global_load_dword v70, v[78:79], off offset:2048 nt
	global_load_dword v71, v[112:113], off offset:1024 nt
	v_add_co_u32_e32 v74, vcc, s15, v72
	s_mov_b32 s15, 0x9c000
	s_nop 0
	v_addc_co_u32_e32 v75, vcc, 0, v73, vcc
	v_add_co_u32_e32 v76, vcc, s15, v72
	s_mov_b32 s15, 0x9f000
	s_nop 0
	v_addc_co_u32_e32 v77, vcc, 0, v73, vcc
	v_add_co_u32_e32 v78, vcc, s15, v72
	s_mov_b32 s15, 0xa2000
	s_nop 0
	v_addc_co_u32_e32 v79, vcc, 0, v73, vcc
	v_add_co_u32_e32 v112, vcc, s15, v72
	s_nop 1
	v_addc_co_u32_e32 v113, vcc, 0, v73, vcc
	v_add_co_u32_e32 v114, vcc, s93, v72
	s_nop 1
	v_addc_co_u32_e32 v115, vcc, 0, v73, vcc
	v_add_co_u32_e32 v116, vcc, 0xa7000, v72
	s_nop 1
	v_addc_co_u32_e32 v117, vcc, 0, v73, vcc
	v_add_co_u32_e32 v118, vcc, 0xaa000, v72
	s_nop 1
	v_addc_co_u32_e32 v119, vcc, 0, v73, vcc
	v_add_co_u32_e32 v120, vcc, 0xad000, v72
	s_nop 1
	v_addc_co_u32_e32 v121, vcc, 0, v73, vcc
	global_load_dword v72, v[74:75], off nt
	global_load_dword v73, v[76:77], off offset:3072 nt
	s_nop 0
	global_load_dword v74, v[78:79], off offset:2048 nt
	global_load_dword v75, v[112:113], off offset:1024 nt
	global_load_dword v76, v[114:115], off nt
	global_load_dword v77, v[116:117], off offset:3072 nt
	s_nop 0
	global_load_dword v78, v[118:119], off offset:2048 nt
	global_load_dword v79, v[120:121], off offset:1024 nt
	s_andn2_b64 vcc, exec, s[6:7]
	s_cbranch_vccnz .LBB0_25
; template <int MODE>
; __device__ __forceinline__ void p0_item(const float* W, int K, int N, bf16u* WT, const float* ks, LAS float* scr, int item, int lane) {
;     ...
;     if (ks) {
; #pragma unroll
;         for (int kk = 0; kk < 64; ++kk) v[kk] *= ks[k0 + kk];
;     }
	s_lshl_b32 s15, s10, 2
	v_mov_b32_e32 v2, s15
	global_load_dwordx4 v[112:115], v2, s[58:59] offset:48 nt
	global_load_dwordx4 v[116:119], v2, s[58:59] offset:32 nt
	global_load_dwordx4 v[120:123], v2, s[58:59] offset:16 nt
	global_load_dwordx4 v[124:127], v2, s[58:59] nt
	s_waitcnt vmcnt(3)
	v_pk_mul_f32 v[28:29], v[28:29], v[112:113]
	s_waitcnt vmcnt(2)
	v_pk_mul_f32 v[24:25], v[24:25], v[116:117]
	s_waitcnt vmcnt(1)
	v_pk_mul_f32 v[20:21], v[20:21], v[120:121]
	s_waitcnt vmcnt(0)
	v_pk_mul_f32 v[16:17], v[16:17], v[124:125]
	v_pk_mul_f32 v[18:19], v[18:19], v[126:127]
	v_pk_mul_f32 v[22:23], v[22:23], v[122:123]
	v_pk_mul_f32 v[26:27], v[26:27], v[118:119]
	v_pk_mul_f32 v[30:31], v[30:31], v[114:115]
	global_load_dwordx4 v[112:115], v2, s[58:59] offset:112 nt
	global_load_dwordx4 v[116:119], v2, s[58:59] offset:96 nt
	global_load_dwordx4 v[120:123], v2, s[58:59] offset:80 nt
	global_load_dwordx4 v[124:127], v2, s[58:59] offset:64 nt
	s_waitcnt vmcnt(3)
	v_pk_mul_f32 v[44:45], v[44:45], v[112:113]
	s_waitcnt vmcnt(2)
	v_pk_mul_f32 v[40:41], v[40:41], v[116:117]
	s_waitcnt vmcnt(1)
	v_pk_mul_f32 v[36:37], v[36:37], v[120:121]
	s_waitcnt vmcnt(0)
	v_pk_mul_f32 v[32:33], v[32:33], v[124:125]
	v_pk_mul_f32 v[34:35], v[34:35], v[126:127]
	v_pk_mul_f32 v[38:39], v[38:39], v[122:123]
	v_pk_mul_f32 v[42:43], v[42:43], v[118:119]
	v_pk_mul_f32 v[46:47], v[46:47], v[114:115]
	global_load_dwordx4 v[112:115], v2, s[58:59] offset:176 nt
	global_load_dwordx4 v[116:119], v2, s[58:59] offset:160 nt
	global_load_dwordx4 v[120:123], v2, s[58:59] offset:144 nt
	global_load_dwordx4 v[124:127], v2, s[58:59] offset:128 nt
	s_waitcnt vmcnt(3)
	v_pk_mul_f32 v[60:61], v[60:61], v[112:113]
	s_waitcnt vmcnt(2)
	v_pk_mul_f32 v[56:57], v[56:57], v[116:117]
	s_waitcnt vmcnt(1)
	v_pk_mul_f32 v[52:53], v[52:53], v[120:121]
	s_waitcnt vmcnt(0)
	v_pk_mul_f32 v[48:49], v[48:49], v[124:125]
	v_pk_mul_f32 v[50:51], v[50:51], v[126:127]
	v_pk_mul_f32 v[54:55], v[54:55], v[122:123]
	v_pk_mul_f32 v[58:59], v[58:59], v[118:119]
	v_pk_mul_f32 v[62:63], v[62:63], v[114:115]
	global_load_dwordx4 v[112:115], v2, s[58:59] offset:240 nt
	global_load_dwordx4 v[116:119], v2, s[58:59] offset:224 nt
	global_load_dwordx4 v[120:123], v2, s[58:59] offset:208 nt
	global_load_dwordx4 v[124:127], v2, s[58:59] offset:192 nt
	s_waitcnt vmcnt(3)
	v_pk_mul_f32 v[76:77], v[76:77], v[112:113]
	s_waitcnt vmcnt(2)
	v_pk_mul_f32 v[72:73], v[72:73], v[116:117]
	s_waitcnt vmcnt(1)
	v_pk_mul_f32 v[68:69], v[68:69], v[120:121]
	s_waitcnt vmcnt(0)
	v_pk_mul_f32 v[64:65], v[64:65], v[124:125]
	v_pk_mul_f32 v[66:67], v[66:67], v[126:127]
	v_pk_mul_f32 v[70:71], v[70:71], v[122:123]
	v_pk_mul_f32 v[74:75], v[74:75], v[118:119]
	v_pk_mul_f32 v[78:79], v[78:79], v[114:115]

; template <int MODE>
; __device__ __forceinline__ void p0_item(const float* W, int K, int N, bf16u* WT, const float* ks, LAS float* scr, int item, int lane) {
;     const int nblk = N / 64, kb = item / nblk, nb = item - kb * nblk, k0 = 64 * kb, n0 = 64 * nb;
;     int nn = n0 + lane;
;     if (MODE == 1) {
;         if (nn < 2048) { const int p = nn & 63; if (p < 16) nn = (nn & ~15) | (p & 3) | ((p & 4) << 1) | ((p & 8) >> 1); }
;         else if (nn >= 4096) { const int sec = nn >= 6144 ? 6144 : 4096, r = nn - sec, q = r & 255; nn = sec + ((q >> 7) << 10) + 128 * (r >> 8) + (q & 127); }
;     }
;     int drow = n0;
;     if (MODE == 2) drow = 256 * (n0 >> 7) + (n0 & 127);
;     if (MODE == 3) drow = 256 * (n0 >> 7) + 128 + (n0 & 127);
;     const float* src = W + (size_t)k0 * N + nn;
;     float v[64];
; #pragma unroll
;     for (int kk = 0; kk < 64; ++kk) v[kk] = src[(size_t)kk * N];
.LBB0_27:
	s_andn2_b64 vcc, exec, s[12:13]
	s_cbranch_vccnz .LBB0_29
	s_add_i32 s10, s18, 0xffffd800
	s_add_i32 s12, s17, s80
	s_and_b32 s10, s10, 0xfc0
	s_add_i32 s12, s12, 0xfffd8000
	v_readlane_b32 s48, v253, 20
	s_and_b32 s12, s12, 0x3c0
	s_lshl_b32 s13, s10, 12
	v_readlane_b32 s56, v253, 28
	v_or_b32_e32 v2, s12, v1
	v_readlane_b32 s57, v253, 29
	s_add_u32 s88, s56, s13
	s_addc_u32 s89, s57, 0
	v_lshlrev_b32_e32 v2, 2, v2
	v_lshl_add_u64 v[16:17], s[88:89], 0, v[2:3]
	v_add_co_u32_e32 v18, vcc, s30, v16
	s_lshl_b32 s10, s10, 1
	s_nop 0
	v_addc_co_u32_e32 v19, vcc, 0, v17, vcc
	v_add_co_u32_e32 v20, vcc, s31, v16
	v_readlane_b32 s49, v253, 21
	s_nop 0
	v_addc_co_u32_e32 v21, vcc, 0, v17, vcc
	v_add_co_u32_e32 v22, vcc, s35, v16
	v_readlane_b32 s50, v253, 22
	s_nop 0
	v_addc_co_u32_e32 v23, vcc, 0, v17, vcc
	global_load_dword v2, v2, s[88:89] nt
	s_nop 0
	global_load_dword v26, v[18:19], off offset:-4096 nt
	global_load_dword v27, v[18:19], off nt
	global_load_dword v28, v[20:21], off offset:-4096 nt
	global_load_dword v29, v[20:21], off nt
	global_load_dword v30, v[22:23], off offset:-4096 nt
	global_load_dword v31, v[22:23], off nt
	v_add_co_u32_e32 v18, vcc, s36, v16
	v_readlane_b32 s51, v253, 23
	s_nop 0
	v_addc_co_u32_e32 v19, vcc, 0, v17, vcc
	v_add_co_u32_e32 v20, vcc, s37, v16
	v_readlane_b32 s52, v253, 24
	s_nop 0
	v_addc_co_u32_e32 v21, vcc, 0, v17, vcc
	v_add_co_u32_e32 v22, vcc, s39, v16
	v_readlane_b32 s53, v253, 25
	s_nop 0
	v_addc_co_u32_e32 v23, vcc, 0, v17, vcc
	v_add_co_u32_e32 v24, vcc, s41, v16
	v_readlane_b32 s54, v253, 26
	s_nop 0
	v_addc_co_u32_e32 v25, vcc, 0, v17, vcc
	global_load_dword v32, v[18:19], off offset:-4096 nt
	global_load_dword v33, v[18:19], off nt
	global_load_dword v34, v[20:21], off offset:-4096 nt
	global_load_dword v35, v[20:21], off nt
	global_load_dword v36, v[22:23], off offset:-4096 nt
	global_load_dword v37, v[22:23], off nt
	global_load_dword v38, v[24:25], off offset:-4096 nt
	global_load_dword v39, v[24:25], off nt
	v_add_co_u32_e32 v18, vcc, s42, v16
	v_readlane_b32 s55, v253, 27
	s_nop 0
	v_addc_co_u32_e32 v19, vcc, 0, v17, vcc
	v_add_co_u32_e32 v20, vcc, s43, v16
	v_readlane_b32 s58, v253, 30
	s_nop 0
	v_addc_co_u32_e32 v21, vcc, 0, v17, vcc
	v_add_co_u32_e32 v22, vcc, s45, v16
	v_readlane_b32 s59, v253, 31
	s_nop 0
	v_addc_co_u32_e32 v23, vcc, 0, v17, vcc
	v_add_co_u32_e32 v24, vcc, s46, v16
	v_readlane_b32 s60, v253, 32
	s_nop 0
	v_addc_co_u32_e32 v25, vcc, 0, v17, vcc
	global_load_dword v40, v[18:19], off offset:-4096 nt
	global_load_dword v41, v[18:19], off nt
	global_load_dword v42, v[20:21], off offset:-4096 nt
	global_load_dword v43, v[20:21], off nt
	global_load_dword v44, v[22:23], off offset:-4096 nt
	global_load_dword v45, v[22:23], off nt
	global_load_dword v46, v[24:25], off offset:-4096 nt
	global_load_dword v47, v[24:25], off nt
	v_add_co_u32_e32 v18, vcc, s47, v16
	v_readlane_b32 s61, v253, 33
	s_nop 0
	v_addc_co_u32_e32 v19, vcc, 0, v17, vcc
	v_add_co_u32_e32 v20, vcc, s95, v16
	v_readlane_b32 s62, v253, 34
	s_nop 0
	v_addc_co_u32_e32 v21, vcc, 0, v17, vcc
	v_add_co_u32_e32 v22, vcc, s33, v16
	v_readlane_b32 s63, v253, 35
	s_nop 0
	v_addc_co_u32_e32 v23, vcc, 0, v17, vcc
	v_add_co_u32_e32 v24, vcc, s38, v16
	s_nop 1
	v_addc_co_u32_e32 v25, vcc, 0, v17, vcc
	global_load_dword v48, v[18:19], off offset:-4096 nt
	global_load_dword v49, v[18:19], off nt
	global_load_dword v50, v[20:21], off offset:-4096 nt
	global_load_dword v51, v[20:21], off nt
	global_load_dword v52, v[22:23], off offset:-4096 nt
	global_load_dword v53, v[22:23], off nt
	global_load_dword v54, v[24:25], off offset:-4096 nt
	global_load_dword v55, v[24:25], off nt
	v_add_co_u32_e32 v18, vcc, s40, v16
	s_nop 1
	v_addc_co_u32_e32 v19, vcc, 0, v17, vcc
	v_add_co_u32_e32 v20, vcc, s44, v16
	s_nop 1
	v_addc_co_u32_e32 v21, vcc, 0, v17, vcc
	v_add_co_u32_e32 v22, vcc, s64, v16
	s_nop 1
	v_addc_co_u32_e32 v23, vcc, 0, v17, vcc
	v_add_co_u32_e32 v24, vcc, s68, v16
	s_nop 1
	v_addc_co_u32_e32 v25, vcc, 0, v17, vcc
	global_load_dword v56, v[18:19], off offset:-4096 nt
	global_load_dword v57, v[18:19], off nt
	global_load_dword v58, v[20:21], off offset:-4096 nt
	global_load_dword v59, v[20:21], off nt
	global_load_dword v60, v[22:23], off offset:-4096 nt
	global_load_dword v61, v[22:23], off nt
	global_load_dword v62, v[24:25], off offset:-4096 nt
	global_load_dword v63, v[24:25], off nt
	v_add_co_u32_e32 v18, vcc, s70, v16
	s_nop 1
	v_addc_co_u32_e32 v19, vcc, 0, v17, vcc
	v_add_co_u32_e32 v20, vcc, s85, v16
	s_nop 1
	v_addc_co_u32_e32 v21, vcc, 0, v17, vcc
	v_add_co_u32_e32 v22, vcc, s87, v16
	s_nop 1
	v_addc_co_u32_e32 v23, vcc, 0, v17, vcc
	v_add_co_u32_e32 v24, vcc, s90, v16
	s_nop 1
	v_addc_co_u32_e32 v25, vcc, 0, v17, vcc
	global_load_dword v64, v[18:19], off offset:-4096 nt
	global_load_dword v65, v[18:19], off nt
	global_load_dword v66, v[20:21], off offset:-4096 nt
	global_load_dword v67, v[20:21], off nt
	global_load_dword v68, v[22:23], off offset:-4096 nt
	global_load_dword v69, v[22:23], off nt
	global_load_dword v70, v[24:25], off offset:-4096 nt
	global_load_dword v71, v[24:25], off nt
	v_add_co_u32_e32 v18, vcc, s92, v16
	s_nop 1
	v_addc_co_u32_e32 v19, vcc, 0, v17, vcc
	v_add_co_u32_e32 v20, vcc, s65, v16
	s_nop 1
	v_addc_co_u32_e32 v21, vcc, 0, v17, vcc
	v_add_co_u32_e32 v22, vcc, s66, v16
	s_nop 1
	v_addc_co_u32_e32 v23, vcc, 0, v17, vcc
	v_add_co_u32_e32 v24, vcc, s67, v16
	s_nop 1
	v_addc_co_u32_e32 v25, vcc, 0, v17, vcc
	global_load_dword v72, v[18:19], off offset:-4096 nt
	global_load_dword v73, v[18:19], off nt
	global_load_dword v74, v[20:21], off offset:-4096 nt
	global_load_dword v75, v[20:21], off nt
	global_load_dword v76, v[22:23], off offset:-4096 nt
	global_load_dword v77, v[22:23], off nt
	global_load_dword v78, v[24:25], off offset:-4096 nt
	global_load_dword v79, v[24:25], off nt
	v_add_co_u32_e32 v18, vcc, s69, v16
	s_nop 1
	v_addc_co_u32_e32 v19, vcc, 0, v17, vcc
	v_add_co_u32_e32 v20, vcc, s71, v16
	s_nop 1
	v_addc_co_u32_e32 v21, vcc, 0, v17, vcc
	v_add_co_u32_e32 v22, vcc, s81, v16
	s_nop 1
	v_addc_co_u32_e32 v23, vcc, 0, v17, vcc
	v_add_co_u32_e32 v24, vcc, s82, v16
	s_nop 1
	v_addc_co_u32_e32 v25, vcc, 0, v17, vcc
	global_load_dword v111, v[18:19], off offset:-4096 nt
	s_nop 0
	global_load_dword v18, v[18:19], off nt
	s_nop 0
	global_load_dword v19, v[20:21], off offset:-4096 nt
	s_nop 0
	global_load_dword v20, v[20:21], off nt
	s_nop 0
	global_load_dword v21, v[22:23], off offset:-4096 nt
	s_nop 0
	global_load_dword v22, v[22:23], off nt
	s_nop 0
	global_load_dword v23, v[24:25], off offset:-4096 nt
	s_nop 0
	global_load_dword v24, v[24:25], off nt
	v_add_co_u32_e32 v16, vcc, s84, v16
	s_nop 1
	v_addc_co_u32_e32 v17, vcc, 0, v17, vcc
	global_load_dword v16, v[16:17], off nt
	s_waitcnt vmcnt(62)
; #define LAS __attribute__((address_space(3)))
; __device__ __forceinline__ unsigned pk2(float lo, float hi) { return pg8::cvt_pk_bf16(lo, hi); }
; template <int MODE>
; __device__ __forceinline__ void p0_item(const float* W, int K, int N, bf16u* WT, const float* ks, LAS float* scr, int item, int lane) {
;     ...
; #pragma unroll
;     for (int kk = 0; kk < 64; ++kk) scr[kk * 65 + lane] = v[kk];
;     asm volatile("s_waitcnt lgkmcnt(0)" ::: "memory");
;     const int c = lane & 7;
; #pragma unroll
;     for (int j = 0; j < 8; ++j) { const int n = (lane >> 3) + 8 * j; const LAS float* s = scr + (8 * c) * 65 + n;
;         v4u o; o.x = pk2(s[0 * 65], s[1 * 65]); o.y = pk2(s[2 * 65], s[3 * 65]); o.z = pk2(s[4 * 65], s[5 * 65]); o.w = pk2(s[6 * 65], s[7 * 65]);
;         *(v4u*)(WT + (size_t)(drow + n) * K + k0 + 8 * c) = o; }
;     asm volatile("s_waitcnt lgkmcnt(0)" ::: "memory");
	ds_write2_b32 v80, v2, v26 offset1:65
	s_waitcnt vmcnt(60)
	ds_write2_b32 v80, v27, v28 offset0:130 offset1:195
	s_waitcnt vmcnt(58)
	ds_write2_b32 v95, v29, v30 offset0:4 offset1:69
	s_waitcnt vmcnt(56)
	ds_write2_b32 v95, v31, v32 offset0:134 offset1:199
	s_waitcnt vmcnt(54)
	ds_write2_b32 v96, v33, v34 offset0:8 offset1:73
	s_waitcnt vmcnt(52)
	ds_write2_b32 v96, v35, v36 offset0:138 offset1:203
	s_waitcnt vmcnt(50)
	ds_write2_b32 v97, v37, v38 offset0:12 offset1:77
	s_waitcnt vmcnt(48)
	ds_write2_b32 v97, v39, v40 offset0:142 offset1:207
	s_waitcnt vmcnt(46)
	ds_write2_b32 v98, v41, v42 offset0:16 offset1:81
	s_waitcnt vmcnt(44)
	ds_write2_b32 v98, v43, v44 offset0:146 offset1:211
	s_waitcnt vmcnt(42)
	ds_write2_b32 v99, v45, v46 offset0:20 offset1:85
	s_waitcnt vmcnt(40)
	ds_write2_b32 v99, v47, v48 offset0:150 offset1:215
	s_waitcnt vmcnt(38)
	ds_write2_b32 v100, v49, v50 offset0:24 offset1:89
	s_waitcnt vmcnt(36)
	ds_write2_b32 v100, v51, v52 offset0:154 offset1:219
	s_waitcnt vmcnt(34)
	ds_write2_b32 v101, v53, v54 offset0:28 offset1:93
	s_waitcnt vmcnt(32)
	ds_write2_b32 v101, v55, v56 offset0:158 offset1:223
	s_waitcnt vmcnt(30)
	ds_write2_b32 v102, v57, v58 offset0:32 offset1:97
	s_waitcnt vmcnt(28)
	ds_write2_b32 v102, v59, v60 offset0:162 offset1:227
	s_waitcnt vmcnt(26)
	ds_write2_b32 v103, v61, v62 offset0:36 offset1:101
	s_waitcnt vmcnt(24)
	ds_write2_b32 v103, v63, v64 offset0:166 offset1:231
	s_waitcnt vmcnt(22)
	ds_write2_b32 v104, v65, v66 offset0:40 offset1:105
	s_waitcnt vmcnt(20)
	ds_write2_b32 v104, v67, v68 offset0:170 offset1:235
	s_waitcnt vmcnt(18)
	ds_write2_b32 v105, v69, v70 offset0:44 offset1:109
	s_waitcnt vmcnt(16)
	ds_write2_b32 v105, v71, v72 offset0:174 offset1:239
	s_waitcnt vmcnt(14)
	ds_write2_b32 v106, v73, v74 offset0:48 offset1:113
	s_waitcnt vmcnt(12)
	ds_write2_b32 v106, v75, v76 offset0:178 offset1:243
	s_waitcnt vmcnt(10)
	ds_write2_b32 v107, v77, v78 offset0:52 offset1:117
	s_waitcnt vmcnt(8)
	ds_write2_b32 v107, v79, v111 offset0:182 offset1:247
	s_waitcnt vmcnt(6)
	ds_write2_b32 v108, v18, v19 offset0:56 offset1:121
	s_waitcnt vmcnt(4)
	ds_write2_b32 v108, v20, v21 offset0:186 offset1:251
	s_waitcnt vmcnt(2)
	ds_write2_b32 v109, v22, v23 offset0:60 offset1:125
	s_waitcnt vmcnt(0)
	ds_write2_b32 v109, v24, v16 offset0:190 offset1:255
	s_waitcnt lgkmcnt(0)
	ds_read2_b32 v[20:21], v82 offset0:65 offset1:73
	ds_read2_b32 v[22:23], v82 offset1:8
	ds_read2_b32 v[24:25], v82 offset0:130 offset1:138
	ds_read2_b32 v[26:27], v82 offset0:195 offset1:203
	ds_read2_b32 v[28:29], v110 offset0:4 offset1:12
	ds_read2_b32 v[30:31], v110 offset0:69 offset1:77
	ds_read2_b32 v[32:33], v110 offset0:134 offset1:142
	ds_read2_b32 v[34:35], v110 offset0:199 offset1:207
	v_or_b32_e32 v2, s12, v81
	v_lshl_add_u64 v[36:37], v[8:9], 0, s[10:11]
	v_lshlrev_b32_e32 v2, 11, v2
	s_waitcnt lgkmcnt(6)
	v_cvt_pk_bf16_f32 v16, v22, v20
	s_waitcnt lgkmcnt(4)
	v_cvt_pk_bf16_f32 v17, v24, v26
	s_waitcnt lgkmcnt(2)
	v_cvt_pk_bf16_f32 v18, v28, v30
	s_waitcnt lgkmcnt(0)
	v_cvt_pk_bf16_f32 v19, v32, v34
	v_lshl_add_u64 v[38:39], v[36:37], 0, v[2:3]
	global_store_dwordx4 v[38:39], v[16:19], off
	v_or_b32_e32 v2, s12, v83
	v_lshlrev_b32_e32 v2, 11, v2
	v_cvt_pk_bf16_f32 v16, v23, v21
	v_cvt_pk_bf16_f32 v17, v25, v27
	v_cvt_pk_bf16_f32 v18, v29, v31
	v_cvt_pk_bf16_f32 v19, v33, v35
	ds_read2_b32 v[22:23], v82 offset0:81 offset1:89
	ds_read2_b32 v[24:25], v82 offset0:16 offset1:24
	ds_read2_b32 v[26:27], v82 offset0:146 offset1:154
	ds_read2_b32 v[28:29], v82 offset0:211 offset1:219
	ds_read2_b32 v[30:31], v110 offset0:20 offset1:28
	ds_read2_b32 v[32:33], v110 offset0:85 offset1:93
	ds_read2_b32 v[34:35], v110 offset0:150 offset1:158
	ds_read2_b32 v[38:39], v110 offset0:215 offset1:223
	v_lshl_add_u64 v[20:21], v[36:37], 0, v[2:3]
	v_or_b32_e32 v2, s12, v84
	v_lshlrev_b32_e32 v2, 11, v2
	global_store_dwordx4 v[20:21], v[16:19], off
	v_lshl_add_u64 v[20:21], v[36:37], 0, v[2:3]
	v_or_b32_e32 v2, s12, v85
	s_waitcnt lgkmcnt(6)
	v_cvt_pk_bf16_f32 v16, v24, v22
	s_waitcnt lgkmcnt(4)
	v_cvt_pk_bf16_f32 v17, v26, v28
	s_waitcnt lgkmcnt(2)
	v_cvt_pk_bf16_f32 v18, v30, v32
	s_waitcnt lgkmcnt(0)
	v_cvt_pk_bf16_f32 v19, v34, v38
	global_store_dwordx4 v[20:21], v[16:19], off
	v_lshlrev_b32_e32 v2, 11, v2
	v_lshl_add_u64 v[20:21], v[36:37], 0, v[2:3]
	v_cvt_pk_bf16_f32 v16, v25, v23
	v_cvt_pk_bf16_f32 v17, v27, v29
	v_cvt_pk_bf16_f32 v18, v31, v33
	v_cvt_pk_bf16_f32 v19, v35, v39
	ds_read2_b32 v[22:23], v82 offset0:32 offset1:40
	ds_read2_b32 v[24:25], v82 offset0:97 offset1:105
	ds_read2_b32 v[26:27], v82 offset0:162 offset1:170
	ds_read2_b32 v[28:29], v82 offset0:227 offset1:235
	ds_read2_b32 v[30:31], v110 offset0:36 offset1:44
	ds_read2_b32 v[32:33], v110 offset0:101 offset1:109
	ds_read2_b32 v[34:35], v110 offset0:166 offset1:174
	ds_read2_b32 v[38:39], v110 offset0:231 offset1:239
	v_or_b32_e32 v2, s12, v86
	v_lshlrev_b32_e32 v2, 11, v2
	global_store_dwordx4 v[20:21], v[16:19], off
	v_lshl_add_u64 v[20:21], v[36:37], 0, v[2:3]
	v_or_b32_e32 v2, s12, v87
	s_waitcnt lgkmcnt(6)
	v_cvt_pk_bf16_f32 v16, v22, v24
	s_waitcnt lgkmcnt(4)
	v_cvt_pk_bf16_f32 v17, v26, v28
	s_waitcnt lgkmcnt(2)
	v_cvt_pk_bf16_f32 v18, v30, v32
	s_waitcnt lgkmcnt(0)
	v_cvt_pk_bf16_f32 v19, v34, v38
	global_store_dwordx4 v[20:21], v[16:19], off
	v_lshlrev_b32_e32 v2, 11, v2
	v_lshl_add_u64 v[20:21], v[36:37], 0, v[2:3]
	v_cvt_pk_bf16_f32 v16, v23, v25
	v_cvt_pk_bf16_f32 v17, v27, v29
	v_cvt_pk_bf16_f32 v18, v31, v33
	v_cvt_pk_bf16_f32 v19, v35, v39
	ds_read2_b32 v[22:23], v82 offset0:48 offset1:56
	ds_read2_b32 v[24:25], v82 offset0:113 offset1:121
	ds_read2_b32 v[26:27], v82 offset0:178 offset1:186
	ds_read2_b32 v[28:29], v82 offset0:243 offset1:251
	ds_read2_b32 v[30:31], v110 offset0:52 offset1:60
	ds_read2_b32 v[32:33], v110 offset0:117 offset1:125
	ds_read2_b32 v[34:35], v110 offset0:182 offset1:190
	ds_read2_b32 v[38:39], v110 offset0:247 offset1:255
	v_or_b32_e32 v2, s12, v88
	v_lshlrev_b32_e32 v2, 11, v2
	global_store_dwordx4 v[20:21], v[16:19], off
	v_lshl_add_u64 v[20:21], v[36:37], 0, v[2:3]
	v_or_b32_e32 v2, s12, v89
	s_waitcnt lgkmcnt(6)
	v_cvt_pk_bf16_f32 v16, v22, v24
	s_waitcnt lgkmcnt(4)
	v_cvt_pk_bf16_f32 v17, v26, v28
	s_waitcnt lgkmcnt(2)
	v_cvt_pk_bf16_f32 v18, v30, v32
	s_waitcnt lgkmcnt(0)
	v_cvt_pk_bf16_f32 v19, v34, v38
	v_lshlrev_b32_e32 v2, 11, v2
	global_store_dwordx4 v[20:21], v[16:19], off
	v_lshl_add_u64 v[20:21], v[36:37], 0, v[2:3]
	s_nop 0
	v_cvt_pk_bf16_f32 v16, v23, v25
	v_cvt_pk_bf16_f32 v17, v27, v29
	v_cvt_pk_bf16_f32 v18, v31, v33
	v_cvt_pk_bf16_f32 v19, v35, v39
	global_store_dwordx4 v[20:21], v[16:19], off
	s_waitcnt lgkmcnt(0)

; template <int MODE>
; __device__ __forceinline__ void p0_item(const float* W, int K, int N, bf16u* WT, const float* ks, LAS float* scr, int item, int lane) {
;     const int nblk = N / 64, kb = item / nblk, nb = item - kb * nblk, k0 = 64 * kb, n0 = 64 * nb;
;     int nn = n0 + lane;
;     if (MODE == 1) {
;         if (nn < 2048) { const int p = nn & 63; if (p < 16) nn = (nn & ~15) | (p & 3) | ((p & 4) << 1) | ((p & 8) >> 1); }
;         else if (nn >= 4096) { const int sec = nn >= 6144 ? 6144 : 4096, r = nn - sec, q = r & 255; nn = sec + ((q >> 7) << 10) + 128 * (r >> 8) + (q & 127); }
;     }
;     int drow = n0;
;     if (MODE == 2) drow = 256 * (n0 >> 7) + (n0 & 127);
;     if (MODE == 3) drow = 256 * (n0 >> 7) + 128 + (n0 & 127);
;     const float* src = W + (size_t)k0 * N + nn;
;     float v[64];
; #pragma unroll
;     for (int kk = 0; kk < 64; ++kk) v[kk] = src[(size_t)kk * N];
.LBB0_30:
	s_andn2_b64 vcc, exec, s[12:13]
	s_cbranch_vccnz .LBB0_32
	s_add_i32 s10, s18, 0xffffdc00
	s_add_i32 s12, s17, s80
	s_and_b32 s10, s10, 0xfc0
	s_add_i32 s12, s12, 0xfffdc000
	v_readlane_b32 s48, v253, 20
	s_and_b32 s12, s12, 0x3c0
	s_lshl_b32 s13, s10, 12
	v_readlane_b32 s54, v253, 26
	v_or_b32_e32 v2, s12, v1
	v_readlane_b32 s55, v253, 27
	s_add_u32 s88, s54, s13
	s_addc_u32 s89, s55, 0
	v_lshlrev_b32_e32 v2, 2, v2
	v_lshl_add_u64 v[16:17], s[88:89], 0, v[2:3]
	v_add_co_u32_e32 v18, vcc, s30, v16
	s_lshl_b32 s10, s10, 1
	s_nop 0
	v_addc_co_u32_e32 v19, vcc, 0, v17, vcc
	v_add_co_u32_e32 v20, vcc, s31, v16
	v_readlane_b32 s49, v253, 21
	s_nop 0
	v_addc_co_u32_e32 v21, vcc, 0, v17, vcc
	v_add_co_u32_e32 v22, vcc, s35, v16
	v_readlane_b32 s50, v253, 22
	s_nop 0
	v_addc_co_u32_e32 v23, vcc, 0, v17, vcc
	global_load_dword v2, v2, s[88:89] nt
	s_nop 0
	global_load_dword v26, v[18:19], off offset:-4096 nt
	global_load_dword v27, v[18:19], off nt
	global_load_dword v28, v[20:21], off offset:-4096 nt
	global_load_dword v29, v[20:21], off nt
	global_load_dword v30, v[22:23], off offset:-4096 nt
	global_load_dword v31, v[22:23], off nt
	v_add_co_u32_e32 v18, vcc, s36, v16
	v_readlane_b32 s51, v253, 23
	s_nop 0
	v_addc_co_u32_e32 v19, vcc, 0, v17, vcc
	v_add_co_u32_e32 v20, vcc, s37, v16
	v_readlane_b32 s52, v253, 24
	s_nop 0
	v_addc_co_u32_e32 v21, vcc, 0, v17, vcc
	v_add_co_u32_e32 v22, vcc, s39, v16
	v_readlane_b32 s53, v253, 25
	s_nop 0
	v_addc_co_u32_e32 v23, vcc, 0, v17, vcc
	v_add_co_u32_e32 v24, vcc, s41, v16
	v_readlane_b32 s56, v253, 28
	s_nop 0
	v_addc_co_u32_e32 v25, vcc, 0, v17, vcc
	global_load_dword v32, v[18:19], off offset:-4096 nt
	global_load_dword v33, v[18:19], off nt
	global_load_dword v34, v[20:21], off offset:-4096 nt
	global_load_dword v35, v[20:21], off nt
	global_load_dword v36, v[22:23], off offset:-4096 nt
	global_load_dword v37, v[22:23], off nt
	global_load_dword v38, v[24:25], off offset:-4096 nt
	global_load_dword v39, v[24:25], off nt
	v_add_co_u32_e32 v18, vcc, s42, v16
	v_readlane_b32 s57, v253, 29
	s_nop 0
	v_addc_co_u32_e32 v19, vcc, 0, v17, vcc
	v_add_co_u32_e32 v20, vcc, s43, v16
	v_readlane_b32 s58, v253, 30
	s_nop 0
	v_addc_co_u32_e32 v21, vcc, 0, v17, vcc
	v_add_co_u32_e32 v22, vcc, s45, v16
	v_readlane_b32 s59, v253, 31
	s_nop 0
	v_addc_co_u32_e32 v23, vcc, 0, v17, vcc
	v_add_co_u32_e32 v24, vcc, s46, v16
	v_readlane_b32 s60, v253, 32
	s_nop 0
	v_addc_co_u32_e32 v25, vcc, 0, v17, vcc
	global_load_dword v40, v[18:19], off offset:-4096 nt
	global_load_dword v41, v[18:19], off nt
	global_load_dword v42, v[20:21], off offset:-4096 nt
	global_load_dword v43, v[20:21], off nt
	global_load_dword v44, v[22:23], off offset:-4096 nt
	global_load_dword v45, v[22:23], off nt
	global_load_dword v46, v[24:25], off offset:-4096 nt
	global_load_dword v47, v[24:25], off nt
	v_add_co_u32_e32 v18, vcc, s47, v16
	v_readlane_b32 s61, v253, 33
	s_nop 0
	v_addc_co_u32_e32 v19, vcc, 0, v17, vcc
	v_add_co_u32_e32 v20, vcc, s95, v16
	v_readlane_b32 s62, v253, 34
	s_nop 0
	v_addc_co_u32_e32 v21, vcc, 0, v17, vcc
	v_add_co_u32_e32 v22, vcc, s33, v16
	v_readlane_b32 s63, v253, 35
	s_nop 0
	v_addc_co_u32_e32 v23, vcc, 0, v17, vcc
	v_add_co_u32_e32 v24, vcc, s38, v16
	s_nop 1
	v_addc_co_u32_e32 v25, vcc, 0, v17, vcc
	global_load_dword v48, v[18:19], off offset:-4096 nt
	global_load_dword v49, v[18:19], off nt
	global_load_dword v50, v[20:21], off offset:-4096 nt
	global_load_dword v51, v[20:21], off nt
	global_load_dword v52, v[22:23], off offset:-4096 nt
	global_load_dword v53, v[22:23], off nt
	global_load_dword v54, v[24:25], off offset:-4096 nt
	global_load_dword v55, v[24:25], off nt
	v_add_co_u32_e32 v18, vcc, s40, v16
	s_nop 1
	v_addc_co_u32_e32 v19, vcc, 0, v17, vcc
	v_add_co_u32_e32 v20, vcc, s44, v16
	s_nop 1
	v_addc_co_u32_e32 v21, vcc, 0, v17, vcc
	v_add_co_u32_e32 v22, vcc, s64, v16
	s_nop 1
	v_addc_co_u32_e32 v23, vcc, 0, v17, vcc
	v_add_co_u32_e32 v24, vcc, s68, v16
	s_nop 1
	v_addc_co_u32_e32 v25, vcc, 0, v17, vcc
	global_load_dword v56, v[18:19], off offset:-4096 nt
	global_load_dword v57, v[18:19], off nt
	global_load_dword v58, v[20:21], off offset:-4096 nt
	global_load_dword v59, v[20:21], off nt
	global_load_dword v60, v[22:23], off offset:-4096 nt
	global_load_dword v61, v[22:23], off nt
	global_load_dword v62, v[24:25], off offset:-4096 nt
	global_load_dword v63, v[24:25], off nt
	v_add_co_u32_e32 v18, vcc, s70, v16
	s_nop 1
	v_addc_co_u32_e32 v19, vcc, 0, v17, vcc
	v_add_co_u32_e32 v20, vcc, s85, v16
	s_nop 1
	v_addc_co_u32_e32 v21, vcc, 0, v17, vcc
	v_add_co_u32_e32 v22, vcc, s87, v16
	s_nop 1
	v_addc_co_u32_e32 v23, vcc, 0, v17, vcc
	v_add_co_u32_e32 v24, vcc, s90, v16
	s_nop 1
	v_addc_co_u32_e32 v25, vcc, 0, v17, vcc
	global_load_dword v64, v[18:19], off offset:-4096 nt
	global_load_dword v65, v[18:19], off nt
	global_load_dword v66, v[20:21], off offset:-4096 nt
	global_load_dword v67, v[20:21], off nt
	global_load_dword v68, v[22:23], off offset:-4096 nt
	global_load_dword v69, v[22:23], off nt
	global_load_dword v70, v[24:25], off offset:-4096 nt
	global_load_dword v71, v[24:25], off nt
	v_add_co_u32_e32 v18, vcc, s92, v16
	s_nop 1
	v_addc_co_u32_e32 v19, vcc, 0, v17, vcc
	v_add_co_u32_e32 v20, vcc, s65, v16
	s_nop 1
	v_addc_co_u32_e32 v21, vcc, 0, v17, vcc
	v_add_co_u32_e32 v22, vcc, s66, v16
	s_nop 1
	v_addc_co_u32_e32 v23, vcc, 0, v17, vcc
	v_add_co_u32_e32 v24, vcc, s67, v16
	s_nop 1
	v_addc_co_u32_e32 v25, vcc, 0, v17, vcc
	global_load_dword v72, v[18:19], off offset:-4096 nt
	global_load_dword v73, v[18:19], off nt
	global_load_dword v74, v[20:21], off offset:-4096 nt
	global_load_dword v75, v[20:21], off nt
	global_load_dword v76, v[22:23], off offset:-4096 nt
	global_load_dword v77, v[22:23], off nt
	global_load_dword v78, v[24:25], off offset:-4096 nt
	global_load_dword v79, v[24:25], off nt
	v_add_co_u32_e32 v18, vcc, s69, v16
	s_nop 1
	v_addc_co_u32_e32 v19, vcc, 0, v17, vcc
	v_add_co_u32_e32 v20, vcc, s71, v16
	s_nop 1
	v_addc_co_u32_e32 v21, vcc, 0, v17, vcc
	v_add_co_u32_e32 v22, vcc, s81, v16
	s_nop 1
	v_addc_co_u32_e32 v23, vcc, 0, v17, vcc
	v_add_co_u32_e32 v24, vcc, s82, v16
	s_nop 1
	v_addc_co_u32_e32 v25, vcc, 0, v17, vcc
	global_load_dword v111, v[18:19], off offset:-4096 nt
	s_nop 0
	global_load_dword v18, v[18:19], off nt
	s_nop 0
	global_load_dword v19, v[20:21], off offset:-4096 nt
	s_nop 0
	global_load_dword v20, v[20:21], off nt
	s_nop 0
	global_load_dword v21, v[22:23], off offset:-4096 nt
	s_nop 0
	global_load_dword v22, v[22:23], off nt
	s_nop 0
	global_load_dword v23, v[24:25], off offset:-4096 nt
	s_nop 0
	global_load_dword v24, v[24:25], off nt
	v_add_co_u32_e32 v16, vcc, s84, v16
	s_nop 1
	v_addc_co_u32_e32 v17, vcc, 0, v17, vcc
	global_load_dword v16, v[16:17], off nt
	s_waitcnt vmcnt(62)
; #define LAS __attribute__((address_space(3)))
; __device__ __forceinline__ unsigned pk2(float lo, float hi) { return pg8::cvt_pk_bf16(lo, hi); }
; template <int MODE>
; __device__ __forceinline__ void p0_item(const float* W, int K, int N, bf16u* WT, const float* ks, LAS float* scr, int item, int lane) {
;     ...
; #pragma unroll
;     for (int kk = 0; kk < 64; ++kk) scr[kk * 65 + lane] = v[kk];
;     asm volatile("s_waitcnt lgkmcnt(0)" ::: "memory");
;     const int c = lane & 7;
; #pragma unroll
;     for (int j = 0; j < 8; ++j) { const int n = (lane >> 3) + 8 * j; const LAS float* s = scr + (8 * c) * 65 + n;
;         v4u o; o.x = pk2(s[0 * 65], s[1 * 65]); o.y = pk2(s[2 * 65], s[3 * 65]); o.z = pk2(s[4 * 65], s[5 * 65]); o.w = pk2(s[6 * 65], s[7 * 65]);
;         *(v4u*)(WT + (size_t)(drow + n) * K + k0 + 8 * c) = o; }
;     asm volatile("s_waitcnt lgkmcnt(0)" ::: "memory");
	ds_write2_b32 v80, v2, v26 offset1:65
	s_waitcnt vmcnt(60)
	ds_write2_b32 v80, v27, v28 offset0:130 offset1:195
	s_waitcnt vmcnt(58)
	ds_write2_b32 v95, v29, v30 offset0:4 offset1:69
	s_waitcnt vmcnt(56)
	ds_write2_b32 v95, v31, v32 offset0:134 offset1:199
	s_waitcnt vmcnt(54)
	ds_write2_b32 v96, v33, v34 offset0:8 offset1:73
	s_waitcnt vmcnt(52)
	ds_write2_b32 v96, v35, v36 offset0:138 offset1:203
	s_waitcnt vmcnt(50)
	ds_write2_b32 v97, v37, v38 offset0:12 offset1:77
	s_waitcnt vmcnt(48)
	ds_write2_b32 v97, v39, v40 offset0:142 offset1:207
	s_waitcnt vmcnt(46)
	ds_write2_b32 v98, v41, v42 offset0:16 offset1:81
	s_waitcnt vmcnt(44)
	ds_write2_b32 v98, v43, v44 offset0:146 offset1:211
	s_waitcnt vmcnt(42)
	ds_write2_b32 v99, v45, v46 offset0:20 offset1:85
	s_waitcnt vmcnt(40)
	ds_write2_b32 v99, v47, v48 offset0:150 offset1:215
	s_waitcnt vmcnt(38)
	ds_write2_b32 v100, v49, v50 offset0:24 offset1:89
	s_waitcnt vmcnt(36)
	ds_write2_b32 v100, v51, v52 offset0:154 offset1:219
	s_waitcnt vmcnt(34)
	ds_write2_b32 v101, v53, v54 offset0:28 offset1:93
	s_waitcnt vmcnt(32)
	ds_write2_b32 v101, v55, v56 offset0:158 offset1:223
	s_waitcnt vmcnt(30)
	ds_write2_b32 v102, v57, v58 offset0:32 offset1:97
	s_waitcnt vmcnt(28)
	ds_write2_b32 v102, v59, v60 offset0:162 offset1:227
	s_waitcnt vmcnt(26)
	ds_write2_b32 v103, v61, v62 offset0:36 offset1:101
	s_waitcnt vmcnt(24)
	ds_write2_b32 v103, v63, v64 offset0:166 offset1:231
	s_waitcnt vmcnt(22)
	ds_write2_b32 v104, v65, v66 offset0:40 offset1:105
	s_waitcnt vmcnt(20)
	ds_write2_b32 v104, v67, v68 offset0:170 offset1:235
	s_waitcnt vmcnt(18)
	ds_write2_b32 v105, v69, v70 offset0:44 offset1:109
	s_waitcnt vmcnt(16)
	ds_write2_b32 v105, v71, v72 offset0:174 offset1:239
	s_waitcnt vmcnt(14)
	ds_write2_b32 v106, v73, v74 offset0:48 offset1:113
	s_waitcnt vmcnt(12)
	ds_write2_b32 v106, v75, v76 offset0:178 offset1:243
	s_waitcnt vmcnt(10)
	ds_write2_b32 v107, v77, v78 offset0:52 offset1:117
	s_waitcnt vmcnt(8)
	ds_write2_b32 v107, v79, v111 offset0:182 offset1:247
	s_waitcnt vmcnt(6)
	ds_write2_b32 v108, v18, v19 offset0:56 offset1:121
	s_waitcnt vmcnt(4)
	ds_write2_b32 v108, v20, v21 offset0:186 offset1:251
	s_waitcnt vmcnt(2)
	ds_write2_b32 v109, v22, v23 offset0:60 offset1:125
	s_waitcnt vmcnt(0)
	ds_write2_b32 v109, v24, v16 offset0:190 offset1:255
	s_waitcnt lgkmcnt(0)
	ds_read2_b32 v[20:21], v82 offset0:65 offset1:73
	ds_read2_b32 v[22:23], v82 offset1:8
	ds_read2_b32 v[24:25], v82 offset0:130 offset1:138
	ds_read2_b32 v[26:27], v82 offset0:195 offset1:203
	ds_read2_b32 v[28:29], v110 offset0:4 offset1:12
	ds_read2_b32 v[30:31], v110 offset0:69 offset1:77
	ds_read2_b32 v[32:33], v110 offset0:134 offset1:142
	ds_read2_b32 v[34:35], v110 offset0:199 offset1:207
	v_or_b32_e32 v2, s12, v81
	v_lshl_add_u64 v[36:37], v[10:11], 0, s[10:11]
	v_lshlrev_b32_e32 v2, 11, v2
	s_waitcnt lgkmcnt(6)
	v_cvt_pk_bf16_f32 v16, v22, v20
	s_waitcnt lgkmcnt(4)
	v_cvt_pk_bf16_f32 v17, v24, v26
	s_waitcnt lgkmcnt(2)
	v_cvt_pk_bf16_f32 v18, v28, v30
	s_waitcnt lgkmcnt(0)
	v_cvt_pk_bf16_f32 v19, v32, v34
	v_lshl_add_u64 v[38:39], v[36:37], 0, v[2:3]
	global_store_dwordx4 v[38:39], v[16:19], off
	v_or_b32_e32 v2, s12, v83
	v_lshlrev_b32_e32 v2, 11, v2
	v_cvt_pk_bf16_f32 v16, v23, v21
	v_cvt_pk_bf16_f32 v17, v25, v27
	v_cvt_pk_bf16_f32 v18, v29, v31
	v_cvt_pk_bf16_f32 v19, v33, v35
	ds_read2_b32 v[22:23], v82 offset0:81 offset1:89
	ds_read2_b32 v[24:25], v82 offset0:16 offset1:24
	ds_read2_b32 v[26:27], v82 offset0:146 offset1:154
	ds_read2_b32 v[28:29], v82 offset0:211 offset1:219
	ds_read2_b32 v[30:31], v110 offset0:20 offset1:28
	ds_read2_b32 v[32:33], v110 offset0:85 offset1:93
	ds_read2_b32 v[34:35], v110 offset0:150 offset1:158
	ds_read2_b32 v[38:39], v110 offset0:215 offset1:223
	v_lshl_add_u64 v[20:21], v[36:37], 0, v[2:3]
	v_or_b32_e32 v2, s12, v84
	v_lshlrev_b32_e32 v2, 11, v2
	global_store_dwordx4 v[20:21], v[16:19], off
	v_lshl_add_u64 v[20:21], v[36:37], 0, v[2:3]
	v_or_b32_e32 v2, s12, v85
	s_waitcnt lgkmcnt(6)
	v_cvt_pk_bf16_f32 v16, v24, v22
	s_waitcnt lgkmcnt(4)
	v_cvt_pk_bf16_f32 v17, v26, v28
	s_waitcnt lgkmcnt(2)
	v_cvt_pk_bf16_f32 v18, v30, v32
	s_waitcnt lgkmcnt(0)
	v_cvt_pk_bf16_f32 v19, v34, v38
	global_store_dwordx4 v[20:21], v[16:19], off
	v_lshlrev_b32_e32 v2, 11, v2
	v_lshl_add_u64 v[20:21], v[36:37], 0, v[2:3]
	v_cvt_pk_bf16_f32 v16, v25, v23
	v_cvt_pk_bf16_f32 v17, v27, v29
	v_cvt_pk_bf16_f32 v18, v31, v33
	v_cvt_pk_bf16_f32 v19, v35, v39
	ds_read2_b32 v[22:23], v82 offset0:32 offset1:40
	ds_read2_b32 v[24:25], v82 offset0:97 offset1:105
	ds_read2_b32 v[26:27], v82 offset0:162 offset1:170
	ds_read2_b32 v[28:29], v82 offset0:227 offset1:235
	ds_read2_b32 v[30:31], v110 offset0:36 offset1:44
	ds_read2_b32 v[32:33], v110 offset0:101 offset1:109
	ds_read2_b32 v[34:35], v110 offset0:166 offset1:174
	ds_read2_b32 v[38:39], v110 offset0:231 offset1:239
	v_or_b32_e32 v2, s12, v86
	v_lshlrev_b32_e32 v2, 11, v2
	global_store_dwordx4 v[20:21], v[16:19], off
	v_lshl_add_u64 v[20:21], v[36:37], 0, v[2:3]
	v_or_b32_e32 v2, s12, v87
	s_waitcnt lgkmcnt(6)
	v_cvt_pk_bf16_f32 v16, v22, v24
	s_waitcnt lgkmcnt(4)
	v_cvt_pk_bf16_f32 v17, v26, v28
	s_waitcnt lgkmcnt(2)
	v_cvt_pk_bf16_f32 v18, v30, v32
	s_waitcnt lgkmcnt(0)
	v_cvt_pk_bf16_f32 v19, v34, v38
	global_store_dwordx4 v[20:21], v[16:19], off
	v_lshlrev_b32_e32 v2, 11, v2
	v_lshl_add_u64 v[20:21], v[36:37], 0, v[2:3]
	v_cvt_pk_bf16_f32 v16, v23, v25
	v_cvt_pk_bf16_f32 v17, v27, v29
	v_cvt_pk_bf16_f32 v18, v31, v33
	v_cvt_pk_bf16_f32 v19, v35, v39
	ds_read2_b32 v[22:23], v82 offset0:48 offset1:56
	ds_read2_b32 v[24:25], v82 offset0:113 offset1:121
	ds_read2_b32 v[26:27], v82 offset0:178 offset1:186
	ds_read2_b32 v[28:29], v82 offset0:243 offset1:251
	ds_read2_b32 v[30:31], v110 offset0:52 offset1:60
	ds_read2_b32 v[32:33], v110 offset0:117 offset1:125
	ds_read2_b32 v[34:35], v110 offset0:182 offset1:190
	ds_read2_b32 v[38:39], v110 offset0:247 offset1:255
	v_or_b32_e32 v2, s12, v88
	v_lshlrev_b32_e32 v2, 11, v2
	global_store_dwordx4 v[20:21], v[16:19], off
	v_lshl_add_u64 v[20:21], v[36:37], 0, v[2:3]
	v_or_b32_e32 v2, s12, v89
	s_waitcnt lgkmcnt(6)
	v_cvt_pk_bf16_f32 v16, v22, v24
	s_waitcnt lgkmcnt(4)
	v_cvt_pk_bf16_f32 v17, v26, v28
	s_waitcnt lgkmcnt(2)
	v_cvt_pk_bf16_f32 v18, v30, v32
	s_waitcnt lgkmcnt(0)
	v_cvt_pk_bf16_f32 v19, v34, v38
	v_lshlrev_b32_e32 v2, 11, v2
	global_store_dwordx4 v[20:21], v[16:19], off
	v_lshl_add_u64 v[20:21], v[36:37], 0, v[2:3]
	s_nop 0
	v_cvt_pk_bf16_f32 v16, v23, v25
	v_cvt_pk_bf16_f32 v17, v27, v29
	v_cvt_pk_bf16_f32 v18, v31, v33
	v_cvt_pk_bf16_f32 v19, v35, v39
	global_store_dwordx4 v[20:21], v[16:19], off
	s_waitcnt lgkmcnt(0)

; template <int MODE>
; __device__ __forceinline__ void p0_item(const float* W, int K, int N, bf16u* WT, const float* ks, LAS float* scr, int item, int lane) {
;     const int nblk = N / 64, kb = item / nblk, nb = item - kb * nblk, k0 = 64 * kb, n0 = 64 * nb;
;     int nn = n0 + lane;
;     if (MODE == 1) {
;         if (nn < 2048) { const int p = nn & 63; if (p < 16) nn = (nn & ~15) | (p & 3) | ((p & 4) << 1) | ((p & 8) >> 1); }
;         else if (nn >= 4096) { const int sec = nn >= 6144 ? 6144 : 4096, r = nn - sec, q = r & 255; nn = sec + ((q >> 7) << 10) + 128 * (r >> 8) + (q & 127); }
;     }
;     int drow = n0;
;     if (MODE == 2) drow = 256 * (n0 >> 7) + (n0 & 127);
;     if (MODE == 3) drow = 256 * (n0 >> 7) + 128 + (n0 & 127);
;     const float* src = W + (size_t)k0 * N + nn;
;     float v[64];
; #pragma unroll
;     for (int kk = 0; kk < 64; ++kk) v[kk] = src[(size_t)kk * N];
.LBB0_33:
	s_andn2_b64 vcc, exec, s[12:13]
	s_cbranch_vccnz .LBB0_35
	s_add_i32 s10, s18, 0xffffe000
	s_add_i32 s12, s17, s80
	s_and_b32 s10, s10, 0xfc0
	s_add_i32 s12, s12, 0xfffe0000
	v_readlane_b32 s48, v253, 20
	s_and_b32 s12, s12, 0x3c0
	s_lshl_b32 s13, s10, 12
	v_readlane_b32 s52, v253, 24
	v_or_b32_e32 v2, s12, v1
	v_readlane_b32 s53, v253, 25
	s_add_u32 s88, s52, s13
	s_addc_u32 s89, s53, 0
	v_lshlrev_b32_e32 v2, 2, v2
	v_lshl_add_u64 v[16:17], s[88:89], 0, v[2:3]
	v_add_co_u32_e32 v18, vcc, s30, v16
	s_lshl_b32 s10, s10, 1
	s_nop 0
	v_addc_co_u32_e32 v19, vcc, 0, v17, vcc
	v_add_co_u32_e32 v20, vcc, s31, v16
	v_readlane_b32 s49, v253, 21
	s_nop 0
	v_addc_co_u32_e32 v21, vcc, 0, v17, vcc
	v_add_co_u32_e32 v22, vcc, s35, v16
	v_readlane_b32 s50, v253, 22
	s_nop 0
	v_addc_co_u32_e32 v23, vcc, 0, v17, vcc
	global_load_dword v2, v2, s[88:89] nt
	s_nop 0
	global_load_dword v26, v[18:19], off offset:-4096 nt
	global_load_dword v27, v[18:19], off nt
	global_load_dword v28, v[20:21], off offset:-4096 nt
	global_load_dword v29, v[20:21], off nt
	global_load_dword v30, v[22:23], off offset:-4096 nt
	global_load_dword v31, v[22:23], off nt
	v_add_co_u32_e32 v18, vcc, s36, v16
	v_readlane_b32 s51, v253, 23
	s_nop 0
	v_addc_co_u32_e32 v19, vcc, 0, v17, vcc
	v_add_co_u32_e32 v20, vcc, s37, v16
	v_readlane_b32 s54, v253, 26
	s_nop 0
	v_addc_co_u32_e32 v21, vcc, 0, v17, vcc
	v_add_co_u32_e32 v22, vcc, s39, v16
	v_readlane_b32 s55, v253, 27
	s_nop 0
	v_addc_co_u32_e32 v23, vcc, 0, v17, vcc
	v_add_co_u32_e32 v24, vcc, s41, v16
	v_readlane_b32 s56, v253, 28
	s_nop 0
	v_addc_co_u32_e32 v25, vcc, 0, v17, vcc
	global_load_dword v32, v[18:19], off offset:-4096 nt
	global_load_dword v33, v[18:19], off nt
	global_load_dword v34, v[20:21], off offset:-4096 nt
	global_load_dword v35, v[20:21], off nt
	global_load_dword v36, v[22:23], off offset:-4096 nt
	global_load_dword v37, v[22:23], off nt
	global_load_dword v38, v[24:25], off offset:-4096 nt
	global_load_dword v39, v[24:25], off nt
	v_add_co_u32_e32 v18, vcc, s42, v16
	v_readlane_b32 s57, v253, 29
	s_nop 0
	v_addc_co_u32_e32 v19, vcc, 0, v17, vcc
	v_add_co_u32_e32 v20, vcc, s43, v16
	v_readlane_b32 s58, v253, 30
	s_nop 0
	v_addc_co_u32_e32 v21, vcc, 0, v17, vcc
	v_add_co_u32_e32 v22, vcc, s45, v16
	v_readlane_b32 s59, v253, 31
	s_nop 0
	v_addc_co_u32_e32 v23, vcc, 0, v17, vcc
	v_add_co_u32_e32 v24, vcc, s46, v16
	v_readlane_b32 s60, v253, 32
	s_nop 0
	v_addc_co_u32_e32 v25, vcc, 0, v17, vcc
	global_load_dword v40, v[18:19], off offset:-4096 nt
	global_load_dword v41, v[18:19], off nt
	global_load_dword v42, v[20:21], off offset:-4096 nt
	global_load_dword v43, v[20:21], off nt
	global_load_dword v44, v[22:23], off offset:-4096 nt
	global_load_dword v45, v[22:23], off nt
	global_load_dword v46, v[24:25], off offset:-4096 nt
	global_load_dword v47, v[24:25], off nt
	v_add_co_u32_e32 v18, vcc, s47, v16
	v_readlane_b32 s61, v253, 33
	s_nop 0
	v_addc_co_u32_e32 v19, vcc, 0, v17, vcc
	v_add_co_u32_e32 v20, vcc, s95, v16
	v_readlane_b32 s62, v253, 34
	s_nop 0
	v_addc_co_u32_e32 v21, vcc, 0, v17, vcc
	v_add_co_u32_e32 v22, vcc, s33, v16
	v_readlane_b32 s63, v253, 35
	s_nop 0
	v_addc_co_u32_e32 v23, vcc, 0, v17, vcc
	v_add_co_u32_e32 v24, vcc, s38, v16
	s_nop 1
	v_addc_co_u32_e32 v25, vcc, 0, v17, vcc
	global_load_dword v48, v[18:19], off offset:-4096 nt
	global_load_dword v49, v[18:19], off nt
	global_load_dword v50, v[20:21], off offset:-4096 nt
	global_load_dword v51, v[20:21], off nt
	global_load_dword v52, v[22:23], off offset:-4096 nt
	global_load_dword v53, v[22:23], off nt
	global_load_dword v54, v[24:25], off offset:-4096 nt
	global_load_dword v55, v[24:25], off nt
	v_add_co_u32_e32 v18, vcc, s40, v16
	s_nop 1
	v_addc_co_u32_e32 v19, vcc, 0, v17, vcc
	v_add_co_u32_e32 v20, vcc, s44, v16
	s_nop 1
	v_addc_co_u32_e32 v21, vcc, 0, v17, vcc
	v_add_co_u32_e32 v22, vcc, s64, v16
	s_nop 1
	v_addc_co_u32_e32 v23, vcc, 0, v17, vcc
	v_add_co_u32_e32 v24, vcc, s68, v16
	s_nop 1
	v_addc_co_u32_e32 v25, vcc, 0, v17, vcc
	global_load_dword v56, v[18:19], off offset:-4096 nt
	global_load_dword v57, v[18:19], off nt
	global_load_dword v58, v[20:21], off offset:-4096 nt
	global_load_dword v59, v[20:21], off nt
	global_load_dword v60, v[22:23], off offset:-4096 nt
	global_load_dword v61, v[22:23], off nt
	global_load_dword v62, v[24:25], off offset:-4096 nt
	global_load_dword v63, v[24:25], off nt
	v_add_co_u32_e32 v18, vcc, s70, v16
	s_nop 1
	v_addc_co_u32_e32 v19, vcc, 0, v17, vcc
	v_add_co_u32_e32 v20, vcc, s85, v16
	s_nop 1
	v_addc_co_u32_e32 v21, vcc, 0, v17, vcc
	v_add_co_u32_e32 v22, vcc, s87, v16
	s_nop 1
	v_addc_co_u32_e32 v23, vcc, 0, v17, vcc
	v_add_co_u32_e32 v24, vcc, s90, v16
	s_nop 1
	v_addc_co_u32_e32 v25, vcc, 0, v17, vcc
	global_load_dword v64, v[18:19], off offset:-4096 nt
	global_load_dword v65, v[18:19], off nt
	global_load_dword v66, v[20:21], off offset:-4096 nt
	global_load_dword v67, v[20:21], off nt
	global_load_dword v68, v[22:23], off offset:-4096 nt
	global_load_dword v69, v[22:23], off nt
	global_load_dword v70, v[24:25], off offset:-4096 nt
	global_load_dword v71, v[24:25], off nt
	v_add_co_u32_e32 v18, vcc, s92, v16
	s_nop 1
	v_addc_co_u32_e32 v19, vcc, 0, v17, vcc
	v_add_co_u32_e32 v20, vcc, s65, v16
	s_nop 1
	v_addc_co_u32_e32 v21, vcc, 0, v17, vcc
	v_add_co_u32_e32 v22, vcc, s66, v16
	s_nop 1
	v_addc_co_u32_e32 v23, vcc, 0, v17, vcc
	v_add_co_u32_e32 v24, vcc, s67, v16
	s_nop 1
	v_addc_co_u32_e32 v25, vcc, 0, v17, vcc
	global_load_dword v72, v[18:19], off offset:-4096 nt
	global_load_dword v73, v[18:19], off nt
	global_load_dword v74, v[20:21], off offset:-4096 nt
	global_load_dword v75, v[20:21], off nt
	global_load_dword v76, v[22:23], off offset:-4096 nt
	global_load_dword v77, v[22:23], off nt
	global_load_dword v78, v[24:25], off offset:-4096 nt
	global_load_dword v79, v[24:25], off nt
	v_add_co_u32_e32 v18, vcc, s69, v16
	s_nop 1
	v_addc_co_u32_e32 v19, vcc, 0, v17, vcc
	v_add_co_u32_e32 v20, vcc, s71, v16
	s_nop 1
	v_addc_co_u32_e32 v21, vcc, 0, v17, vcc
	v_add_co_u32_e32 v22, vcc, s81, v16
	s_nop 1
	v_addc_co_u32_e32 v23, vcc, 0, v17, vcc
	v_add_co_u32_e32 v24, vcc, s82, v16
	s_nop 1
	v_addc_co_u32_e32 v25, vcc, 0, v17, vcc
	global_load_dword v111, v[18:19], off offset:-4096 nt
	s_nop 0
	global_load_dword v18, v[18:19], off nt
	s_nop 0
	global_load_dword v19, v[20:21], off offset:-4096 nt
	s_nop 0
	global_load_dword v20, v[20:21], off nt
	s_nop 0
	global_load_dword v21, v[22:23], off offset:-4096 nt
	s_nop 0
	global_load_dword v22, v[22:23], off nt
	s_nop 0
	global_load_dword v23, v[24:25], off offset:-4096 nt
	s_nop 0
	global_load_dword v24, v[24:25], off nt
	v_add_co_u32_e32 v16, vcc, s84, v16
	s_nop 1
	v_addc_co_u32_e32 v17, vcc, 0, v17, vcc
	global_load_dword v16, v[16:17], off nt
	s_waitcnt vmcnt(62)
; #define LAS __attribute__((address_space(3)))
; __device__ __forceinline__ unsigned pk2(float lo, float hi) { return pg8::cvt_pk_bf16(lo, hi); }
; template <int MODE>
; __device__ __forceinline__ void p0_item(const float* W, int K, int N, bf16u* WT, const float* ks, LAS float* scr, int item, int lane) {
;     ...
; #pragma unroll
;     for (int kk = 0; kk < 64; ++kk) scr[kk * 65 + lane] = v[kk];
;     asm volatile("s_waitcnt lgkmcnt(0)" ::: "memory");
;     const int c = lane & 7;
; #pragma unroll
;     for (int j = 0; j < 8; ++j) { const int n = (lane >> 3) + 8 * j; const LAS float* s = scr + (8 * c) * 65 + n;
;         v4u o; o.x = pk2(s[0 * 65], s[1 * 65]); o.y = pk2(s[2 * 65], s[3 * 65]); o.z = pk2(s[4 * 65], s[5 * 65]); o.w = pk2(s[6 * 65], s[7 * 65]);
;         *(v4u*)(WT + (size_t)(drow + n) * K + k0 + 8 * c) = o; }
;     asm volatile("s_waitcnt lgkmcnt(0)" ::: "memory");
	ds_write2_b32 v80, v2, v26 offset1:65
	s_waitcnt vmcnt(60)
	ds_write2_b32 v80, v27, v28 offset0:130 offset1:195
	s_waitcnt vmcnt(58)
	ds_write2_b32 v95, v29, v30 offset0:4 offset1:69
	s_waitcnt vmcnt(56)
	ds_write2_b32 v95, v31, v32 offset0:134 offset1:199
	s_waitcnt vmcnt(54)
	ds_write2_b32 v96, v33, v34 offset0:8 offset1:73
	s_waitcnt vmcnt(52)
	ds_write2_b32 v96, v35, v36 offset0:138 offset1:203
	s_waitcnt vmcnt(50)
	ds_write2_b32 v97, v37, v38 offset0:12 offset1:77
	s_waitcnt vmcnt(48)
	ds_write2_b32 v97, v39, v40 offset0:142 offset1:207
	s_waitcnt vmcnt(46)
	ds_write2_b32 v98, v41, v42 offset0:16 offset1:81
	s_waitcnt vmcnt(44)
	ds_write2_b32 v98, v43, v44 offset0:146 offset1:211
	s_waitcnt vmcnt(42)
	ds_write2_b32 v99, v45, v46 offset0:20 offset1:85
	s_waitcnt vmcnt(40)
	ds_write2_b32 v99, v47, v48 offset0:150 offset1:215
	s_waitcnt vmcnt(38)
	ds_write2_b32 v100, v49, v50 offset0:24 offset1:89
	s_waitcnt vmcnt(36)
	ds_write2_b32 v100, v51, v52 offset0:154 offset1:219
	s_waitcnt vmcnt(34)
	ds_write2_b32 v101, v53, v54 offset0:28 offset1:93
	s_waitcnt vmcnt(32)
	ds_write2_b32 v101, v55, v56 offset0:158 offset1:223
	s_waitcnt vmcnt(30)
	ds_write2_b32 v102, v57, v58 offset0:32 offset1:97
	s_waitcnt vmcnt(28)
	ds_write2_b32 v102, v59, v60 offset0:162 offset1:227
	s_waitcnt vmcnt(26)
	ds_write2_b32 v103, v61, v62 offset0:36 offset1:101
	s_waitcnt vmcnt(24)
	ds_write2_b32 v103, v63, v64 offset0:166 offset1:231
	s_waitcnt vmcnt(22)
	ds_write2_b32 v104, v65, v66 offset0:40 offset1:105
	s_waitcnt vmcnt(20)
	ds_write2_b32 v104, v67, v68 offset0:170 offset1:235
	s_waitcnt vmcnt(18)
	ds_write2_b32 v105, v69, v70 offset0:44 offset1:109
	s_waitcnt vmcnt(16)
	ds_write2_b32 v105, v71, v72 offset0:174 offset1:239
	s_waitcnt vmcnt(14)
	ds_write2_b32 v106, v73, v74 offset0:48 offset1:113
	s_waitcnt vmcnt(12)
	ds_write2_b32 v106, v75, v76 offset0:178 offset1:243
	s_waitcnt vmcnt(10)
	ds_write2_b32 v107, v77, v78 offset0:52 offset1:117
	s_waitcnt vmcnt(8)
	ds_write2_b32 v107, v79, v111 offset0:182 offset1:247
	s_waitcnt vmcnt(6)
	ds_write2_b32 v108, v18, v19 offset0:56 offset1:121
	s_waitcnt vmcnt(4)
	ds_write2_b32 v108, v20, v21 offset0:186 offset1:251
	s_waitcnt vmcnt(2)
	ds_write2_b32 v109, v22, v23 offset0:60 offset1:125
	s_waitcnt vmcnt(0)
	ds_write2_b32 v109, v24, v16 offset0:190 offset1:255
	s_waitcnt lgkmcnt(0)
	ds_read2_b32 v[20:21], v82 offset0:65 offset1:73
	ds_read2_b32 v[22:23], v82 offset1:8
	ds_read2_b32 v[24:25], v82 offset0:130 offset1:138
	ds_read2_b32 v[26:27], v82 offset0:195 offset1:203
	ds_read2_b32 v[28:29], v110 offset0:4 offset1:12
	ds_read2_b32 v[30:31], v110 offset0:69 offset1:77
	ds_read2_b32 v[32:33], v110 offset0:134 offset1:142
	ds_read2_b32 v[34:35], v110 offset0:199 offset1:207
	v_or_b32_e32 v2, s12, v81
	v_lshl_add_u64 v[36:37], v[12:13], 0, s[10:11]
	v_lshlrev_b32_e32 v2, 11, v2
	s_waitcnt lgkmcnt(6)
	v_cvt_pk_bf16_f32 v16, v22, v20
	s_waitcnt lgkmcnt(4)
	v_cvt_pk_bf16_f32 v17, v24, v26
	s_waitcnt lgkmcnt(2)
	v_cvt_pk_bf16_f32 v18, v28, v30
	s_waitcnt lgkmcnt(0)
	v_cvt_pk_bf16_f32 v19, v32, v34
	v_lshl_add_u64 v[38:39], v[36:37], 0, v[2:3]
	global_store_dwordx4 v[38:39], v[16:19], off
	v_or_b32_e32 v2, s12, v83
	v_lshlrev_b32_e32 v2, 11, v2
	v_cvt_pk_bf16_f32 v16, v23, v21
	v_cvt_pk_bf16_f32 v17, v25, v27
	v_cvt_pk_bf16_f32 v18, v29, v31
	v_cvt_pk_bf16_f32 v19, v33, v35
	ds_read2_b32 v[22:23], v82 offset0:81 offset1:89
	ds_read2_b32 v[24:25], v82 offset0:16 offset1:24
	ds_read2_b32 v[26:27], v82 offset0:146 offset1:154
	ds_read2_b32 v[28:29], v82 offset0:211 offset1:219
	ds_read2_b32 v[30:31], v110 offset0:20 offset1:28
	ds_read2_b32 v[32:33], v110 offset0:85 offset1:93
	ds_read2_b32 v[34:35], v110 offset0:150 offset1:158
	ds_read2_b32 v[38:39], v110 offset0:215 offset1:223
	v_lshl_add_u64 v[20:21], v[36:37], 0, v[2:3]
	v_or_b32_e32 v2, s12, v84
	v_lshlrev_b32_e32 v2, 11, v2
	global_store_dwordx4 v[20:21], v[16:19], off
	v_lshl_add_u64 v[20:21], v[36:37], 0, v[2:3]
	v_or_b32_e32 v2, s12, v85
	s_waitcnt lgkmcnt(6)
	v_cvt_pk_bf16_f32 v16, v24, v22
	s_waitcnt lgkmcnt(4)
	v_cvt_pk_bf16_f32 v17, v26, v28
	s_waitcnt lgkmcnt(2)
	v_cvt_pk_bf16_f32 v18, v30, v32
	s_waitcnt lgkmcnt(0)
	v_cvt_pk_bf16_f32 v19, v34, v38
	global_store_dwordx4 v[20:21], v[16:19], off
	v_lshlrev_b32_e32 v2, 11, v2
	v_lshl_add_u64 v[20:21], v[36:37], 0, v[2:3]
	v_cvt_pk_bf16_f32 v16, v25, v23
	v_cvt_pk_bf16_f32 v17, v27, v29
	v_cvt_pk_bf16_f32 v18, v31, v33
	v_cvt_pk_bf16_f32 v19, v35, v39
	ds_read2_b32 v[22:23], v82 offset0:32 offset1:40
	ds_read2_b32 v[24:25], v82 offset0:97 offset1:105
	ds_read2_b32 v[26:27], v82 offset0:162 offset1:170
	ds_read2_b32 v[28:29], v82 offset0:227 offset1:235
	ds_read2_b32 v[30:31], v110 offset0:36 offset1:44
	ds_read2_b32 v[32:33], v110 offset0:101 offset1:109
	ds_read2_b32 v[34:35], v110 offset0:166 offset1:174
	ds_read2_b32 v[38:39], v110 offset0:231 offset1:239
	v_or_b32_e32 v2, s12, v86
	v_lshlrev_b32_e32 v2, 11, v2
	global_store_dwordx4 v[20:21], v[16:19], off
	v_lshl_add_u64 v[20:21], v[36:37], 0, v[2:3]
	v_or_b32_e32 v2, s12, v87
	s_waitcnt lgkmcnt(6)
	v_cvt_pk_bf16_f32 v16, v22, v24
	s_waitcnt lgkmcnt(4)
	v_cvt_pk_bf16_f32 v17, v26, v28
	s_waitcnt lgkmcnt(2)
	v_cvt_pk_bf16_f32 v18, v30, v32
	s_waitcnt lgkmcnt(0)
	v_cvt_pk_bf16_f32 v19, v34, v38
	global_store_dwordx4 v[20:21], v[16:19], off
	v_lshlrev_b32_e32 v2, 11, v2
	v_lshl_add_u64 v[20:21], v[36:37], 0, v[2:3]
	v_cvt_pk_bf16_f32 v16, v23, v25
	v_cvt_pk_bf16_f32 v17, v27, v29
	v_cvt_pk_bf16_f32 v18, v31, v33
	v_cvt_pk_bf16_f32 v19, v35, v39
	ds_read2_b32 v[22:23], v82 offset0:48 offset1:56
	ds_read2_b32 v[24:25], v82 offset0:113 offset1:121
	ds_read2_b32 v[26:27], v82 offset0:178 offset1:186
	ds_read2_b32 v[28:29], v82 offset0:243 offset1:251
	ds_read2_b32 v[30:31], v110 offset0:52 offset1:60
	ds_read2_b32 v[32:33], v110 offset0:117 offset1:125
	ds_read2_b32 v[34:35], v110 offset0:182 offset1:190
	ds_read2_b32 v[38:39], v110 offset0:247 offset1:255
	v_or_b32_e32 v2, s12, v88
	v_lshlrev_b32_e32 v2, 11, v2
	global_store_dwordx4 v[20:21], v[16:19], off
	v_lshl_add_u64 v[20:21], v[36:37], 0, v[2:3]
	v_or_b32_e32 v2, s12, v89
	s_waitcnt lgkmcnt(6)
	v_cvt_pk_bf16_f32 v16, v22, v24
	s_waitcnt lgkmcnt(4)
	v_cvt_pk_bf16_f32 v17, v26, v28
	s_waitcnt lgkmcnt(2)
	v_cvt_pk_bf16_f32 v18, v30, v32
	s_waitcnt lgkmcnt(0)
	v_cvt_pk_bf16_f32 v19, v34, v38
	v_lshlrev_b32_e32 v2, 11, v2
	global_store_dwordx4 v[20:21], v[16:19], off
	v_lshl_add_u64 v[20:21], v[36:37], 0, v[2:3]
	s_nop 0
	v_cvt_pk_bf16_f32 v16, v23, v25
	v_cvt_pk_bf16_f32 v17, v27, v29
	v_cvt_pk_bf16_f32 v18, v31, v33
	v_cvt_pk_bf16_f32 v19, v35, v39
	global_store_dwordx4 v[20:21], v[16:19], off
	s_waitcnt lgkmcnt(0)

; template <int MODE>
; __device__ __forceinline__ void p0_item(const float* W, int K, int N, bf16u* WT, const float* ks, LAS float* scr, int item, int lane) {
;     const int nblk = N / 64, kb = item / nblk, nb = item - kb * nblk, k0 = 64 * kb, n0 = 64 * nb;
;     int nn = n0 + lane;
;     if (MODE == 1) {
;         if (nn < 2048) { const int p = nn & 63; if (p < 16) nn = (nn & ~15) | (p & 3) | ((p & 4) << 1) | ((p & 8) >> 1); }
;         else if (nn >= 4096) { const int sec = nn >= 6144 ? 6144 : 4096, r = nn - sec, q = r & 255; nn = sec + ((q >> 7) << 10) + 128 * (r >> 8) + (q & 127); }
;     }
;     int drow = n0;
;     if (MODE == 2) drow = 256 * (n0 >> 7) + (n0 & 127);
;     if (MODE == 3) drow = 256 * (n0 >> 7) + 128 + (n0 & 127);
;     const float* src = W + (size_t)k0 * N + nn;
;     float v[64];
; #pragma unroll
;     for (int kk = 0; kk < 64; ++kk) v[kk] = src[(size_t)kk * N];
.LBB0_40:
	s_andn2_saveexec_b64 s[12:13], s[12:13]
	s_add_i32 s15, s10, s80
	v_add_u32_e32 v2, s15, v93
	v_cndmask_b32_e64 v16, v16, v2, s[4:5]
	s_or_b64 exec, exec, s[12:13]
	s_lshl_b32 s12, s14, 6
	s_ashr_i32 s13, s12, 31
	v_readlane_b32 s48, v253, 2
	s_lshl_b64 s[14:15], s[12:13], 15
	v_readlane_b32 s54, v253, 8
	v_readlane_b32 s55, v253, 9
	s_add_u32 s14, s54, s14
	s_addc_u32 s15, s55, s15
	v_ashrrev_i32_e32 v17, 31, v16
	v_lshl_add_u64 v[72:73], v[16:17], 2, s[14:15]
	v_add_co_u32_e32 v18, vcc, s36, v72
	s_mov_b32 s14, 0x40000
	s_nop 0
	v_addc_co_u32_e32 v19, vcc, 0, v73, vcc
	v_add_co_u32_e32 v20, vcc, s42, v72
	v_readlane_b32 s52, v253, 6
	s_nop 0
	v_addc_co_u32_e32 v21, vcc, 0, v73, vcc
	v_add_co_u32_e32 v22, vcc, s47, v72
	v_readlane_b32 s53, v253, 7
	s_nop 0
	v_addc_co_u32_e32 v23, vcc, 0, v73, vcc
	v_add_co_u32_e32 v24, vcc, s40, v72
	v_readlane_b32 s49, v253, 3
	s_nop 0
	v_addc_co_u32_e32 v25, vcc, 0, v73, vcc
	v_add_co_u32_e32 v26, vcc, s70, v72
	v_readlane_b32 s50, v253, 4
	s_nop 0
	v_addc_co_u32_e32 v27, vcc, 0, v73, vcc
	v_add_co_u32_e32 v28, vcc, s92, v72
	v_readlane_b32 s51, v253, 5
	s_nop 0
	v_addc_co_u32_e32 v29, vcc, 0, v73, vcc
	v_add_co_u32_e32 v30, vcc, s69, v72
	v_readlane_b32 s56, v253, 10
	s_nop 0
	v_addc_co_u32_e32 v31, vcc, 0, v73, vcc
	global_load_dword v16, v[72:73], off nt
	global_load_dword v17, v[18:19], off nt
	s_nop 0
	global_load_dword v18, v[20:21], off nt
	global_load_dword v19, v[22:23], off nt
	s_nop 0
	global_load_dword v20, v[24:25], off nt
	global_load_dword v21, v[26:27], off nt
	global_load_dword v22, v[28:29], off nt
	global_load_dword v23, v[30:31], off nt
	v_add_co_u32_e32 v24, vcc, s14, v72
	s_mov_b32 s14, 0x48000
	s_nop 0
	v_addc_co_u32_e32 v25, vcc, 0, v73, vcc
	v_add_co_u32_e32 v26, vcc, s14, v72
	s_mov_b32 s14, 0x50000
	s_nop 0
	v_addc_co_u32_e32 v27, vcc, 0, v73, vcc
	v_add_co_u32_e32 v28, vcc, s14, v72
	s_mov_b32 s14, 0x78000
	s_nop 0
	v_addc_co_u32_e32 v29, vcc, 0, v73, vcc
	v_add_co_u32_e32 v30, vcc, s83, v72
	v_readlane_b32 s57, v253, 11
	s_nop 0
	v_addc_co_u32_e32 v31, vcc, 0, v73, vcc
	v_add_co_u32_e32 v32, vcc, s86, v72
	v_readlane_b32 s58, v253, 12
	s_nop 0
	v_addc_co_u32_e32 v33, vcc, 0, v73, vcc
	v_add_co_u32_e32 v34, vcc, s91, v72
	v_readlane_b32 s59, v253, 13
	s_nop 0
	v_addc_co_u32_e32 v35, vcc, 0, v73, vcc
	v_add_co_u32_e32 v36, vcc, s94, v72
	v_readlane_b32 s60, v253, 14
	s_nop 0
	v_addc_co_u32_e32 v37, vcc, 0, v73, vcc
	v_add_co_u32_e32 v38, vcc, s14, v72
	s_mov_b32 s14, 0x80000
	s_nop 0
	v_addc_co_u32_e32 v39, vcc, 0, v73, vcc
	global_load_dword v24, v[24:25], off nt
	s_nop 0
	global_load_dword v25, v[26:27], off nt
	s_nop 0
	global_load_dword v26, v[28:29], off nt
	global_load_dword v27, v[30:31], off nt
	s_nop 0
	global_load_dword v28, v[32:33], off nt
	global_load_dword v29, v[34:35], off nt
	global_load_dword v30, v[36:37], off nt
	global_load_dword v31, v[38:39], off nt
	v_add_co_u32_e32 v32, vcc, s14, v72
	s_mov_b32 s14, 0x88000
	s_nop 0
	v_addc_co_u32_e32 v33, vcc, 0, v73, vcc
	v_add_co_u32_e32 v34, vcc, s14, v72
	s_mov_b32 s14, 0x90000
	s_nop 0
	v_addc_co_u32_e32 v35, vcc, 0, v73, vcc
	v_add_co_u32_e32 v36, vcc, s14, v72
	s_mov_b32 s14, 0x98000
	s_nop 0
	v_addc_co_u32_e32 v37, vcc, 0, v73, vcc
	v_add_co_u32_e32 v38, vcc, s14, v72
	s_mov_b32 s14, 0xa0000
	s_nop 0
	v_addc_co_u32_e32 v39, vcc, 0, v73, vcc
	v_add_co_u32_e32 v40, vcc, s14, v72
	s_mov_b32 s14, 0xa8000
	s_nop 0
	v_addc_co_u32_e32 v41, vcc, 0, v73, vcc
	v_add_co_u32_e32 v42, vcc, s14, v72
	s_mov_b32 s14, 0xb0000
	s_nop 0
	v_addc_co_u32_e32 v43, vcc, 0, v73, vcc
	v_add_co_u32_e32 v44, vcc, s14, v72
	s_mov_b32 s14, 0xb8000
	s_nop 0
	v_addc_co_u32_e32 v45, vcc, 0, v73, vcc
	v_add_co_u32_e32 v46, vcc, s14, v72
	s_mov_b32 s14, 0xc0000
	s_nop 0
	v_addc_co_u32_e32 v47, vcc, 0, v73, vcc
	global_load_dword v32, v[32:33], off nt
	s_nop 0
	global_load_dword v33, v[34:35], off nt
	s_nop 0
	global_load_dword v34, v[36:37], off nt
	global_load_dword v35, v[38:39], off nt
	s_nop 0
	global_load_dword v36, v[40:41], off nt
	global_load_dword v37, v[42:43], off nt
	global_load_dword v38, v[44:45], off nt
	global_load_dword v39, v[46:47], off nt
	v_add_co_u32_e32 v40, vcc, s14, v72
	s_mov_b32 s14, 0xc8000
	s_nop 0
	v_addc_co_u32_e32 v41, vcc, 0, v73, vcc
	v_add_co_u32_e32 v42, vcc, s14, v72
	s_mov_b32 s14, 0xd0000
	s_nop 0
	v_addc_co_u32_e32 v43, vcc, 0, v73, vcc
	v_add_co_u32_e32 v44, vcc, s14, v72
	s_mov_b32 s14, 0xd8000
	s_nop 0
	v_addc_co_u32_e32 v45, vcc, 0, v73, vcc
	v_add_co_u32_e32 v46, vcc, s14, v72
	s_mov_b32 s14, 0xe0000
	s_nop 0
	v_addc_co_u32_e32 v47, vcc, 0, v73, vcc
	v_add_co_u32_e32 v48, vcc, s14, v72
	s_mov_b32 s14, 0xe8000
	s_nop 0
	v_addc_co_u32_e32 v49, vcc, 0, v73, vcc
	v_add_co_u32_e32 v50, vcc, s14, v72
	s_mov_b32 s14, 0xf0000
	s_nop 0
	v_addc_co_u32_e32 v51, vcc, 0, v73, vcc
	v_add_co_u32_e32 v52, vcc, s14, v72
	s_mov_b32 s14, 0xf8000
	s_nop 0
	v_addc_co_u32_e32 v53, vcc, 0, v73, vcc
	v_add_co_u32_e32 v54, vcc, s14, v72
	s_mov_b32 s14, 0x100000
	s_nop 0
	v_addc_co_u32_e32 v55, vcc, 0, v73, vcc
	global_load_dword v40, v[40:41], off nt
	s_nop 0
	global_load_dword v41, v[42:43], off nt
	s_nop 0
	global_load_dword v42, v[44:45], off nt
	global_load_dword v43, v[46:47], off nt
	s_nop 0
	global_load_dword v44, v[48:49], off nt
	global_load_dword v45, v[50:51], off nt
	global_load_dword v46, v[52:53], off nt
	global_load_dword v47, v[54:55], off nt
	v_add_co_u32_e32 v48, vcc, s14, v72
	s_mov_b32 s14, 0x108000
	s_nop 0
	v_addc_co_u32_e32 v49, vcc, 0, v73, vcc
	v_add_co_u32_e32 v50, vcc, s14, v72
	s_mov_b32 s14, 0x110000
	s_nop 0
	v_addc_co_u32_e32 v51, vcc, 0, v73, vcc
	v_add_co_u32_e32 v52, vcc, s14, v72
; template <int MODE>
; __device__ __forceinline__ void p0_item(const float* W, int K, int N, bf16u* WT, const float* ks, LAS float* scr, int item, int lane) {
;     ...
;     const float* src = W + (size_t)k0 * N + nn;
;     float v[64];
; #pragma unroll
;     for (int kk = 0; kk < 64; ++kk) v[kk] = src[(size_t)kk * N];
	s_mov_b32 s14, 0x118000
	s_nop 0
	v_addc_co_u32_e32 v53, vcc, 0, v73, vcc
	v_add_co_u32_e32 v54, vcc, s14, v72
	s_mov_b32 s14, 0x120000
	s_nop 0
	v_addc_co_u32_e32 v55, vcc, 0, v73, vcc
	v_add_co_u32_e32 v56, vcc, s14, v72
	s_mov_b32 s14, 0x128000
	s_nop 0
	v_addc_co_u32_e32 v57, vcc, 0, v73, vcc
	v_add_co_u32_e32 v58, vcc, s14, v72
	s_mov_b32 s14, 0x130000
	s_nop 0
	v_addc_co_u32_e32 v59, vcc, 0, v73, vcc
	v_add_co_u32_e32 v60, vcc, s14, v72
	s_mov_b32 s14, 0x138000
	s_nop 0
	v_addc_co_u32_e32 v61, vcc, 0, v73, vcc
	v_add_co_u32_e32 v62, vcc, s14, v72
	s_mov_b32 s14, 0x140000
	s_nop 0
	v_addc_co_u32_e32 v63, vcc, 0, v73, vcc
	global_load_dword v48, v[48:49], off nt
	s_nop 0
	global_load_dword v49, v[50:51], off nt
	s_nop 0
	global_load_dword v50, v[52:53], off nt
	global_load_dword v51, v[54:55], off nt
	s_nop 0
	global_load_dword v52, v[56:57], off nt
	global_load_dword v53, v[58:59], off nt
	global_load_dword v54, v[60:61], off nt
	global_load_dword v55, v[62:63], off nt
	v_add_co_u32_e32 v56, vcc, s14, v72
	s_mov_b32 s14, 0x148000
	s_nop 0
	v_addc_co_u32_e32 v57, vcc, 0, v73, vcc
	v_add_co_u32_e32 v58, vcc, s14, v72
	s_mov_b32 s14, 0x150000
	s_nop 0
	v_addc_co_u32_e32 v59, vcc, 0, v73, vcc
	v_add_co_u32_e32 v60, vcc, s14, v72
	s_mov_b32 s14, 0x158000
	s_nop 0
	v_addc_co_u32_e32 v61, vcc, 0, v73, vcc
	v_add_co_u32_e32 v62, vcc, s14, v72
	s_mov_b32 s14, 0x160000
	s_nop 0
	v_addc_co_u32_e32 v63, vcc, 0, v73, vcc
	v_add_co_u32_e32 v64, vcc, s14, v72
	s_mov_b32 s14, 0x168000
	s_nop 0
	v_addc_co_u32_e32 v65, vcc, 0, v73, vcc
	v_add_co_u32_e32 v66, vcc, s14, v72
	s_mov_b32 s14, 0x170000
	s_nop 0
	v_addc_co_u32_e32 v67, vcc, 0, v73, vcc
	v_add_co_u32_e32 v68, vcc, s14, v72
	s_mov_b32 s14, 0x178000
	s_nop 0
	v_addc_co_u32_e32 v69, vcc, 0, v73, vcc
	v_add_co_u32_e32 v70, vcc, s14, v72
	s_mov_b32 s14, 0x180000
	s_nop 0
	v_addc_co_u32_e32 v71, vcc, 0, v73, vcc
	global_load_dword v56, v[56:57], off nt
	s_nop 0
	global_load_dword v57, v[58:59], off nt
	s_nop 0
	global_load_dword v58, v[60:61], off nt
	global_load_dword v59, v[62:63], off nt
	s_nop 0
	global_load_dword v60, v[64:65], off nt
	global_load_dword v61, v[66:67], off nt
	global_load_dword v62, v[68:69], off nt
	global_load_dword v63, v[70:71], off nt
	v_add_co_u32_e32 v64, vcc, s14, v72
	s_mov_b32 s14, 0x188000
	s_nop 0
	v_addc_co_u32_e32 v65, vcc, 0, v73, vcc
	v_add_co_u32_e32 v66, vcc, s14, v72
	s_mov_b32 s14, 0x190000
	s_nop 0
	v_addc_co_u32_e32 v67, vcc, 0, v73, vcc
	v_add_co_u32_e32 v68, vcc, s14, v72
	s_mov_b32 s14, 0x198000
	s_nop 0
	v_addc_co_u32_e32 v69, vcc, 0, v73, vcc
	v_add_co_u32_e32 v70, vcc, s14, v72
	s_mov_b32 s14, 0x1a0000
	s_nop 0
	v_addc_co_u32_e32 v71, vcc, 0, v73, vcc
	v_add_co_u32_e32 v74, vcc, s14, v72
	s_mov_b32 s14, 0x1a8000
	s_nop 0
	v_addc_co_u32_e32 v75, vcc, 0, v73, vcc
	v_add_co_u32_e32 v76, vcc, s14, v72
	s_mov_b32 s14, 0x1b0000
	s_nop 0
	v_addc_co_u32_e32 v77, vcc, 0, v73, vcc
	v_add_co_u32_e32 v78, vcc, s14, v72
	s_mov_b32 s14, 0x1b8000
	s_nop 0
	v_addc_co_u32_e32 v79, vcc, 0, v73, vcc
	v_add_co_u32_e32 v112, vcc, s14, v72
	s_mov_b32 s14, 0x1c0000
	s_nop 0
	v_addc_co_u32_e32 v113, vcc, 0, v73, vcc
	global_load_dword v64, v[64:65], off nt
	s_nop 0
	global_load_dword v65, v[66:67], off nt
	s_nop 0
	global_load_dword v66, v[68:69], off nt
	global_load_dword v67, v[70:71], off nt
	s_nop 0
	global_load_dword v68, v[74:75], off nt
	global_load_dword v69, v[76:77], off nt
	global_load_dword v70, v[78:79], off nt
	global_load_dword v71, v[112:113], off nt
	v_add_co_u32_e32 v74, vcc, s14, v72
	s_mov_b32 s14, 0x1c8000
	s_nop 0
	v_addc_co_u32_e32 v75, vcc, 0, v73, vcc
	v_add_co_u32_e32 v76, vcc, s14, v72
	s_mov_b32 s14, 0x1d0000
	s_nop 0
	v_addc_co_u32_e32 v77, vcc, 0, v73, vcc
	v_add_co_u32_e32 v78, vcc, s14, v72
	s_mov_b32 s14, 0x1d8000
	s_nop 0
	v_addc_co_u32_e32 v79, vcc, 0, v73, vcc
	v_add_co_u32_e32 v112, vcc, s14, v72
	s_mov_b32 s14, 0x1e0000
	s_nop 0
	v_addc_co_u32_e32 v113, vcc, 0, v73, vcc
	v_add_co_u32_e32 v114, vcc, s14, v72
	v_readlane_b32 s61, v253, 15
	s_nop 0
	v_addc_co_u32_e32 v115, vcc, 0, v73, vcc
	v_add_co_u32_e32 v116, vcc, 0x1e8000, v72
	v_readlane_b32 s62, v253, 16
	s_nop 0
	v_addc_co_u32_e32 v117, vcc, 0, v73, vcc
	v_add_co_u32_e32 v118, vcc, 0x1f0000, v72
	v_readlane_b32 s63, v253, 17
	s_nop 0
	v_addc_co_u32_e32 v119, vcc, 0, v73, vcc
	v_add_co_u32_e32 v120, vcc, 0x1f8000, v72
	s_nop 1
	v_addc_co_u32_e32 v121, vcc, 0, v73, vcc
	global_load_dword v72, v[74:75], off nt
	global_load_dword v73, v[76:77], off nt
	s_nop 0
	global_load_dword v74, v[78:79], off nt
	global_load_dword v75, v[112:113], off nt
	global_load_dword v76, v[114:115], off nt
	global_load_dword v77, v[116:117], off nt
	s_nop 0
	global_load_dword v78, v[118:119], off nt
	global_load_dword v79, v[120:121], off nt
	s_andn2_b64 vcc, exec, s[8:9]
	s_cbranch_vccnz .LBB0_8
; template <int MODE>
; __device__ __forceinline__ void p0_item(const float* W, int K, int N, bf16u* WT, const float* ks, LAS float* scr, int item, int lane) {
;     ...
;     if (ks) {
; #pragma unroll
;         for (int kk = 0; kk < 64; ++kk) v[kk] *= ks[k0 + kk];
;     }
	s_lshl_b64 s[14:15], s[12:13], 2
	s_add_u32 s14, s52, s14
	s_addc_u32 s15, s53, s15
	global_load_dwordx4 v[112:115], v3, s[14:15] offset:48 nt
	global_load_dwordx4 v[116:119], v3, s[14:15] offset:32 nt
	global_load_dwordx4 v[120:123], v3, s[14:15] offset:16 nt
	global_load_dwordx4 v[124:127], v3, s[14:15] nt
	s_waitcnt vmcnt(3)
	v_pk_mul_f32 v[28:29], v[28:29], v[112:113]
	s_waitcnt vmcnt(2)
	v_pk_mul_f32 v[24:25], v[24:25], v[116:117]
	s_waitcnt vmcnt(1)
	v_pk_mul_f32 v[20:21], v[20:21], v[120:121]
	s_waitcnt vmcnt(0)
	v_pk_mul_f32 v[16:17], v[16:17], v[124:125]
	v_pk_mul_f32 v[18:19], v[18:19], v[126:127]
	v_pk_mul_f32 v[22:23], v[22:23], v[122:123]
	v_pk_mul_f32 v[26:27], v[26:27], v[118:119]
	v_pk_mul_f32 v[30:31], v[30:31], v[114:115]
	global_load_dwordx4 v[112:115], v3, s[14:15] offset:112 nt
	global_load_dwordx4 v[116:119], v3, s[14:15] offset:96 nt
	global_load_dwordx4 v[120:123], v3, s[14:15] offset:80 nt
	global_load_dwordx4 v[124:127], v3, s[14:15] offset:64 nt
	s_waitcnt vmcnt(3)
	v_pk_mul_f32 v[44:45], v[44:45], v[112:113]
	s_waitcnt vmcnt(2)
	v_pk_mul_f32 v[40:41], v[40:41], v[116:117]
	s_waitcnt vmcnt(1)
	v_pk_mul_f32 v[36:37], v[36:37], v[120:121]
	s_waitcnt vmcnt(0)
	v_pk_mul_f32 v[32:33], v[32:33], v[124:125]
	v_pk_mul_f32 v[34:35], v[34:35], v[126:127]
	v_pk_mul_f32 v[38:39], v[38:39], v[122:123]
	v_pk_mul_f32 v[42:43], v[42:43], v[118:119]
	v_pk_mul_f32 v[46:47], v[46:47], v[114:115]
	global_load_dwordx4 v[112:115], v3, s[14:15] offset:176 nt
	global_load_dwordx4 v[116:119], v3, s[14:15] offset:160 nt
	global_load_dwordx4 v[120:123], v3, s[14:15] offset:144 nt
	global_load_dwordx4 v[124:127], v3, s[14:15] offset:128 nt
	s_waitcnt vmcnt(3)
	v_pk_mul_f32 v[60:61], v[60:61], v[112:113]
	s_waitcnt vmcnt(2)
	v_pk_mul_f32 v[56:57], v[56:57], v[116:117]
	s_waitcnt vmcnt(1)
	v_pk_mul_f32 v[52:53], v[52:53], v[120:121]
	s_waitcnt vmcnt(0)
	v_pk_mul_f32 v[48:49], v[48:49], v[124:125]
	v_pk_mul_f32 v[50:51], v[50:51], v[126:127]
	v_pk_mul_f32 v[54:55], v[54:55], v[122:123]
	v_pk_mul_f32 v[58:59], v[58:59], v[118:119]
	v_pk_mul_f32 v[62:63], v[62:63], v[114:115]
	global_load_dwordx4 v[112:115], v3, s[14:15] offset:240 nt
	global_load_dwordx4 v[116:119], v3, s[14:15] offset:224 nt
	global_load_dwordx4 v[120:123], v3, s[14:15] offset:208 nt
	global_load_dwordx4 v[124:127], v3, s[14:15] offset:192 nt
	s_waitcnt vmcnt(3)
	v_pk_mul_f32 v[76:77], v[76:77], v[112:113]
	s_waitcnt vmcnt(2)
	v_pk_mul_f32 v[72:73], v[72:73], v[116:117]
	s_waitcnt vmcnt(1)
	v_pk_mul_f32 v[68:69], v[68:69], v[120:121]
	s_waitcnt vmcnt(0)
	v_pk_mul_f32 v[64:65], v[64:65], v[124:125]
	v_pk_mul_f32 v[66:67], v[66:67], v[126:127]
	v_pk_mul_f32 v[70:71], v[70:71], v[122:123]
	v_pk_mul_f32 v[74:75], v[74:75], v[118:119]
	v_pk_mul_f32 v[78:79], v[78:79], v[114:115]
	s_branch .LBB0_8

; template <int MODE>
; __device__ __forceinline__ void p0_item(const float* W, int K, int N, bf16u* WT, const float* ks, LAS float* scr, int item, int lane) {
;     const int nblk = N / 64, kb = item / nblk, nb = item - kb * nblk, k0 = 64 * kb, n0 = 64 * nb;
;     int nn = n0 + lane;
;     if (MODE == 1) {
;         if (nn < 2048) { const int p = nn & 63; if (p < 16) nn = (nn & ~15) | (p & 3) | ((p & 4) << 1) | ((p & 8) >> 1); }
;         else if (nn >= 4096) { const int sec = nn >= 6144 ? 6144 : 4096, r = nn - sec, q = r & 255; nn = sec + ((q >> 7) << 10) + 128 * (r >> 8) + (q & 127); }
;     }
;     int drow = n0;
;     if (MODE == 2) drow = 256 * (n0 >> 7) + (n0 & 127);
;     if (MODE == 3) drow = 256 * (n0 >> 7) + 128 + (n0 & 127);
;     const float* src = W + (size_t)k0 * N + nn;
;     float v[64];
; #pragma unroll
;     for (int kk = 0; kk < 64; ++kk) v[kk] = src[(size_t)kk * N];
.LBB0_597:
	s_or_b64 exec, exec, s[16:17]
	s_lshl_b32 s16, s4, 6
	s_ashr_i32 s17, s16, 31
	s_lshl_b64 s[20:21], s[16:17], 15
	s_add_u32 s20, s3, s20
	s_addc_u32 s21, s49, s21
	v_ashrrev_i32_e32 v3, 31, v2
	v_lshl_add_u64 v[2:3], v[2:3], 2, s[20:21]
	v_add_co_u32_e32 v6, vcc, s88, v2
	s_mov_b32 s4, 0x10000
	s_nop 0
	v_addc_co_u32_e32 v7, vcc, 0, v3, vcc
	global_load_dword v4, v[2:3], off nt
	global_load_dword v5, v[6:7], off nt
	v_add_co_u32_e32 v6, vcc, s4, v2
	s_mov_b32 s4, 0x20000
	s_nop 0
	v_addc_co_u32_e32 v7, vcc, 0, v3, vcc
	v_add_co_u32_e32 v8, vcc, s5, v2
	global_load_dword v6, v[6:7], off nt
	s_nop 0
	v_addc_co_u32_e32 v9, vcc, 0, v3, vcc
	global_load_dword v7, v[8:9], off nt
	v_add_co_u32_e32 v8, vcc, s4, v2
	s_mov_b32 s4, 0x28000
	s_nop 0
	v_addc_co_u32_e32 v9, vcc, 0, v3, vcc
	v_add_co_u32_e32 v10, vcc, s4, v2
	s_mov_b32 s4, 0x30000
	s_nop 0
	v_addc_co_u32_e32 v11, vcc, 0, v3, vcc
	v_add_co_u32_e32 v12, vcc, s4, v2
	s_mov_b32 s4, 0x38000
	s_nop 0
	v_addc_co_u32_e32 v13, vcc, 0, v3, vcc
	v_add_co_u32_e32 v14, vcc, s4, v2
	s_mov_b32 s4, 0x40000
	s_nop 0
	v_addc_co_u32_e32 v15, vcc, 0, v3, vcc
	global_load_dword v8, v[8:9], off nt
	s_lshl_b64 s[20:21], s[16:17], 2
	global_load_dword v10, v[10:11], off nt
	s_add_u32 s20, s50, s20
	global_load_dword v12, v[12:13], off nt
	s_addc_u32 s21, s51, s21
	global_load_dword v61, v[14:15], off nt
	v_add_co_u32_e32 v14, vcc, s4, v2
	s_mov_b32 s4, 0x48000
	s_nop 0
	v_addc_co_u32_e32 v15, vcc, 0, v3, vcc
	global_load_dword v62, v[14:15], off nt
	v_add_co_u32_e32 v14, vcc, s4, v2
	s_mov_b32 s4, 0x58000
	s_nop 0
	v_addc_co_u32_e32 v15, vcc, 0, v3, vcc
	global_load_dword v65, v[14:15], off nt
	v_add_co_u32_e32 v14, vcc, s0, v2
	s_add_i32 s1, s1, s59
	s_nop 0
	v_addc_co_u32_e32 v15, vcc, 0, v3, vcc
	global_load_dword v67, v[14:15], off nt
	v_add_co_u32_e32 v14, vcc, s4, v2
	s_mov_b32 s4, 0x60000
	s_nop 0
	v_addc_co_u32_e32 v15, vcc, 0, v3, vcc
	global_load_dword v69, v[14:15], off nt
	v_add_co_u32_e32 v14, vcc, s4, v2
	s_mov_b32 s4, 0x68000
	s_nop 0
	v_addc_co_u32_e32 v15, vcc, 0, v3, vcc
	global_load_dword v71, v[14:15], off nt
	v_add_co_u32_e32 v14, vcc, s4, v2
	s_mov_b32 s4, 0x70000
	s_nop 0
	v_addc_co_u32_e32 v15, vcc, 0, v3, vcc
	global_load_dword v75, v[14:15], off nt
	v_add_co_u32_e32 v14, vcc, s4, v2
	s_mov_b32 s4, 0x78000
	s_nop 0
	v_addc_co_u32_e32 v15, vcc, 0, v3, vcc
	global_load_dword v82, v[14:15], off nt
	v_add_co_u32_e32 v14, vcc, s4, v2
	s_mov_b32 s4, 0x80000
	s_nop 0
	v_addc_co_u32_e32 v15, vcc, 0, v3, vcc
	global_load_dword v92, v[14:15], off nt
	v_add_co_u32_e32 v14, vcc, s4, v2
	s_mov_b32 s4, 0x88000
	s_nop 0
	v_addc_co_u32_e32 v15, vcc, 0, v3, vcc
	global_load_dword v9, v[14:15], off nt
	v_add_co_u32_e32 v14, vcc, s4, v2
	s_mov_b32 s4, 0x90000
	s_nop 0
	v_addc_co_u32_e32 v15, vcc, 0, v3, vcc
	global_load_dword v11, v[14:15], off nt
	v_add_co_u32_e32 v14, vcc, s4, v2
	s_mov_b32 s4, 0x98000
	s_nop 0
	v_addc_co_u32_e32 v15, vcc, 0, v3, vcc
	global_load_dword v13, v[14:15], off nt
	v_add_co_u32_e32 v14, vcc, s4, v2
	s_mov_b32 s4, 0xa0000
	s_nop 0
	v_addc_co_u32_e32 v15, vcc, 0, v3, vcc
	global_load_dword v58, v[14:15], off nt
	v_add_co_u32_e32 v14, vcc, s4, v2
	s_mov_b32 s4, 0xa8000
	s_nop 0
	v_addc_co_u32_e32 v15, vcc, 0, v3, vcc
	global_load_dword v59, v[14:15], off nt
	v_add_co_u32_e32 v14, vcc, s4, v2
	s_mov_b32 s4, 0xb0000
	s_nop 0
	v_addc_co_u32_e32 v15, vcc, 0, v3, vcc
	global_load_dword v60, v[14:15], off nt
	v_add_co_u32_e32 v14, vcc, s4, v2
	s_mov_b32 s4, 0xb8000
	s_nop 0
	v_addc_co_u32_e32 v15, vcc, 0, v3, vcc
	global_load_dword v63, v[14:15], off nt
	v_add_co_u32_e32 v14, vcc, s4, v2
	s_mov_b32 s4, 0xc0000
	s_nop 0
	v_addc_co_u32_e32 v15, vcc, 0, v3, vcc
	global_load_dword v72, v[14:15], off nt
	v_add_co_u32_e32 v14, vcc, s4, v2
	s_mov_b32 s4, 0xc8000
	s_nop 0
	v_addc_co_u32_e32 v15, vcc, 0, v3, vcc
	global_load_dword v73, v[14:15], off nt
	v_add_co_u32_e32 v14, vcc, s4, v2
	s_mov_b32 s4, 0xd0000
	s_nop 0
	v_addc_co_u32_e32 v15, vcc, 0, v3, vcc
	global_load_dword v76, v[14:15], off nt
	v_add_co_u32_e32 v14, vcc, s4, v2
	s_mov_b32 s4, 0xd8000
	s_nop 0
	v_addc_co_u32_e32 v15, vcc, 0, v3, vcc
	global_load_dword v87, v[14:15], off nt
	v_add_co_u32_e32 v14, vcc, s4, v2
	s_mov_b32 s4, 0xe0000
	s_nop 0
	v_addc_co_u32_e32 v15, vcc, 0, v3, vcc
	global_load_dword v89, v[14:15], off nt
	v_add_co_u32_e32 v14, vcc, s4, v2
	s_mov_b32 s4, 0xe8000
	s_nop 0
	v_addc_co_u32_e32 v15, vcc, 0, v3, vcc
	global_load_dword v90, v[14:15], off nt
	v_add_co_u32_e32 v14, vcc, s4, v2
	s_mov_b32 s4, 0xf0000
	s_nop 0
	v_addc_co_u32_e32 v15, vcc, 0, v3, vcc
	global_load_dword v91, v[14:15], off nt
	v_add_co_u32_e32 v14, vcc, s4, v2
	s_mov_b32 s4, 0xf8000
	s_nop 0
	v_addc_co_u32_e32 v15, vcc, 0, v3, vcc
	global_load_dword v93, v[14:15], off nt
	v_add_co_u32_e32 v14, vcc, s4, v2
	s_mov_b32 s4, 0x100000
	s_nop 0
	v_addc_co_u32_e32 v15, vcc, 0, v3, vcc
	global_load_dword v99, v[14:15], off nt
	v_add_co_u32_e32 v14, vcc, s4, v2
	s_mov_b32 s4, 0x108000
	s_nop 0
	v_addc_co_u32_e32 v15, vcc, 0, v3, vcc
	global_load_dword v64, v[14:15], off nt
	v_add_co_u32_e32 v14, vcc, s4, v2
	s_mov_b32 s4, 0x110000
	s_nop 0
	v_addc_co_u32_e32 v15, vcc, 0, v3, vcc
	global_load_dword v66, v[14:15], off nt
	v_add_co_u32_e32 v14, vcc, s4, v2
	s_mov_b32 s4, 0x118000
	s_nop 0
	v_addc_co_u32_e32 v15, vcc, 0, v3, vcc
	global_load_dword v68, v[14:15], off nt
	v_add_co_u32_e32 v14, vcc, s4, v2
	s_mov_b32 s4, 0x120000
	s_nop 0
	v_addc_co_u32_e32 v15, vcc, 0, v3, vcc
	global_load_dword v70, v[14:15], off nt
	v_add_co_u32_e32 v14, vcc, s4, v2
	s_mov_b32 s4, 0x128000
	s_nop 0
	v_addc_co_u32_e32 v15, vcc, 0, v3, vcc
; template <int MODE>
; __device__ __forceinline__ void p0_item(const float* W, int K, int N, bf16u* WT, const float* ks, LAS float* scr, int item, int lane) {
;     ...
;     const float* src = W + (size_t)k0 * N + nn;
;     float v[64];
; #pragma unroll
;     for (int kk = 0; kk < 64; ++kk) v[kk] = src[(size_t)kk * N];
;     if (ks) {
; #pragma unroll
;         for (int kk = 0; kk < 64; ++kk) v[kk] *= ks[k0 + kk];
;     }
	global_load_dword v74, v[14:15], off nt
	v_add_co_u32_e32 v14, vcc, s4, v2
	s_mov_b32 s4, 0x130000
	s_nop 0
	v_addc_co_u32_e32 v15, vcc, 0, v3, vcc
	global_load_dword v78, v[14:15], off nt
	v_add_co_u32_e32 v14, vcc, s4, v2
	s_mov_b32 s4, 0x138000
	s_nop 0
	v_addc_co_u32_e32 v15, vcc, 0, v3, vcc
	global_load_dword v88, v[14:15], off nt
	v_add_co_u32_e32 v14, vcc, s4, v2
	s_mov_b32 s4, 0x140000
	s_nop 0
	v_addc_co_u32_e32 v15, vcc, 0, v3, vcc
	global_load_dword v94, v[14:15], off nt
	v_add_co_u32_e32 v14, vcc, s4, v2
	s_mov_b32 s4, 0x148000
	s_nop 0
	v_addc_co_u32_e32 v15, vcc, 0, v3, vcc
	global_load_dword v95, v[14:15], off nt
	v_add_co_u32_e32 v14, vcc, s4, v2
	s_mov_b32 s4, 0x150000
	s_nop 0
	v_addc_co_u32_e32 v15, vcc, 0, v3, vcc
	global_load_dword v96, v[14:15], off nt
	v_add_co_u32_e32 v14, vcc, s4, v2
	s_mov_b32 s4, 0x158000
	s_nop 0
	v_addc_co_u32_e32 v15, vcc, 0, v3, vcc
	global_load_dword v97, v[14:15], off nt
	v_add_co_u32_e32 v14, vcc, s4, v2
	s_mov_b32 s4, 0x160000
	s_nop 0
	v_addc_co_u32_e32 v15, vcc, 0, v3, vcc
	global_load_dword v98, v[14:15], off nt
	v_add_co_u32_e32 v14, vcc, s4, v2
	s_mov_b32 s4, 0x168000
	s_nop 0
	v_addc_co_u32_e32 v15, vcc, 0, v3, vcc
	global_load_dword v100, v[14:15], off nt
	v_add_co_u32_e32 v14, vcc, s4, v2
	s_mov_b32 s4, 0x170000
	s_nop 0
	v_addc_co_u32_e32 v15, vcc, 0, v3, vcc
	global_load_dword v101, v[14:15], off nt
	v_add_co_u32_e32 v14, vcc, s4, v2
	s_mov_b32 s4, 0x178000
	s_nop 0
	v_addc_co_u32_e32 v15, vcc, 0, v3, vcc
	global_load_dword v102, v[14:15], off nt
	v_add_co_u32_e32 v14, vcc, s4, v2
	s_mov_b32 s4, 0x180000
	s_nop 0
	v_addc_co_u32_e32 v15, vcc, 0, v3, vcc
	global_load_dword v103, v[14:15], off nt
	v_add_co_u32_e32 v14, vcc, s4, v2
	s_mov_b32 s4, 0x188000
	s_nop 0
	v_addc_co_u32_e32 v15, vcc, 0, v3, vcc
	global_load_dword v0, v[14:15], off nt
	v_add_co_u32_e32 v14, vcc, s4, v2
	s_mov_b32 s4, 0x190000
	s_nop 0
	v_addc_co_u32_e32 v15, vcc, 0, v3, vcc
	v_add_co_u32_e32 v16, vcc, s4, v2
	s_mov_b32 s4, 0x198000
	s_nop 0
	v_addc_co_u32_e32 v17, vcc, 0, v3, vcc
	global_load_dword v14, v[14:15], off nt
	s_nop 0
	global_load_dword v15, v[16:17], off nt
	v_add_co_u32_e32 v16, vcc, s4, v2
	s_mov_b32 s4, 0x1a0000
	s_nop 0
	v_addc_co_u32_e32 v17, vcc, 0, v3, vcc
	v_add_co_u32_e32 v48, vcc, s4, v2
	s_mov_b32 s4, 0x1a8000
	s_nop 0
	v_addc_co_u32_e32 v49, vcc, 0, v3, vcc
	global_load_dword v16, v[16:17], off nt
	s_nop 0
	global_load_dword v17, v[48:49], off nt
	v_add_co_u32_e32 v48, vcc, s4, v2
	s_mov_b32 s4, 0x1b0000
	s_nop 0
	v_addc_co_u32_e32 v49, vcc, 0, v3, vcc
	global_load_dword v47, v[48:49], off nt
	v_add_co_u32_e32 v48, vcc, s4, v2
	s_mov_b32 s4, 0x1b8000
	s_nop 0
	v_addc_co_u32_e32 v49, vcc, 0, v3, vcc
	v_add_co_u32_e32 v50, vcc, s4, v2
	s_mov_b32 s4, 0x1c0000
	s_nop 0
	v_addc_co_u32_e32 v51, vcc, 0, v3, vcc
	global_load_dword v48, v[48:49], off nt
	s_nop 0
	global_load_dword v49, v[50:51], off nt
	v_add_co_u32_e32 v50, vcc, s4, v2
	s_mov_b32 s4, 0x1c8000
	s_nop 0
	v_addc_co_u32_e32 v51, vcc, 0, v3, vcc
	v_add_co_u32_e32 v52, vcc, s4, v2
	s_mov_b32 s4, 0x1d0000
	s_nop 0
	v_addc_co_u32_e32 v53, vcc, 0, v3, vcc
	global_load_dword v50, v[50:51], off nt
	s_nop 0
	global_load_dword v51, v[52:53], off nt
	v_add_co_u32_e32 v52, vcc, s4, v2
	s_mov_b32 s4, 0x1d8000
	s_nop 0
	v_addc_co_u32_e32 v53, vcc, 0, v3, vcc
	v_add_co_u32_e32 v54, vcc, s4, v2
	s_mov_b32 s4, 0x1e0000
	s_nop 0
	v_addc_co_u32_e32 v55, vcc, 0, v3, vcc
	global_load_dword v52, v[52:53], off nt
	s_nop 0
	global_load_dword v53, v[54:55], off nt
	v_add_co_u32_e32 v54, vcc, s4, v2
	s_mov_b32 s4, 0x1e8000
	s_nop 0
	v_addc_co_u32_e32 v55, vcc, 0, v3, vcc
	v_add_co_u32_e32 v56, vcc, s4, v2
	s_mov_b32 s4, 0x1f0000
	s_nop 0
	v_addc_co_u32_e32 v57, vcc, 0, v3, vcc
	global_load_dword v54, v[54:55], off nt
	s_nop 0
	global_load_dword v55, v[56:57], off nt
	v_add_co_u32_e32 v56, vcc, s4, v2
	s_mov_b32 s4, 0x1f8000
	s_nop 0
	v_addc_co_u32_e32 v57, vcc, 0, v3, vcc
	v_add_co_u32_e32 v2, vcc, s4, v2
	global_load_dword v56, v[56:57], off nt
	s_nop 0
	v_addc_co_u32_e32 v3, vcc, 0, v3, vcc
	global_load_dword v57, v[2:3], off nt
	global_load_dwordx4 v[104:107], v1, s[20:21] offset:48 nt
	global_load_dwordx4 v[108:111], v1, s[20:21] offset:32 nt
	global_load_dwordx4 v[112:115], v1, s[20:21] offset:16 nt
	global_load_dwordx4 v[116:119], v1, s[20:21] nt
	s_waitcnt vmcnt(0)
	v_mul_f32_e32 v69, v69, v111
	v_mul_f32_e32 v81, v8, v112
	v_mul_f32_e32 v77, v4, v116
	v_mul_f32_e32 v79, v5, v117
	v_mul_f32_e32 v84, v10, v113
	v_mul_f32_e32 v85, v12, v114
	v_mul_f32_e32 v86, v61, v115
	v_mul_f32_e32 v61, v62, v108
	v_mul_f32_e32 v62, v65, v109
	v_mul_f32_e32 v65, v67, v110
	v_mul_f32_e32 v67, v71, v104
	v_mul_f32_e32 v71, v75, v105
	v_mul_f32_e32 v75, v82, v106
	v_mul_f32_e32 v82, v92, v107
	global_load_dwordx4 v[2:5], v1, s[20:21] offset:112 nt
	global_load_dwordx4 v[108:111], v1, s[20:21] offset:96 nt
	global_load_dwordx4 v[112:115], v1, s[20:21] offset:80 nt
	global_load_dwordx4 v[104:107], v1, s[20:21] offset:64 nt
	v_mul_f32_e32 v80, v6, v118
	v_mul_f32_e32 v83, v7, v119
	s_waitcnt vmcnt(2)
	v_mul_f32_e32 v89, v89, v111
	s_waitcnt vmcnt(1)
	v_mul_f32_e32 v72, v72, v115
	s_waitcnt vmcnt(0)
	v_mul_f32_e32 v92, v9, v104
	v_mul_f32_e32 v104, v11, v105
	v_mul_f32_e32 v105, v13, v106
	v_mul_f32_e32 v106, v58, v107
	v_mul_f32_e32 v58, v59, v112
	v_mul_f32_e32 v59, v60, v113
	v_mul_f32_e32 v60, v63, v114
	v_mul_f32_e32 v63, v73, v108
	v_mul_f32_e32 v73, v76, v109
	v_mul_f32_e32 v76, v87, v110
	v_mul_f32_e32 v87, v90, v2
	v_mul_f32_e32 v90, v91, v3
	v_mul_f32_e32 v91, v93, v4
	v_mul_f32_e32 v93, v99, v5
	global_load_dwordx4 v[2:5], v1, s[20:21] offset:176 nt
	global_load_dwordx4 v[6:9], v1, s[20:21] offset:160 nt
	global_load_dwordx4 v[10:13], v1, s[20:21] offset:144 nt
	global_load_dwordx4 v[108:111], v1, s[20:21] offset:128 nt
	s_waitcnt vmcnt(3)
; #define LAS __attribute__((address_space(3)))
; __device__ __forceinline__ unsigned pk2(float lo, float hi) { return pg8::cvt_pk_bf16(lo, hi); }
; template <int MODE>
; __device__ __forceinline__ void p0_item(const float* W, int K, int N, bf16u* WT, const float* ks, LAS float* scr, int item, int lane) {
;     ...
;     if (ks) {
; #pragma unroll
;         for (int kk = 0; kk < 64; ++kk) v[kk] *= ks[k0 + kk];
;     }
; #pragma unroll
;     for (int kk = 0; kk < 64; ++kk) scr[kk * 65 + lane] = v[kk];
;     asm volatile("s_waitcnt lgkmcnt(0)" ::: "memory");
;     const int c = lane & 7;
; #pragma unroll
;     for (int j = 0; j < 8; ++j) { const int n = (lane >> 3) + 8 * j; const LAS float* s = scr + (8 * c) * 65 + n;
;         v4u o; o.x = pk2(s[0 * 65], s[1 * 65]); o.y = pk2(s[2 * 65], s[3 * 65]); o.z = pk2(s[4 * 65], s[5 * 65]); o.w = pk2(s[6 * 65], s[7 * 65]);
;         *(v4u*)(WT + (size_t)(drow + n) * K + k0 + 8 * c) = o; }
;     asm volatile("s_waitcnt lgkmcnt(0)" ::: "memory");
	v_mul_f32_e32 v100, v100, v2
	s_waitcnt vmcnt(2)
	v_mul_f32_e32 v107, v95, v6
	s_waitcnt vmcnt(1)
	v_mul_f32_e32 v74, v74, v10
	s_waitcnt vmcnt(0)
	v_mul_f32_e32 v64, v64, v108
	v_mul_f32_e32 v66, v66, v109
	v_mul_f32_e32 v78, v78, v11
	v_mul_f32_e32 v88, v88, v12
	v_mul_f32_e32 v99, v94, v13
	v_mul_f32_e32 v108, v96, v7
	v_mul_f32_e32 v109, v97, v8
	v_mul_f32_e32 v98, v98, v9
	v_mul_f32_e32 v101, v101, v3
	v_mul_f32_e32 v102, v102, v4
	v_mul_f32_e32 v103, v103, v5
	global_load_dwordx4 v[2:5], v1, s[20:21] offset:240 nt
	global_load_dwordx4 v[6:9], v1, s[20:21] offset:224 nt
	global_load_dwordx4 v[10:13], v1, s[20:21] offset:208 nt
	global_load_dwordx4 v[94:97], v1, s[20:21] offset:192 nt
	ds_write2_b32 v31, v77, v79 offset1:65
	ds_write2_b32 v31, v80, v83 offset0:130 offset1:195
	v_mul_f32_e32 v68, v68, v110
	v_mul_f32_e32 v70, v70, v111
	s_waitcnt vmcnt(3)
	v_mul_f32_e32 v2, v54, v2
	s_waitcnt vmcnt(2)
	v_mul_f32_e32 v6, v50, v6
	s_waitcnt vmcnt(1)
	v_mul_f32_e32 v10, v17, v10
	v_add_u32_e32 v17, 0x400, v31
	ds_write2_b32 v17, v81, v84 offset0:4 offset1:69
	ds_write2_b32 v17, v85, v86 offset0:134 offset1:199
	v_add_u32_e32 v17, 0x800, v31
	ds_write2_b32 v17, v61, v62 offset0:8 offset1:73
	ds_write2_b32 v17, v65, v69 offset0:138 offset1:203
	v_add_u32_e32 v17, 0xc00, v31
	ds_write2_b32 v17, v67, v71 offset0:12 offset1:77
	ds_write2_b32 v17, v75, v82 offset0:142 offset1:207
	v_add_u32_e32 v17, 0x1000, v31
	ds_write2_b32 v17, v92, v104 offset0:16 offset1:81
	ds_write2_b32 v17, v105, v106 offset0:146 offset1:211
	v_add_u32_e32 v17, 0x1400, v31
	ds_write2_b32 v17, v58, v59 offset0:20 offset1:85
	ds_write2_b32 v17, v60, v72 offset0:150 offset1:215
	v_add_u32_e32 v17, 0x1800, v31
	ds_write2_b32 v17, v63, v73 offset0:24 offset1:89
	ds_write2_b32 v17, v76, v89 offset0:154 offset1:219
	v_add_u32_e32 v17, 0x1c00, v31
	ds_write2_b32 v17, v87, v90 offset0:28 offset1:93
	ds_write2_b32 v17, v91, v93 offset0:158 offset1:223
	v_add_u32_e32 v17, 0x2000, v31
	ds_write2_b32 v17, v64, v66 offset0:32 offset1:97
	ds_write2_b32 v17, v68, v70 offset0:162 offset1:227
	v_add_u32_e32 v17, 0x2400, v31
	ds_write2_b32 v17, v74, v78 offset0:36 offset1:101
	ds_write2_b32 v17, v88, v99 offset0:166 offset1:231
	v_add_u32_e32 v17, 0x2800, v31
	ds_write2_b32 v17, v107, v108 offset0:40 offset1:105
	ds_write2_b32 v17, v109, v98 offset0:170 offset1:235
	v_add_u32_e32 v17, 0x2c00, v31
	s_waitcnt vmcnt(0)
	v_mul_f32_e32 v0, v0, v94
	v_mul_f32_e32 v14, v14, v95
	ds_write2_b32 v17, v100, v101 offset0:44 offset1:109
	ds_write2_b32 v17, v102, v103 offset0:174 offset1:239
	v_add_u32_e32 v17, 0x3000, v31
	v_mul_f32_e32 v15, v15, v96
	v_mul_f32_e32 v16, v16, v97
	v_mul_f32_e32 v11, v47, v11
	ds_write2_b32 v17, v0, v14 offset0:48 offset1:113
	ds_write2_b32 v17, v15, v16 offset0:178 offset1:243
	v_add_u32_e32 v0, 0x3400, v31
	v_mul_f32_e32 v12, v48, v12
	v_mul_f32_e32 v13, v49, v13
	v_mul_f32_e32 v7, v51, v7
	ds_write2_b32 v0, v10, v11 offset0:52 offset1:117
	ds_write2_b32 v0, v12, v13 offset0:182 offset1:247
	v_add_u32_e32 v0, 0x3800, v31
	v_mul_f32_e32 v8, v52, v8
	v_mul_f32_e32 v9, v53, v9
	v_mul_f32_e32 v3, v55, v3
	ds_write2_b32 v0, v6, v7 offset0:56 offset1:121
	ds_write2_b32 v0, v8, v9 offset0:186 offset1:251
	v_add_u32_e32 v0, 0x3c00, v31
	v_mul_f32_e32 v4, v56, v4
	v_mul_f32_e32 v5, v57, v5
	ds_write2_b32 v0, v2, v3 offset0:60 offset1:125
	ds_write2_b32 v0, v4, v5 offset0:190 offset1:255
	s_waitcnt lgkmcnt(0)
	v_add_u32_e32 v0, 0x400, v33
	ds_read2_b32 v[8:9], v33 offset0:65 offset1:73
	ds_read2_b32 v[10:11], v33 offset1:8
	ds_read2_b32 v[12:13], v33 offset0:130 offset1:138
	ds_read2_b32 v[14:15], v33 offset0:195 offset1:203
	ds_read2_b32 v[16:17], v0 offset0:4 offset1:12
	ds_read2_b32 v[48:49], v0 offset0:69 offset1:77
	ds_read2_b32 v[50:51], v0 offset0:134 offset1:142
	ds_read2_b32 v[52:53], v0 offset0:199 offset1:207
	v_add_u32_e32 v54, s1, v45
	v_ashrrev_i32_e32 v55, 31, v54
	v_lshl_add_u64 v[2:3], s[16:17], 1, v[18:19]
	v_lshlrev_b64 v[56:57], 11, v[54:55]
	s_waitcnt lgkmcnt(6)
; #define LAS __attribute__((address_space(3)))
; __device__ __forceinline__ unsigned pk2(float lo, float hi) { return pg8::cvt_pk_bf16(lo, hi); }
; template <int MODE>
; __device__ __forceinline__ void p0_item(const float* W, int K, int N, bf16u* WT, const float* ks, LAS float* scr, int item, int lane) {
;     ...
;     const int c = lane & 7;
; #pragma unroll
;     for (int j = 0; j < 8; ++j) { const int n = (lane >> 3) + 8 * j; const LAS float* s = scr + (8 * c) * 65 + n;
;         v4u o; o.x = pk2(s[0 * 65], s[1 * 65]); o.y = pk2(s[2 * 65], s[3 * 65]); o.z = pk2(s[4 * 65], s[5 * 65]); o.w = pk2(s[6 * 65], s[7 * 65]);
;         *(v4u*)(WT + (size_t)(drow + n) * K + k0 + 8 * c) = o; }
;     asm volatile("s_waitcnt lgkmcnt(0)" ::: "memory");
	v_cvt_pk_bf16_f32 v4, v10, v8
	s_waitcnt lgkmcnt(4)
	v_cvt_pk_bf16_f32 v5, v12, v14
	s_waitcnt lgkmcnt(2)
	v_cvt_pk_bf16_f32 v6, v16, v48
	s_waitcnt lgkmcnt(0)
	v_cvt_pk_bf16_f32 v7, v50, v52
	v_lshl_add_u64 v[56:57], v[2:3], 0, v[56:57]
	v_add_u32_e32 v8, 8, v54
	global_store_dwordx4 v[56:57], v[4:7], off sc1
	v_add_u32_e32 v56, 16, v54
	v_ashrrev_i32_e32 v57, 31, v56
	v_cvt_pk_bf16_f32 v4, v11, v9
	v_ashrrev_i32_e32 v9, 31, v8
	v_lshlrev_b64 v[8:9], 11, v[8:9]
	v_cvt_pk_bf16_f32 v5, v13, v15
	v_cvt_pk_bf16_f32 v6, v17, v49
	v_cvt_pk_bf16_f32 v7, v51, v53
	v_lshl_add_u64 v[8:9], v[2:3], 0, v[8:9]
	global_store_dwordx4 v[8:9], v[4:7], off sc1
	ds_read2_b32 v[8:9], v33 offset0:81 offset1:89
	ds_read2_b32 v[10:11], v33 offset0:16 offset1:24
	ds_read2_b32 v[12:13], v33 offset0:146 offset1:154
	ds_read2_b32 v[14:15], v33 offset0:211 offset1:219
	ds_read2_b32 v[16:17], v0 offset0:20 offset1:28
	ds_read2_b32 v[48:49], v0 offset0:85 offset1:93
	ds_read2_b32 v[50:51], v0 offset0:150 offset1:158
	ds_read2_b32 v[52:53], v0 offset0:215 offset1:223
	v_lshlrev_b64 v[56:57], 11, v[56:57]
	s_waitcnt lgkmcnt(6)
	v_cvt_pk_bf16_f32 v4, v10, v8
	s_waitcnt lgkmcnt(4)
	v_cvt_pk_bf16_f32 v5, v12, v14
	s_waitcnt lgkmcnt(2)
	v_cvt_pk_bf16_f32 v6, v16, v48
	s_waitcnt lgkmcnt(0)
	v_cvt_pk_bf16_f32 v7, v50, v52
	v_lshl_add_u64 v[56:57], v[2:3], 0, v[56:57]
	v_add_u32_e32 v8, 24, v54
	global_store_dwordx4 v[56:57], v[4:7], off sc1
	v_add_u32_e32 v56, 32, v54
	v_ashrrev_i32_e32 v57, 31, v56
	v_cvt_pk_bf16_f32 v4, v11, v9
	v_ashrrev_i32_e32 v9, 31, v8
	v_lshlrev_b64 v[8:9], 11, v[8:9]
	v_cvt_pk_bf16_f32 v5, v13, v15
	v_cvt_pk_bf16_f32 v6, v17, v49
	v_cvt_pk_bf16_f32 v7, v51, v53
	v_lshl_add_u64 v[8:9], v[2:3], 0, v[8:9]
	global_store_dwordx4 v[8:9], v[4:7], off sc1
	ds_read2_b32 v[8:9], v33 offset0:32 offset1:40
	ds_read2_b32 v[10:11], v33 offset0:97 offset1:105
	ds_read2_b32 v[12:13], v33 offset0:162 offset1:170
	ds_read2_b32 v[14:15], v33 offset0:227 offset1:235
	ds_read2_b32 v[16:17], v0 offset0:36 offset1:44
	ds_read2_b32 v[48:49], v0 offset0:101 offset1:109
	ds_read2_b32 v[50:51], v0 offset0:166 offset1:174
	ds_read2_b32 v[52:53], v0 offset0:231 offset1:239
	v_lshlrev_b64 v[56:57], 11, v[56:57]
	s_waitcnt lgkmcnt(6)
	v_cvt_pk_bf16_f32 v4, v8, v10
	s_waitcnt lgkmcnt(4)
	v_cvt_pk_bf16_f32 v5, v12, v14
	s_waitcnt lgkmcnt(2)
	v_cvt_pk_bf16_f32 v6, v16, v48
	s_waitcnt lgkmcnt(0)
	v_cvt_pk_bf16_f32 v7, v50, v52
	v_lshl_add_u64 v[56:57], v[2:3], 0, v[56:57]
	v_add_u32_e32 v8, 40, v54
	global_store_dwordx4 v[56:57], v[4:7], off sc1
	v_add_u32_e32 v56, 48, v54
	v_ashrrev_i32_e32 v57, 31, v56
	v_cvt_pk_bf16_f32 v4, v9, v11
	v_ashrrev_i32_e32 v9, 31, v8
	v_lshlrev_b64 v[8:9], 11, v[8:9]
	v_cvt_pk_bf16_f32 v5, v13, v15
	v_cvt_pk_bf16_f32 v6, v17, v49
	v_cvt_pk_bf16_f32 v7, v51, v53
	v_lshl_add_u64 v[8:9], v[2:3], 0, v[8:9]
	global_store_dwordx4 v[8:9], v[4:7], off sc1
	ds_read2_b32 v[8:9], v33 offset0:48 offset1:56
	ds_read2_b32 v[10:11], v33 offset0:113 offset1:121
	ds_read2_b32 v[12:13], v33 offset0:178 offset1:186
	ds_read2_b32 v[14:15], v33 offset0:243 offset1:251
	ds_read2_b32 v[16:17], v0 offset0:52 offset1:60
	ds_read2_b32 v[48:49], v0 offset0:117 offset1:125
	ds_read2_b32 v[50:51], v0 offset0:182 offset1:190
	ds_read2_b32 v[52:53], v0 offset0:247 offset1:255
	v_lshlrev_b64 v[56:57], 11, v[56:57]
	s_waitcnt lgkmcnt(6)
	v_cvt_pk_bf16_f32 v4, v8, v10
	s_waitcnt lgkmcnt(4)
	v_cvt_pk_bf16_f32 v5, v12, v14
	s_waitcnt lgkmcnt(2)
	v_cvt_pk_bf16_f32 v6, v16, v48
	s_waitcnt lgkmcnt(0)
	v_cvt_pk_bf16_f32 v7, v50, v52
	v_lshl_add_u64 v[56:57], v[2:3], 0, v[56:57]
	v_add_u32_e32 v8, 56, v54
	global_store_dwordx4 v[56:57], v[4:7], off sc1
	s_nop 1
	v_cvt_pk_bf16_f32 v4, v9, v11
	v_ashrrev_i32_e32 v9, 31, v8
	v_lshlrev_b64 v[8:9], 11, v[8:9]
	v_cvt_pk_bf16_f32 v5, v13, v15
	v_cvt_pk_bf16_f32 v6, v17, v49
	v_cvt_pk_bf16_f32 v7, v51, v53
	v_lshl_add_u64 v[2:3], v[2:3], 0, v[8:9]
	global_store_dwordx4 v[2:3], v[4:7], off sc1
	s_waitcnt lgkmcnt(0)

; template <int MODE>
; __device__ __forceinline__ void p0_item(const float* W, int K, int N, bf16u* WT, const float* ks, LAS float* scr, int item, int lane) {
;     const int nblk = N / 64, kb = item / nblk, nb = item - kb * nblk, k0 = 64 * kb, n0 = 64 * nb;
;     int nn = n0 + lane;
;     if (MODE == 1) {
;         if (nn < 2048) { const int p = nn & 63; if (p < 16) nn = (nn & ~15) | (p & 3) | ((p & 4) << 1) | ((p & 8) >> 1); }
;         else if (nn >= 4096) { const int sec = nn >= 6144 ? 6144 : 4096, r = nn - sec, q = r & 255; nn = sec + ((q >> 7) << 10) + 128 * (r >> 8) + (q & 127); }
;     }
;     int drow = n0;
;     if (MODE == 2) drow = 256 * (n0 >> 7) + (n0 & 127);
;     if (MODE == 3) drow = 256 * (n0 >> 7) + 128 + (n0 & 127);
;     const float* src = W + (size_t)k0 * N + nn;
;     float v[64];
; #pragma unroll
;     for (int kk = 0; kk < 64; ++kk) v[kk] = src[(size_t)kk * N];
.LBB0_599:
	s_add_i32 s1, s55, 0xdc0
	s_cmpk_gt_i32 s1, 0x7ff
	s_mov_b64 s[16:17], -1
	s_cbranch_scc0 .LBB0_621
	s_cmpk_gt_u32 s1, 0x8ff
	s_cbranch_scc0 .LBB0_618
	s_cmpk_gt_u32 s1, 0x9ff
	s_cbranch_scc0 .LBB0_615
	s_cmpk_gt_u32 s1, 0xaff
	s_cbranch_scc0 .LBB0_612
	s_cmpk_gt_u32 s1, 0xdbf
	s_cbranch_scc0 .LBB0_609
	s_cmpk_gt_u32 s1, 0x107f
	s_cbranch_scc0 .LBB0_606
	s_add_i32 s4, s53, 0xffffbe00
	s_and_b32 s12, s4, 0xfc0
	s_add_i32 s4, s52, s59
	s_add_i32 s4, s4, 0xfffbe000
	s_and_b32 s4, s4, 0x3c0
	s_lshl_b32 s16, s12, 12
	v_or_b32_e32 v0, s4, v30
	s_add_u32 s16, s13, s16
	s_addc_u32 s17, s34, 0
	v_lshlrev_b32_e32 v0, 2, v0
	v_lshl_add_u64 v[2:3], s[16:17], 0, v[0:1]
	v_add_co_u32_e32 v4, vcc, s61, v2
	global_load_dword v0, v0, s[16:17] nt
	s_nop 0
	v_addc_co_u32_e32 v5, vcc, 0, v3, vcc
	s_movk_i32 s16, 0x4000
	global_load_dword v6, v[4:5], off offset:-4096 nt
	global_load_dword v7, v[4:5], off nt
	v_add_co_u32_e32 v4, vcc, s16, v2
	s_movk_i32 s16, 0x6000
	s_nop 0
	v_addc_co_u32_e32 v5, vcc, 0, v3, vcc
	global_load_dword v8, v[4:5], off offset:-4096 nt
	global_load_dword v9, v[4:5], off nt
	v_add_co_u32_e32 v4, vcc, s16, v2
	s_mov_b32 s16, 0xe000
	s_nop 0
	v_addc_co_u32_e32 v5, vcc, 0, v3, vcc
	global_load_dword v10, v[4:5], off offset:-4096 nt
	global_load_dword v11, v[4:5], off nt
	v_add_co_u32_e32 v4, vcc, s88, v2
	s_lshl_b32 s90, s12, 1
	s_nop 0
	v_addc_co_u32_e32 v5, vcc, 0, v3, vcc
	global_load_dword v12, v[4:5], off offset:-4096 nt
	global_load_dword v13, v[4:5], off nt
	v_add_co_u32_e32 v4, vcc, s27, v2
	s_nop 1
	v_addc_co_u32_e32 v5, vcc, 0, v3, vcc
	global_load_dword v14, v[4:5], off offset:-4096 nt
	global_load_dword v15, v[4:5], off nt
	v_add_co_u32_e32 v4, vcc, s26, v2
	s_nop 1
	v_addc_co_u32_e32 v5, vcc, 0, v3, vcc
	global_load_dword v16, v[4:5], off offset:-4096 nt
	global_load_dword v17, v[4:5], off nt
	v_add_co_u32_e32 v4, vcc, s16, v2
	s_mov_b32 s16, 0x10000
	s_nop 0
	v_addc_co_u32_e32 v5, vcc, 0, v3, vcc
	global_load_dword v47, v[4:5], off offset:-4096 nt
	global_load_dword v48, v[4:5], off nt
	v_add_co_u32_e32 v4, vcc, s16, v2
	s_mov_b32 s16, 0x14000
	s_nop 0
	v_addc_co_u32_e32 v5, vcc, 0, v3, vcc
	global_load_dword v49, v[4:5], off offset:-4096 nt
	global_load_dword v50, v[4:5], off nt
	v_add_co_u32_e32 v4, vcc, s22, v2
	s_nop 1
	v_addc_co_u32_e32 v5, vcc, 0, v3, vcc
	global_load_dword v51, v[4:5], off offset:-4096 nt
	global_load_dword v52, v[4:5], off nt
	v_add_co_u32_e32 v4, vcc, s16, v2
	s_mov_b32 s16, 0x16000
	s_nop 0
	v_addc_co_u32_e32 v5, vcc, 0, v3, vcc
	global_load_dword v53, v[4:5], off offset:-4096 nt
	global_load_dword v54, v[4:5], off nt
	v_add_co_u32_e32 v4, vcc, s16, v2
	s_mov_b32 s16, 0x1a000
	s_nop 0
	v_addc_co_u32_e32 v5, vcc, 0, v3, vcc
	global_load_dword v55, v[4:5], off offset:-4096 nt
	global_load_dword v56, v[4:5], off nt
	v_add_co_u32_e32 v4, vcc, s5, v2
	s_nop 1
	v_addc_co_u32_e32 v5, vcc, 0, v3, vcc
	global_load_dword v57, v[4:5], off offset:-4096 nt
	global_load_dword v58, v[4:5], off nt
	v_add_co_u32_e32 v4, vcc, s16, v2
	s_mov_b32 s16, 0x1c000
	s_nop 0
	v_addc_co_u32_e32 v5, vcc, 0, v3, vcc
	global_load_dword v59, v[4:5], off offset:-4096 nt
	global_load_dword v60, v[4:5], off nt
	v_add_co_u32_e32 v4, vcc, s16, v2
	s_mov_b32 s16, 0x1e000
	s_nop 0
	v_addc_co_u32_e32 v5, vcc, 0, v3, vcc
	global_load_dword v61, v[4:5], off offset:-4096 nt
	global_load_dword v62, v[4:5], off nt
	v_add_co_u32_e32 v4, vcc, s16, v2
	s_mov_b32 s16, 0x20000
	s_nop 0
	v_addc_co_u32_e32 v5, vcc, 0, v3, vcc
	global_load_dword v63, v[4:5], off offset:-4096 nt
	global_load_dword v64, v[4:5], off nt
	v_add_co_u32_e32 v4, vcc, s16, v2
	s_mov_b32 s16, 0x22000
	s_nop 0
	v_addc_co_u32_e32 v5, vcc, 0, v3, vcc
	global_load_dword v65, v[4:5], off offset:-4096 nt
	global_load_dword v66, v[4:5], off nt
	v_add_co_u32_e32 v4, vcc, s16, v2
	s_mov_b32 s16, 0x24000
	s_nop 0
	v_addc_co_u32_e32 v5, vcc, 0, v3, vcc
	global_load_dword v67, v[4:5], off offset:-4096 nt
	global_load_dword v68, v[4:5], off nt
	v_add_co_u32_e32 v4, vcc, s16, v2
	s_mov_b32 s16, 0x26000
	s_nop 0
	v_addc_co_u32_e32 v5, vcc, 0, v3, vcc
	global_load_dword v69, v[4:5], off offset:-4096 nt
	global_load_dword v70, v[4:5], off nt
	v_add_co_u32_e32 v4, vcc, s16, v2
	s_mov_b32 s16, 0x28000
	s_nop 0
	v_addc_co_u32_e32 v5, vcc, 0, v3, vcc
	global_load_dword v71, v[4:5], off offset:-4096 nt
	global_load_dword v72, v[4:5], off nt
	v_add_co_u32_e32 v4, vcc, s16, v2
	s_mov_b32 s16, 0x2a000
	s_nop 0
	v_addc_co_u32_e32 v5, vcc, 0, v3, vcc
	global_load_dword v73, v[4:5], off offset:-4096 nt
	global_load_dword v74, v[4:5], off nt
	v_add_co_u32_e32 v4, vcc, s16, v2
	s_mov_b32 s16, 0x2c000
	s_nop 0
	v_addc_co_u32_e32 v5, vcc, 0, v3, vcc
	global_load_dword v75, v[4:5], off offset:-4096 nt
	global_load_dword v76, v[4:5], off nt
	v_add_co_u32_e32 v4, vcc, s16, v2
	s_mov_b32 s16, 0x2e000
	s_nop 0
	v_addc_co_u32_e32 v5, vcc, 0, v3, vcc
	global_load_dword v77, v[4:5], off offset:-4096 nt
	global_load_dword v78, v[4:5], off nt
	v_add_co_u32_e32 v4, vcc, s16, v2
	s_mov_b32 s16, 0x30000
	s_nop 0
	v_addc_co_u32_e32 v5, vcc, 0, v3, vcc
	global_load_dword v79, v[4:5], off offset:-4096 nt
	global_load_dword v80, v[4:5], off nt
	v_add_co_u32_e32 v4, vcc, s16, v2
	s_mov_b32 s16, 0x32000
	s_nop 0
	v_addc_co_u32_e32 v5, vcc, 0, v3, vcc
	global_load_dword v81, v[4:5], off offset:-4096 nt
	global_load_dword v82, v[4:5], off nt
	v_add_co_u32_e32 v4, vcc, s16, v2
	s_mov_b32 s16, 0x34000
	s_nop 0
	v_addc_co_u32_e32 v5, vcc, 0, v3, vcc
	global_load_dword v83, v[4:5], off offset:-4096 nt
	global_load_dword v84, v[4:5], off nt
	v_add_co_u32_e32 v4, vcc, s16, v2
	s_mov_b32 s16, 0x36000
	s_nop 0
	v_addc_co_u32_e32 v5, vcc, 0, v3, vcc
	global_load_dword v85, v[4:5], off offset:-4096 nt
	global_load_dword v86, v[4:5], off nt
	v_add_co_u32_e32 v4, vcc, s16, v2
	s_mov_b32 s16, 0x38000
	s_nop 0
	v_addc_co_u32_e32 v5, vcc, 0, v3, vcc
	global_load_dword v87, v[4:5], off offset:-4096 nt
	global_load_dword v88, v[4:5], off nt
	v_add_co_u32_e32 v4, vcc, s16, v2
	s_mov_b32 s16, 0x3a000
	s_nop 0
	v_addc_co_u32_e32 v5, vcc, 0, v3, vcc
	global_load_dword v89, v[4:5], off offset:-4096 nt
	global_load_dword v90, v[4:5], off nt
	v_add_co_u32_e32 v4, vcc, s16, v2
	s_mov_b32 s16, 0x3c000
	s_nop 0
	v_addc_co_u32_e32 v5, vcc, 0, v3, vcc
	global_load_dword v91, v[4:5], off offset:-4096 nt
	global_load_dword v92, v[4:5], off nt
	v_add_co_u32_e32 v4, vcc, s16, v2
	s_mov_b32 s16, 0x3e000
	s_nop 0
	v_addc_co_u32_e32 v5, vcc, 0, v3, vcc
	global_load_dword v93, v[4:5], off offset:-4096 nt
	global_load_dword v94, v[4:5], off nt
	v_add_co_u32_e32 v4, vcc, s16, v2
	s_mov_b32 s16, 0x3f000
	s_nop 0
	v_addc_co_u32_e32 v5, vcc, 0, v3, vcc
	v_add_co_u32_e32 v2, vcc, s16, v2
	global_load_dword v95, v[4:5], off offset:-4096 nt
	s_nop 0
	global_load_dword v4, v[4:5], off nt
	v_addc_co_u32_e32 v3, vcc, 0, v3, vcc
	global_load_dword v2, v[2:3], off nt
	s_waitcnt vmcnt(0)
; #define LAS __attribute__((address_space(3)))
; __device__ __forceinline__ unsigned pk2(float lo, float hi) { return pg8::cvt_pk_bf16(lo, hi); }
; template <int MODE>
; __device__ __forceinline__ void p0_item(const float* W, int K, int N, bf16u* WT, const float* ks, LAS float* scr, int item, int lane) {
;     ...
; #pragma unroll
;     for (int kk = 0; kk < 64; ++kk) scr[kk * 65 + lane] = v[kk];
;     asm volatile("s_waitcnt lgkmcnt(0)" ::: "memory");
;     const int c = lane & 7;
; #pragma unroll
;     for (int j = 0; j < 8; ++j) { const int n = (lane >> 3) + 8 * j; const LAS float* s = scr + (8 * c) * 65 + n;
;         v4u o; o.x = pk2(s[0 * 65], s[1 * 65]); o.y = pk2(s[2 * 65], s[3 * 65]); o.z = pk2(s[4 * 65], s[5 * 65]); o.w = pk2(s[6 * 65], s[7 * 65]);
;         *(v4u*)(WT + (size_t)(drow + n) * K + k0 + 8 * c) = o; }
;     asm volatile("s_waitcnt lgkmcnt(0)" ::: "memory");
	ds_write2_b32 v31, v0, v6 offset1:65
	ds_write2_b32 v31, v7, v8 offset0:130 offset1:195
	v_add_u32_e32 v0, 0x400, v31
	ds_write2_b32 v0, v9, v10 offset0:4 offset1:69
	ds_write2_b32 v0, v11, v12 offset0:134 offset1:199
	v_add_u32_e32 v0, 0x800, v31
	ds_write2_b32 v0, v13, v14 offset0:8 offset1:73
	ds_write2_b32 v0, v15, v16 offset0:138 offset1:203
	v_add_u32_e32 v0, 0xc00, v31
	ds_write2_b32 v0, v17, v47 offset0:12 offset1:77
	ds_write2_b32 v0, v48, v49 offset0:142 offset1:207
	v_add_u32_e32 v0, 0x1000, v31
	ds_write2_b32 v0, v50, v51 offset0:16 offset1:81
	ds_write2_b32 v0, v52, v53 offset0:146 offset1:211
	v_add_u32_e32 v0, 0x1400, v31
	ds_write2_b32 v0, v54, v55 offset0:20 offset1:85
	ds_write2_b32 v0, v56, v57 offset0:150 offset1:215
	v_add_u32_e32 v0, 0x1800, v31
	ds_write2_b32 v0, v58, v59 offset0:24 offset1:89
	ds_write2_b32 v0, v60, v61 offset0:154 offset1:219
	v_add_u32_e32 v0, 0x1c00, v31
	ds_write2_b32 v0, v62, v63 offset0:28 offset1:93
	ds_write2_b32 v0, v64, v65 offset0:158 offset1:223
	v_add_u32_e32 v0, 0x2000, v31
	ds_write2_b32 v0, v66, v67 offset0:32 offset1:97
	ds_write2_b32 v0, v68, v69 offset0:162 offset1:227
	v_add_u32_e32 v0, 0x2400, v31
	ds_write2_b32 v0, v70, v71 offset0:36 offset1:101
	ds_write2_b32 v0, v72, v73 offset0:166 offset1:231
	v_add_u32_e32 v0, 0x2800, v31
	ds_write2_b32 v0, v74, v75 offset0:40 offset1:105
	ds_write2_b32 v0, v76, v77 offset0:170 offset1:235
	v_add_u32_e32 v0, 0x2c00, v31
	ds_write2_b32 v0, v78, v79 offset0:44 offset1:109
	ds_write2_b32 v0, v80, v81 offset0:174 offset1:239
	v_add_u32_e32 v0, 0x3000, v31
	ds_write2_b32 v0, v82, v83 offset0:48 offset1:113
	ds_write2_b32 v0, v84, v85 offset0:178 offset1:243
	v_add_u32_e32 v0, 0x3400, v31
	ds_write2_b32 v0, v86, v87 offset0:52 offset1:117
	ds_write2_b32 v0, v88, v89 offset0:182 offset1:247
	v_add_u32_e32 v0, 0x3800, v31
	ds_write2_b32 v0, v90, v91 offset0:56 offset1:121
	ds_write2_b32 v0, v92, v93 offset0:186 offset1:251
	v_add_u32_e32 v0, 0x3c00, v31
	ds_write2_b32 v0, v94, v95 offset0:60 offset1:125
	ds_write2_b32 v0, v4, v2 offset0:190 offset1:255
	s_waitcnt lgkmcnt(0)
	v_add_u32_e32 v47, 0x400, v33
	ds_read2_b32 v[8:9], v33 offset0:65 offset1:73
	ds_read2_b32 v[10:11], v33 offset1:8
	ds_read2_b32 v[12:13], v33 offset0:130 offset1:138
	ds_read2_b32 v[14:15], v33 offset0:195 offset1:203
	ds_read2_b32 v[16:17], v47 offset0:4 offset1:12
	ds_read2_b32 v[48:49], v47 offset0:69 offset1:77
	ds_read2_b32 v[50:51], v47 offset0:134 offset1:142
	ds_read2_b32 v[52:53], v47 offset0:199 offset1:207
	v_or_b32_e32 v0, s4, v32
	v_mul_u32_u24_e32 v0, 0xb00, v0
	v_lshl_add_u64 v[2:3], v[20:21], 0, s[90:91]
	v_lshlrev_b32_e32 v0, 1, v0
	v_lshl_add_u64 v[54:55], v[2:3], 0, v[0:1]
	v_or_b32_e32 v0, s4, v34
	v_mul_u32_u24_e32 v0, 0xb00, v0
	s_waitcnt lgkmcnt(6)
	v_cvt_pk_bf16_f32 v4, v10, v8
	s_waitcnt lgkmcnt(4)
	v_cvt_pk_bf16_f32 v5, v12, v14
	s_waitcnt lgkmcnt(2)
	v_cvt_pk_bf16_f32 v6, v16, v48
	s_waitcnt lgkmcnt(0)
	v_cvt_pk_bf16_f32 v7, v50, v52
	v_lshlrev_b32_e32 v0, 1, v0
	global_store_dwordx4 v[54:55], v[4:7], off sc1
	s_mov_b64 s[16:17], 0
	s_nop 0
	v_cvt_pk_bf16_f32 v4, v11, v9
	v_cvt_pk_bf16_f32 v5, v13, v15
	v_cvt_pk_bf16_f32 v6, v17, v49
	v_cvt_pk_bf16_f32 v7, v51, v53
	v_lshl_add_u64 v[8:9], v[2:3], 0, v[0:1]
	global_store_dwordx4 v[8:9], v[4:7], off sc1
	ds_read2_b32 v[8:9], v33 offset0:16 offset1:24
	ds_read2_b32 v[10:11], v33 offset0:81 offset1:89
	ds_read2_b32 v[12:13], v33 offset0:146 offset1:154
	ds_read2_b32 v[14:15], v33 offset0:211 offset1:219
	ds_read2_b32 v[16:17], v47 offset0:20 offset1:28
	ds_read2_b32 v[48:49], v47 offset0:85 offset1:93
	ds_read2_b32 v[50:51], v47 offset0:150 offset1:158
	ds_read2_b32 v[52:53], v47 offset0:215 offset1:223
	v_or_b32_e32 v0, s4, v35
	v_mul_u32_u24_e32 v0, 0xb00, v0
	v_lshlrev_b32_e32 v0, 1, v0
	v_lshl_add_u64 v[54:55], v[2:3], 0, v[0:1]
	v_or_b32_e32 v0, s4, v36
	v_mul_u32_u24_e32 v0, 0xb00, v0
	s_waitcnt lgkmcnt(6)
	v_cvt_pk_bf16_f32 v4, v8, v10
	s_waitcnt lgkmcnt(4)
	v_cvt_pk_bf16_f32 v5, v12, v14
	s_waitcnt lgkmcnt(2)
	v_cvt_pk_bf16_f32 v6, v16, v48
	s_waitcnt lgkmcnt(0)
	v_cvt_pk_bf16_f32 v7, v50, v52
	v_lshlrev_b32_e32 v0, 1, v0
	global_store_dwordx4 v[54:55], v[4:7], off sc1
	s_nop 1
	v_cvt_pk_bf16_f32 v4, v9, v11
	v_cvt_pk_bf16_f32 v5, v13, v15
	v_cvt_pk_bf16_f32 v6, v17, v49
	v_cvt_pk_bf16_f32 v7, v51, v53
	v_lshl_add_u64 v[8:9], v[2:3], 0, v[0:1]
	global_store_dwordx4 v[8:9], v[4:7], off sc1
	ds_read2_b32 v[8:9], v33 offset0:32 offset1:40
	ds_read2_b32 v[10:11], v33 offset0:97 offset1:105
	ds_read2_b32 v[12:13], v33 offset0:162 offset1:170
	ds_read2_b32 v[14:15], v33 offset0:227 offset1:235
	ds_read2_b32 v[16:17], v47 offset0:36 offset1:44
	ds_read2_b32 v[48:49], v47 offset0:101 offset1:109
	ds_read2_b32 v[50:51], v47 offset0:166 offset1:174
	ds_read2_b32 v[52:53], v47 offset0:231 offset1:239
	v_or_b32_e32 v0, s4, v37
	v_mul_u32_u24_e32 v0, 0xb00, v0
	v_lshlrev_b32_e32 v0, 1, v0
	v_lshl_add_u64 v[54:55], v[2:3], 0, v[0:1]
	v_or_b32_e32 v0, s4, v38
	v_mul_u32_u24_e32 v0, 0xb00, v0
	s_waitcnt lgkmcnt(6)
	v_cvt_pk_bf16_f32 v4, v8, v10
	s_waitcnt lgkmcnt(4)
	v_cvt_pk_bf16_f32 v5, v12, v14
	s_waitcnt lgkmcnt(2)
	v_cvt_pk_bf16_f32 v6, v16, v48
	s_waitcnt lgkmcnt(0)
	v_cvt_pk_bf16_f32 v7, v50, v52
	v_lshlrev_b32_e32 v0, 1, v0
	global_store_dwordx4 v[54:55], v[4:7], off sc1
	s_nop 1
	v_cvt_pk_bf16_f32 v4, v9, v11
	v_cvt_pk_bf16_f32 v5, v13, v15
	v_cvt_pk_bf16_f32 v6, v17, v49
	v_cvt_pk_bf16_f32 v7, v51, v53
	v_lshl_add_u64 v[8:9], v[2:3], 0, v[0:1]
	global_store_dwordx4 v[8:9], v[4:7], off sc1
	ds_read2_b32 v[8:9], v33 offset0:48 offset1:56
	ds_read2_b32 v[10:11], v33 offset0:113 offset1:121
	ds_read2_b32 v[12:13], v33 offset0:178 offset1:186
	ds_read2_b32 v[14:15], v33 offset0:243 offset1:251
	ds_read2_b32 v[16:17], v47 offset0:52 offset1:60
	ds_read2_b32 v[48:49], v47 offset0:117 offset1:125
	ds_read2_b32 v[50:51], v47 offset0:182 offset1:190
	ds_read2_b32 v[52:53], v47 offset0:247 offset1:255
	v_or_b32_e32 v0, s4, v39
	v_mul_u32_u24_e32 v0, 0xb00, v0
	v_lshlrev_b32_e32 v0, 1, v0
	v_lshl_add_u64 v[54:55], v[2:3], 0, v[0:1]
	v_or_b32_e32 v0, s4, v40
	v_mul_u32_u24_e32 v0, 0xb00, v0
	s_waitcnt lgkmcnt(6)
	v_cvt_pk_bf16_f32 v4, v8, v10
	s_waitcnt lgkmcnt(4)
	v_cvt_pk_bf16_f32 v5, v12, v14
	s_waitcnt lgkmcnt(2)
	v_cvt_pk_bf16_f32 v6, v16, v48
	s_waitcnt lgkmcnt(0)
	v_cvt_pk_bf16_f32 v7, v50, v52
	v_lshlrev_b32_e32 v0, 1, v0
	global_store_dwordx4 v[54:55], v[4:7], off sc1
	v_lshl_add_u64 v[2:3], v[2:3], 0, v[0:1]
	s_nop 0
	v_cvt_pk_bf16_f32 v4, v9, v11
	v_cvt_pk_bf16_f32 v5, v13, v15
	v_cvt_pk_bf16_f32 v6, v17, v49
	v_cvt_pk_bf16_f32 v7, v51, v53
	global_store_dwordx4 v[2:3], v[4:7], off sc1
	s_waitcnt lgkmcnt(0)
; template <int MODE>
; __device__ __forceinline__ void p0_item(const float* W, int K, int N, bf16u* WT, const float* ks, LAS float* scr, int item, int lane) {
;     const int nblk = N / 64, kb = item / nblk, nb = item - kb * nblk, k0 = 64 * kb, n0 = 64 * nb;
;     int nn = n0 + lane;
;     if (MODE == 1) {
;         if (nn < 2048) { const int p = nn & 63; if (p < 16) nn = (nn & ~15) | (p & 3) | ((p & 4) << 1) | ((p & 8) >> 1); }
;         else if (nn >= 4096) { const int sec = nn >= 6144 ? 6144 : 4096, r = nn - sec, q = r & 255; nn = sec + ((q >> 7) << 10) + 128 * (r >> 8) + (q & 127); }
;     }
;     int drow = n0;
;     if (MODE == 2) drow = 256 * (n0 >> 7) + (n0 & 127);
;     if (MODE == 3) drow = 256 * (n0 >> 7) + 128 + (n0 & 127);
;     const float* src = W + (size_t)k0 * N + nn;
;     float v[64];
; #pragma unroll
;     for (int kk = 0; kk < 64; ++kk) v[kk] = src[(size_t)kk * N];
.LBB0_606:
	s_andn2_b64 vcc, exec, s[16:17]
	s_cbranch_vccnz .LBB0_608
	s_and_b32 s4, s55, 0xffff
	s_mul_hi_u32 s12, s4, 0x5d1745e
	s_mul_i32 s16, s12, 0xb00
	s_sub_i32 s17, s58, s16
	s_and_b32 s17, s17, 64
	s_mul_i32 s4, s4, 0xba2f
	v_add_u32_e32 v0, s17, v41
	s_mulk_i32 s12, 0x1600
	s_lshr_b32 s4, s4, 21
	v_subrev_u32_e32 v0, s12, v0
	v_subrev_u32_e32 v2, s16, v42
	s_mul_i32 s12, s4, 0xb0000
	v_add_u32_e32 v2, s59, v2
	s_add_u32 s16, s35, s12
	s_addc_u32 s17, s36, 0
	v_ashrrev_i32_e32 v3, 31, v2
	v_lshl_add_u64 v[2:3], v[2:3], 2, s[16:17]
	v_add_co_u32_e32 v6, vcc, s61, v2
	s_movk_i32 s12, 0x5000
	s_nop 0
	v_addc_co_u32_e32 v7, vcc, 0, v3, vcc
	global_load_dword v5, v[6:7], off offset:3072 nt
	v_add_co_u32_e32 v6, vcc, s12, v2
	s_mov_b32 s12, 0xb000
	s_nop 0
	v_addc_co_u32_e32 v7, vcc, 0, v3, vcc
	v_add_co_u32_e32 v8, vcc, s88, v2
	global_load_dword v4, v[2:3], off nt
	s_nop 0
	v_addc_co_u32_e32 v9, vcc, 0, v3, vcc
	global_load_dword v6, v[6:7], off offset:2048 nt
	s_lshl_b32 s90, s4, 7
	global_load_dword v7, v[8:9], off offset:1024 nt
	v_add_co_u32_e32 v8, vcc, s12, v2
	s_mov_b32 s12, 0xd000
	s_nop 0
	v_addc_co_u32_e32 v9, vcc, 0, v3, vcc
	v_add_co_u32_e32 v10, vcc, s12, v2
	s_mov_b32 s12, 0x10000
	s_nop 0
	v_addc_co_u32_e32 v11, vcc, 0, v3, vcc
	global_load_dword v8, v[8:9], off nt
	s_nop 0
	global_load_dword v9, v[10:11], off offset:3072 nt
	v_add_co_u32_e32 v10, vcc, s12, v2
	s_mov_b32 s12, 0x13000
	s_nop 0
	v_addc_co_u32_e32 v11, vcc, 0, v3, vcc
	v_add_co_u32_e32 v12, vcc, s12, v2
	s_mov_b32 s12, 0x16000
	s_nop 0
	v_addc_co_u32_e32 v13, vcc, 0, v3, vcc
	global_load_dword v16, v[12:13], off offset:1024 nt
	v_add_co_u32_e32 v12, vcc, s12, v2
	global_load_dword v11, v[10:11], off offset:2048 nt
	s_nop 0
	v_addc_co_u32_e32 v13, vcc, 0, v3, vcc
	global_load_dword v63, v[12:13], off nt
	v_add_co_u32_e32 v12, vcc, s5, v2
	s_mov_b32 s12, 0x1b000
	s_nop 0
	v_addc_co_u32_e32 v13, vcc, 0, v3, vcc
	global_load_dword v65, v[12:13], off offset:3072 nt
	v_add_co_u32_e32 v12, vcc, s12, v2
	s_mov_b32 s12, 0x1e000
	s_nop 0
	v_addc_co_u32_e32 v13, vcc, 0, v3, vcc
	global_load_dword v67, v[12:13], off offset:2048 nt
	v_add_co_u32_e32 v12, vcc, s12, v2
	s_mov_b32 s12, 0x21000
	s_nop 0
	v_addc_co_u32_e32 v13, vcc, 0, v3, vcc
	global_load_dword v69, v[12:13], off offset:1024 nt
	v_add_co_u32_e32 v12, vcc, s12, v2
	s_mov_b32 s12, 0x23000
	s_nop 0
	v_addc_co_u32_e32 v13, vcc, 0, v3, vcc
	global_load_dword v72, v[12:13], off nt
	v_add_co_u32_e32 v12, vcc, s12, v2
	s_mov_b32 s12, 0x26000
	s_nop 0
	v_addc_co_u32_e32 v13, vcc, 0, v3, vcc
	global_load_dword v81, v[12:13], off offset:3072 nt
	v_add_co_u32_e32 v12, vcc, s12, v2
	s_mov_b32 s12, 0x29000
	s_nop 0
	v_addc_co_u32_e32 v13, vcc, 0, v3, vcc
	global_load_dword v83, v[12:13], off offset:2048 nt
	v_add_co_u32_e32 v12, vcc, s12, v2
	s_mov_b32 s12, 0x2c000
	s_nop 0
	v_addc_co_u32_e32 v13, vcc, 0, v3, vcc
	global_load_dword v93, v[12:13], off offset:1024 nt
	v_add_co_u32_e32 v12, vcc, s12, v2
	s_mov_b32 s12, 0x2e000
	s_nop 0
	v_addc_co_u32_e32 v13, vcc, 0, v3, vcc
	global_load_dword v10, v[12:13], off nt
	v_add_co_u32_e32 v12, vcc, s12, v2
	s_mov_b32 s12, 0x31000
	s_nop 0
	v_addc_co_u32_e32 v13, vcc, 0, v3, vcc
	v_add_co_u32_e32 v14, vcc, s12, v2
	s_mov_b32 s12, 0x34000
	s_nop 0
	v_addc_co_u32_e32 v15, vcc, 0, v3, vcc
	global_load_dword v12, v[12:13], off offset:3072 nt
	s_nop 0
	global_load_dword v13, v[14:15], off offset:2048 nt
	v_add_co_u32_e32 v14, vcc, s12, v2
	s_mov_b32 s12, 0x37000
	s_nop 0
	v_addc_co_u32_e32 v15, vcc, 0, v3, vcc
	v_add_co_u32_e32 v48, vcc, s12, v2
	s_mov_b32 s12, 0x39000
	s_nop 0
	v_addc_co_u32_e32 v49, vcc, 0, v3, vcc
	global_load_dword v14, v[14:15], off offset:1024 nt
	s_nop 0
	global_load_dword v15, v[48:49], off nt
	v_add_co_u32_e32 v48, vcc, s12, v2
	s_mov_b32 s12, 0x3c000
	s_nop 0
	v_addc_co_u32_e32 v49, vcc, 0, v3, vcc
	global_load_dword v17, v[48:49], off offset:3072 nt
	v_add_co_u32_e32 v48, vcc, s12, v2
	s_mov_b32 s12, 0x3f000
	s_nop 0
	v_addc_co_u32_e32 v49, vcc, 0, v3, vcc
	global_load_dword v64, v[48:49], off offset:2048 nt
	v_add_co_u32_e32 v48, vcc, s12, v2
	s_mov_b32 s12, 0x42000
	s_nop 0
	v_addc_co_u32_e32 v49, vcc, 0, v3, vcc
	global_load_dword v84, v[48:49], off offset:1024 nt
	v_add_co_u32_e32 v48, vcc, s12, v2
	s_mov_b32 s12, 0x44000
	s_nop 0
	v_addc_co_u32_e32 v49, vcc, 0, v3, vcc
	global_load_dword v85, v[48:49], off nt
	v_add_co_u32_e32 v48, vcc, s12, v2
	s_mov_b32 s12, 0x47000
	s_nop 0
	v_addc_co_u32_e32 v49, vcc, 0, v3, vcc
	global_load_dword v87, v[48:49], off offset:3072 nt
	v_add_co_u32_e32 v48, vcc, s12, v2
	s_mov_b32 s12, 0x4a000
	s_nop 0
	v_addc_co_u32_e32 v49, vcc, 0, v3, vcc
	global_load_dword v89, v[48:49], off offset:2048 nt
	v_add_co_u32_e32 v48, vcc, s12, v2
	s_mov_b32 s12, 0x4d000
	s_nop 0
	v_addc_co_u32_e32 v49, vcc, 0, v3, vcc
	global_load_dword v91, v[48:49], off offset:1024 nt
	v_add_co_u32_e32 v48, vcc, s12, v2
	s_mov_b32 s12, 0x4f000
	s_nop 0
	v_addc_co_u32_e32 v49, vcc, 0, v3, vcc
	global_load_dword v92, v[48:49], off nt
	v_add_co_u32_e32 v48, vcc, s12, v2
	s_mov_b32 s12, 0x52000
	s_nop 0
	v_addc_co_u32_e32 v49, vcc, 0, v3, vcc
	global_load_dword v94, v[48:49], off offset:3072 nt
	v_add_co_u32_e32 v48, vcc, s12, v2
	s_mov_b32 s12, 0x55000
	s_nop 0
	v_addc_co_u32_e32 v49, vcc, 0, v3, vcc
	global_load_dword v95, v[48:49], off offset:2048 nt
	v_add_co_u32_e32 v48, vcc, s12, v2
	s_mov_b32 s12, 0x58000
	s_nop 0
	v_addc_co_u32_e32 v49, vcc, 0, v3, vcc
	global_load_dword v101, v[48:49], off offset:1024 nt
	v_add_co_u32_e32 v48, vcc, s12, v2
	s_mov_b32 s12, 0x5a000
	s_nop 0
	v_addc_co_u32_e32 v49, vcc, 0, v3, vcc
	global_load_dword v66, v[48:49], off nt
; template <int MODE>
; __device__ __forceinline__ void p0_item(const float* W, int K, int N, bf16u* WT, const float* ks, LAS float* scr, int item, int lane) {
;     ...
;     const float* src = W + (size_t)k0 * N + nn;
;     float v[64];
; #pragma unroll
;     for (int kk = 0; kk < 64; ++kk) v[kk] = src[(size_t)kk * N];
;     if (ks) {
; #pragma unroll
;         for (int kk = 0; kk < 64; ++kk) v[kk] *= ks[k0 + kk];
	v_add_co_u32_e32 v48, vcc, s12, v2
	s_mov_b32 s12, 0x5d000
	s_nop 0
	v_addc_co_u32_e32 v49, vcc, 0, v3, vcc
	global_load_dword v68, v[48:49], off offset:3072 nt
	v_add_co_u32_e32 v48, vcc, s12, v2
	s_mov_b32 s12, 0x60000
	s_nop 0
	v_addc_co_u32_e32 v49, vcc, 0, v3, vcc
	global_load_dword v70, v[48:49], off offset:2048 nt
	v_add_co_u32_e32 v48, vcc, s12, v2
	s_mov_b32 s12, 0x63000
	s_nop 0
	v_addc_co_u32_e32 v49, vcc, 0, v3, vcc
	global_load_dword v82, v[48:49], off offset:1024 nt
	v_add_co_u32_e32 v48, vcc, s12, v2
	s_mov_b32 s12, 0x65000
	s_nop 0
	v_addc_co_u32_e32 v49, vcc, 0, v3, vcc
	global_load_dword v86, v[48:49], off nt
	v_add_co_u32_e32 v48, vcc, s12, v2
	s_mov_b32 s12, 0x68000
	s_nop 0
	v_addc_co_u32_e32 v49, vcc, 0, v3, vcc
	global_load_dword v88, v[48:49], off offset:3072 nt
	v_add_co_u32_e32 v48, vcc, s12, v2
	s_mov_b32 s12, 0x6b000
	s_nop 0
	v_addc_co_u32_e32 v49, vcc, 0, v3, vcc
	global_load_dword v90, v[48:49], off offset:2048 nt
	v_add_co_u32_e32 v48, vcc, s12, v2
	s_mov_b32 s12, 0x6e000
	s_nop 0
	v_addc_co_u32_e32 v49, vcc, 0, v3, vcc
	global_load_dword v96, v[48:49], off offset:1024 nt
	v_add_co_u32_e32 v48, vcc, s12, v2
	s_mov_b32 s12, 0x70000
	s_nop 0
	v_addc_co_u32_e32 v49, vcc, 0, v3, vcc
	global_load_dword v97, v[48:49], off nt
	v_add_co_u32_e32 v48, vcc, s12, v2
	s_mov_b32 s12, 0x73000
	s_nop 0
	v_addc_co_u32_e32 v49, vcc, 0, v3, vcc
	global_load_dword v98, v[48:49], off offset:3072 nt
	v_add_co_u32_e32 v48, vcc, s12, v2
	s_mov_b32 s12, 0x76000
	s_nop 0
	v_addc_co_u32_e32 v49, vcc, 0, v3, vcc
	global_load_dword v99, v[48:49], off offset:2048 nt
	v_add_co_u32_e32 v48, vcc, s12, v2
	s_mov_b32 s12, 0x79000
	s_nop 0
	v_addc_co_u32_e32 v49, vcc, 0, v3, vcc
	global_load_dword v100, v[48:49], off offset:1024 nt
	v_add_co_u32_e32 v48, vcc, s12, v2
	s_mov_b32 s12, 0x7b000
	s_nop 0
	v_addc_co_u32_e32 v49, vcc, 0, v3, vcc
	global_load_dword v102, v[48:49], off nt
	v_add_co_u32_e32 v48, vcc, s12, v2
	s_mov_b32 s12, 0x7e000
	s_nop 0
	v_addc_co_u32_e32 v49, vcc, 0, v3, vcc
	global_load_dword v103, v[48:49], off offset:3072 nt
	v_add_co_u32_e32 v48, vcc, s12, v2
	s_mov_b32 s12, 0x81000
	s_nop 0
	v_addc_co_u32_e32 v49, vcc, 0, v3, vcc
	global_load_dword v104, v[48:49], off offset:2048 nt
	v_add_co_u32_e32 v48, vcc, s12, v2
	s_mov_b32 s12, 0x84000
	s_nop 0
	v_addc_co_u32_e32 v49, vcc, 0, v3, vcc
	global_load_dword v111, v[48:49], off offset:1024 nt
	v_add_co_u32_e32 v48, vcc, s12, v2
	s_mov_b32 s12, 0x86000
	s_nop 0
	v_addc_co_u32_e32 v49, vcc, 0, v3, vcc
	global_load_dword v47, v[48:49], off nt
	v_add_co_u32_e32 v48, vcc, s12, v2
	s_mov_b32 s12, 0x89000
	s_nop 0
	v_addc_co_u32_e32 v49, vcc, 0, v3, vcc
	v_add_co_u32_e32 v50, vcc, s12, v2
	s_mov_b32 s12, 0x8c000
	s_nop 0
	v_addc_co_u32_e32 v51, vcc, 0, v3, vcc
	global_load_dword v48, v[48:49], off offset:3072 nt
	s_nop 0
	global_load_dword v49, v[50:51], off offset:2048 nt
	v_add_co_u32_e32 v50, vcc, s12, v2
	s_mov_b32 s12, 0x8f000
	s_nop 0
	v_addc_co_u32_e32 v51, vcc, 0, v3, vcc
	v_add_co_u32_e32 v52, vcc, s12, v2
	s_mov_b32 s12, 0x91000
	s_nop 0
	v_addc_co_u32_e32 v53, vcc, 0, v3, vcc
	global_load_dword v50, v[50:51], off offset:1024 nt
	s_nop 0
	global_load_dword v51, v[52:53], off nt
	v_add_co_u32_e32 v52, vcc, s12, v2
	s_mov_b32 s12, 0x94000
	s_nop 0
	v_addc_co_u32_e32 v53, vcc, 0, v3, vcc
	v_add_co_u32_e32 v54, vcc, s12, v2
	s_mov_b32 s12, 0x97000
	s_nop 0
	v_addc_co_u32_e32 v55, vcc, 0, v3, vcc
	global_load_dword v52, v[52:53], off offset:3072 nt
	s_nop 0
	global_load_dword v53, v[54:55], off offset:2048 nt
	v_add_co_u32_e32 v54, vcc, s12, v2
	s_mov_b32 s12, 0x9a000
	s_nop 0
	v_addc_co_u32_e32 v55, vcc, 0, v3, vcc
	v_add_co_u32_e32 v56, vcc, s12, v2
	s_mov_b32 s12, 0x9c000
	s_nop 0
	v_addc_co_u32_e32 v57, vcc, 0, v3, vcc
	global_load_dword v54, v[54:55], off offset:1024 nt
	s_nop 0
	global_load_dword v55, v[56:57], off nt
	v_add_co_u32_e32 v56, vcc, s12, v2
	s_mov_b32 s12, 0x9f000
	s_nop 0
	v_addc_co_u32_e32 v57, vcc, 0, v3, vcc
	v_add_co_u32_e32 v58, vcc, s12, v2
	s_mov_b32 s12, 0xa2000
	s_nop 0
	v_addc_co_u32_e32 v59, vcc, 0, v3, vcc
	global_load_dword v56, v[56:57], off offset:3072 nt
	s_nop 0
	global_load_dword v57, v[58:59], off offset:2048 nt
	v_add_co_u32_e32 v58, vcc, s12, v2
	s_mov_b32 s12, 0xa5000
	s_nop 0
	v_addc_co_u32_e32 v59, vcc, 0, v3, vcc
	v_add_co_u32_e32 v60, vcc, s12, v2
	s_mov_b32 s12, 0xa7000
	s_nop 0
	v_addc_co_u32_e32 v61, vcc, 0, v3, vcc
	global_load_dword v58, v[58:59], off offset:1024 nt
	s_nop 0
	global_load_dword v59, v[60:61], off nt
	v_add_co_u32_e32 v60, vcc, s12, v2
	s_mov_b32 s12, 0xaa000
	s_nop 0
	v_addc_co_u32_e32 v61, vcc, 0, v3, vcc
	v_add_co_u32_e32 v74, vcc, s12, v2
	s_mov_b32 s12, 0xad000
	s_nop 0
	v_addc_co_u32_e32 v75, vcc, 0, v3, vcc
	v_add_co_u32_e32 v2, vcc, s12, v2
	s_lshl_b32 s12, s4, 8
	s_nop 0
	v_addc_co_u32_e32 v3, vcc, 0, v3, vcc
	v_mov_b32_e32 v120, s12
	global_load_dword v60, v[60:61], off offset:3072 nt
	s_nop 0
	global_load_dword v62, v[2:3], off offset:1024 nt
	global_load_dword v61, v[74:75], off offset:2048 nt
	global_load_dwordx4 v[106:109], v120, s[18:19] offset:48 nt
	global_load_dwordx4 v[112:115], v120, s[18:19] offset:32 nt
	global_load_dwordx4 v[116:119], v120, s[18:19] offset:16 nt
	s_nop 0
	global_load_dwordx4 v[74:77], v120, s[18:19] nt
	s_waitcnt vmcnt(0)
; template <int MODE>
; __device__ __forceinline__ void p0_item(const float* W, int K, int N, bf16u* WT, const float* ks, LAS float* scr, int item, int lane) {
;     ...
;     if (ks) {
; #pragma unroll
;         for (int kk = 0; kk < 64; ++kk) v[kk] *= ks[k0 + kk];
;     }
; #pragma unroll
;     for (int kk = 0; kk < 64; ++kk) scr[kk * 65 + lane] = v[kk];
;     asm volatile("s_waitcnt lgkmcnt(0)" ::: "memory");
	v_mul_f32_e32 v63, v63, v112
	v_mul_f32_e32 v65, v65, v113
	v_mul_f32_e32 v71, v4, v74
	v_mul_f32_e32 v73, v5, v75
	v_mul_f32_e32 v74, v6, v76
	v_mul_f32_e32 v76, v7, v77
	v_mul_f32_e32 v75, v8, v116
	v_mul_f32_e32 v77, v9, v117
	v_mul_f32_e32 v67, v67, v114
	v_mul_f32_e32 v80, v69, v115
	v_mul_f32_e32 v69, v72, v106
	v_mul_f32_e32 v72, v81, v107
	v_mul_f32_e32 v81, v83, v108
	v_mul_f32_e32 v83, v93, v109
	global_load_dwordx4 v[2:5], v120, s[18:19] offset:112 nt
	global_load_dwordx4 v[6:9], v120, s[18:19] offset:96 nt
	global_load_dwordx4 v[112:115], v120, s[18:19] offset:80 nt
	global_load_dwordx4 v[106:109], v120, s[18:19] offset:64 nt
	v_mul_f32_e32 v78, v11, v118
	v_mul_f32_e32 v79, v16, v119
	s_waitcnt vmcnt(2)
	v_mul_f32_e32 v91, v91, v9
	s_waitcnt vmcnt(1)
	v_mul_f32_e32 v110, v84, v115
	s_waitcnt vmcnt(0)
	v_mul_f32_e32 v93, v10, v106
	v_mul_f32_e32 v105, v12, v107
	v_mul_f32_e32 v106, v13, v108
	v_mul_f32_e32 v108, v14, v109
	v_mul_f32_e32 v107, v15, v112
	v_mul_f32_e32 v109, v17, v113
	v_mul_f32_e32 v84, v85, v6
	v_mul_f32_e32 v85, v87, v7
	v_mul_f32_e32 v87, v89, v8
	v_mul_f32_e32 v89, v92, v2
	v_mul_f32_e32 v92, v94, v3
	v_mul_f32_e32 v94, v95, v4
	v_mul_f32_e32 v95, v101, v5
	global_load_dwordx4 v[2:5], v120, s[18:19] offset:176 nt
	global_load_dwordx4 v[6:9], v120, s[18:19] offset:160 nt
	global_load_dwordx4 v[10:13], v120, s[18:19] offset:144 nt
	global_load_dwordx4 v[14:17], v120, s[18:19] offset:128 nt
	v_mul_f32_e32 v64, v64, v114
	s_waitcnt vmcnt(3)
	v_mul_f32_e32 v101, v102, v2
	s_waitcnt vmcnt(2)
	v_mul_f32_e32 v97, v97, v6
	s_waitcnt vmcnt(1)
	v_mul_f32_e32 v86, v86, v10
	s_waitcnt vmcnt(0)
	v_mul_f32_e32 v66, v66, v14
	v_mul_f32_e32 v68, v68, v15
	v_mul_f32_e32 v70, v70, v16
	v_mul_f32_e32 v82, v82, v17
	v_mul_f32_e32 v88, v88, v11
	v_mul_f32_e32 v90, v90, v12
	v_mul_f32_e32 v96, v96, v13
	v_mul_f32_e32 v98, v98, v7
	v_mul_f32_e32 v99, v99, v8
	v_mul_f32_e32 v100, v100, v9
	v_mul_f32_e32 v102, v103, v3
	v_mul_f32_e32 v103, v104, v4
	v_mul_f32_e32 v104, v111, v5
	global_load_dwordx4 v[2:5], v120, s[18:19] offset:240 nt
	global_load_dwordx4 v[6:9], v120, s[18:19] offset:224 nt
	global_load_dwordx4 v[10:13], v120, s[18:19] offset:208 nt
	global_load_dwordx4 v[14:17], v120, s[18:19] offset:192 nt
	ds_write2_b32 v31, v71, v73 offset1:65
	ds_write2_b32 v31, v74, v76 offset0:130 offset1:195
	s_waitcnt vmcnt(3)
	v_mul_f32_e32 v2, v59, v2
	s_waitcnt vmcnt(2)
	v_mul_f32_e32 v6, v55, v6
	s_waitcnt vmcnt(1)
	v_mul_f32_e32 v10, v51, v10
	s_waitcnt vmcnt(0)
	v_mul_f32_e32 v14, v47, v14
	v_add_u32_e32 v47, 0x400, v31
	ds_write2_b32 v47, v75, v77 offset0:4 offset1:69
	ds_write2_b32 v47, v78, v79 offset0:134 offset1:199
	v_add_u32_e32 v47, 0x800, v31
	ds_write2_b32 v47, v63, v65 offset0:8 offset1:73
	ds_write2_b32 v47, v67, v80 offset0:138 offset1:203
	v_add_u32_e32 v47, 0xc00, v31
	ds_write2_b32 v47, v69, v72 offset0:12 offset1:77
	ds_write2_b32 v47, v81, v83 offset0:142 offset1:207
	v_add_u32_e32 v47, 0x1000, v31
	ds_write2_b32 v47, v93, v105 offset0:16 offset1:81
	ds_write2_b32 v47, v106, v108 offset0:146 offset1:211
	v_add_u32_e32 v47, 0x1400, v31
	ds_write2_b32 v47, v107, v109 offset0:20 offset1:85
	ds_write2_b32 v47, v64, v110 offset0:150 offset1:215
	v_add_u32_e32 v47, 0x1800, v31
	ds_write2_b32 v47, v84, v85 offset0:24 offset1:89
	ds_write2_b32 v47, v87, v91 offset0:154 offset1:219
	v_add_u32_e32 v47, 0x1c00, v31
	ds_write2_b32 v47, v89, v92 offset0:28 offset1:93
	ds_write2_b32 v47, v94, v95 offset0:158 offset1:223
	v_add_u32_e32 v47, 0x2000, v31
	ds_write2_b32 v47, v66, v68 offset0:32 offset1:97
	ds_write2_b32 v47, v70, v82 offset0:162 offset1:227
	v_add_u32_e32 v47, 0x2400, v31
	ds_write2_b32 v47, v86, v88 offset0:36 offset1:101
	ds_write2_b32 v47, v90, v96 offset0:166 offset1:231
	v_add_u32_e32 v47, 0x2800, v31
	ds_write2_b32 v47, v97, v98 offset0:40 offset1:105
	ds_write2_b32 v47, v99, v100 offset0:170 offset1:235
	v_add_u32_e32 v47, 0x2c00, v31
	v_mul_f32_e32 v15, v48, v15
	ds_write2_b32 v47, v101, v102 offset0:44 offset1:109
	ds_write2_b32 v47, v103, v104 offset0:174 offset1:239
	v_add_u32_e32 v47, 0x3000, v31
	v_mul_f32_e32 v16, v49, v16
	v_mul_f32_e32 v17, v50, v17
	v_mul_f32_e32 v11, v52, v11
	ds_write2_b32 v47, v14, v15 offset0:48 offset1:113
	ds_write2_b32 v47, v16, v17 offset0:178 offset1:243
	v_add_u32_e32 v14, 0x3400, v31
	v_mul_f32_e32 v12, v53, v12
	v_mul_f32_e32 v13, v54, v13
	v_mul_f32_e32 v7, v56, v7
	ds_write2_b32 v14, v10, v11 offset0:52 offset1:117
	ds_write2_b32 v14, v12, v13 offset0:182 offset1:247
	v_add_u32_e32 v10, 0x3800, v31
	v_mul_f32_e32 v8, v57, v8
	v_mul_f32_e32 v9, v58, v9
	v_mul_f32_e32 v3, v60, v3
	ds_write2_b32 v10, v6, v7 offset0:56 offset1:121
	ds_write2_b32 v10, v8, v9 offset0:186 offset1:251
	v_add_u32_e32 v6, 0x3c00, v31
	v_mul_f32_e32 v4, v61, v4
	v_mul_f32_e32 v5, v62, v5
	ds_write2_b32 v6, v2, v3 offset0:60 offset1:125
	ds_write2_b32 v6, v4, v5 offset0:190 offset1:255
	s_waitcnt lgkmcnt(0)
; #define LAS __attribute__((address_space(3)))
; __device__ __forceinline__ unsigned pk2(float lo, float hi) { return pg8::cvt_pk_bf16(lo, hi); }
; template <int MODE>
; __device__ __forceinline__ void p0_item(const float* W, int K, int N, bf16u* WT, const float* ks, LAS float* scr, int item, int lane) {
;     ...
;     const int c = lane & 7;
; #pragma unroll
;     for (int j = 0; j < 8; ++j) { const int n = (lane >> 3) + 8 * j; const LAS float* s = scr + (8 * c) * 65 + n;
;         v4u o; o.x = pk2(s[0 * 65], s[1 * 65]); o.y = pk2(s[2 * 65], s[3 * 65]); o.z = pk2(s[4 * 65], s[5 * 65]); o.w = pk2(s[6 * 65], s[7 * 65]);
;         *(v4u*)(WT + (size_t)(drow + n) * K + k0 + 8 * c) = o; }
;     asm volatile("s_waitcnt lgkmcnt(0)" ::: "memory");
	v_add_u32_e32 v47, 0x400, v33
	ds_read2_b32 v[8:9], v33 offset0:65 offset1:73
	ds_read2_b32 v[10:11], v33 offset1:8
	ds_read2_b32 v[12:13], v33 offset0:130 offset1:138
	ds_read2_b32 v[14:15], v33 offset0:195 offset1:203
	ds_read2_b32 v[16:17], v47 offset0:4 offset1:12
	ds_read2_b32 v[48:49], v47 offset0:69 offset1:77
	ds_read2_b32 v[50:51], v47 offset0:134 offset1:142
	ds_read2_b32 v[52:53], v47 offset0:199 offset1:207
	v_or_b32_e32 v54, 0x80, v0
	v_ashrrev_i32_e32 v55, 31, v54
	v_lshl_add_u64 v[2:3], v[22:23], 0, s[90:91]
	v_lshlrev_b64 v[54:55], 11, v[54:55]
	s_waitcnt lgkmcnt(6)
	v_cvt_pk_bf16_f32 v4, v10, v8
	s_waitcnt lgkmcnt(4)
	v_cvt_pk_bf16_f32 v5, v12, v14
	s_waitcnt lgkmcnt(2)
	v_cvt_pk_bf16_f32 v6, v16, v48
	s_waitcnt lgkmcnt(0)
	v_cvt_pk_bf16_f32 v7, v50, v52
	v_lshl_add_u64 v[54:55], v[2:3], 0, v[54:55]
	v_or_b32_e32 v8, 0x88, v0
	global_store_dwordx4 v[54:55], v[4:7], off sc1
	v_or_b32_e32 v54, 0x90, v0
	v_ashrrev_i32_e32 v55, 31, v54
	v_cvt_pk_bf16_f32 v4, v11, v9
	v_ashrrev_i32_e32 v9, 31, v8
	v_lshlrev_b64 v[8:9], 11, v[8:9]
	v_cvt_pk_bf16_f32 v5, v13, v15
	v_cvt_pk_bf16_f32 v6, v17, v49
	v_cvt_pk_bf16_f32 v7, v51, v53
	v_lshl_add_u64 v[8:9], v[2:3], 0, v[8:9]
	global_store_dwordx4 v[8:9], v[4:7], off sc1
	ds_read2_b32 v[8:9], v33 offset0:16 offset1:24
	ds_read2_b32 v[10:11], v33 offset0:81 offset1:89
	ds_read2_b32 v[12:13], v33 offset0:146 offset1:154
	ds_read2_b32 v[14:15], v33 offset0:211 offset1:219
	ds_read2_b32 v[16:17], v47 offset0:20 offset1:28
	ds_read2_b32 v[48:49], v47 offset0:85 offset1:93
	ds_read2_b32 v[50:51], v47 offset0:150 offset1:158
	ds_read2_b32 v[52:53], v47 offset0:215 offset1:223
	v_lshlrev_b64 v[54:55], 11, v[54:55]
	s_waitcnt lgkmcnt(6)
	v_cvt_pk_bf16_f32 v4, v8, v10
	s_waitcnt lgkmcnt(4)
	v_cvt_pk_bf16_f32 v5, v12, v14
	s_waitcnt lgkmcnt(2)
	v_cvt_pk_bf16_f32 v6, v16, v48
	s_waitcnt lgkmcnt(0)
	v_cvt_pk_bf16_f32 v7, v50, v52
	v_lshl_add_u64 v[54:55], v[2:3], 0, v[54:55]
	v_or_b32_e32 v8, 0x98, v0
	global_store_dwordx4 v[54:55], v[4:7], off sc1
	v_or_b32_e32 v54, 0xa0, v0
	v_ashrrev_i32_e32 v55, 31, v54
	v_cvt_pk_bf16_f32 v4, v9, v11
	v_ashrrev_i32_e32 v9, 31, v8
	v_lshlrev_b64 v[8:9], 11, v[8:9]
	v_cvt_pk_bf16_f32 v5, v13, v15
	v_cvt_pk_bf16_f32 v6, v17, v49
	v_cvt_pk_bf16_f32 v7, v51, v53
	v_lshl_add_u64 v[8:9], v[2:3], 0, v[8:9]
	global_store_dwordx4 v[8:9], v[4:7], off sc1
	ds_read2_b32 v[8:9], v33 offset0:32 offset1:40
	ds_read2_b32 v[10:11], v33 offset0:97 offset1:105
	ds_read2_b32 v[12:13], v33 offset0:162 offset1:170
	ds_read2_b32 v[14:15], v33 offset0:227 offset1:235
	ds_read2_b32 v[16:17], v47 offset0:36 offset1:44
	ds_read2_b32 v[48:49], v47 offset0:101 offset1:109
	ds_read2_b32 v[50:51], v47 offset0:166 offset1:174
	ds_read2_b32 v[52:53], v47 offset0:231 offset1:239
	v_lshlrev_b64 v[54:55], 11, v[54:55]
	s_waitcnt lgkmcnt(6)
	v_cvt_pk_bf16_f32 v4, v8, v10
	s_waitcnt lgkmcnt(4)
	v_cvt_pk_bf16_f32 v5, v12, v14
	s_waitcnt lgkmcnt(2)
	v_cvt_pk_bf16_f32 v6, v16, v48
	s_waitcnt lgkmcnt(0)
	v_cvt_pk_bf16_f32 v7, v50, v52
	v_lshl_add_u64 v[54:55], v[2:3], 0, v[54:55]
	v_or_b32_e32 v8, 0xa8, v0
	global_store_dwordx4 v[54:55], v[4:7], off sc1
	v_or_b32_e32 v54, 0xb0, v0
	v_ashrrev_i32_e32 v55, 31, v54
	v_cvt_pk_bf16_f32 v4, v9, v11
	v_ashrrev_i32_e32 v9, 31, v8
	v_lshlrev_b64 v[8:9], 11, v[8:9]
	v_cvt_pk_bf16_f32 v5, v13, v15
	v_cvt_pk_bf16_f32 v6, v17, v49
	v_cvt_pk_bf16_f32 v7, v51, v53
	v_lshl_add_u64 v[8:9], v[2:3], 0, v[8:9]
	global_store_dwordx4 v[8:9], v[4:7], off sc1
	ds_read2_b32 v[8:9], v33 offset0:48 offset1:56
	ds_read2_b32 v[10:11], v33 offset0:113 offset1:121
	ds_read2_b32 v[12:13], v33 offset0:178 offset1:186
	ds_read2_b32 v[14:15], v33 offset0:243 offset1:251
	ds_read2_b32 v[16:17], v47 offset0:52 offset1:60
	ds_read2_b32 v[48:49], v47 offset0:117 offset1:125
	ds_read2_b32 v[50:51], v47 offset0:182 offset1:190
	ds_read2_b32 v[52:53], v47 offset0:247 offset1:255
	v_lshlrev_b64 v[54:55], 11, v[54:55]
	s_waitcnt lgkmcnt(6)
	v_cvt_pk_bf16_f32 v4, v8, v10
	s_waitcnt lgkmcnt(4)
	v_cvt_pk_bf16_f32 v5, v12, v14
	s_waitcnt lgkmcnt(2)
	v_cvt_pk_bf16_f32 v6, v16, v48
	s_waitcnt lgkmcnt(0)
	v_cvt_pk_bf16_f32 v7, v50, v52
	v_lshl_add_u64 v[54:55], v[2:3], 0, v[54:55]
	v_or_b32_e32 v8, 0xb8, v0
	global_store_dwordx4 v[54:55], v[4:7], off sc1
	s_nop 1
	v_cvt_pk_bf16_f32 v4, v9, v11
	v_ashrrev_i32_e32 v9, 31, v8
	v_lshlrev_b64 v[8:9], 11, v[8:9]
	v_cvt_pk_bf16_f32 v5, v13, v15
	v_cvt_pk_bf16_f32 v6, v17, v49
	v_cvt_pk_bf16_f32 v7, v51, v53
	v_lshl_add_u64 v[2:3], v[2:3], 0, v[8:9]
	global_store_dwordx4 v[2:3], v[4:7], off sc1
	s_waitcnt lgkmcnt(0)

; template <int MODE>
; __device__ __forceinline__ void p0_item(const float* W, int K, int N, bf16u* WT, const float* ks, LAS float* scr, int item, int lane) {
;     const int nblk = N / 64, kb = item / nblk, nb = item - kb * nblk, k0 = 64 * kb, n0 = 64 * nb;
;     int nn = n0 + lane;
;     if (MODE == 1) {
;         if (nn < 2048) { const int p = nn & 63; if (p < 16) nn = (nn & ~15) | (p & 3) | ((p & 4) << 1) | ((p & 8) >> 1); }
;         else if (nn >= 4096) { const int sec = nn >= 6144 ? 6144 : 4096, r = nn - sec, q = r & 255; nn = sec + ((q >> 7) << 10) + 128 * (r >> 8) + (q & 127); }
;     }
;     int drow = n0;
;     if (MODE == 2) drow = 256 * (n0 >> 7) + (n0 & 127);
;     if (MODE == 3) drow = 256 * (n0 >> 7) + 128 + (n0 & 127);
;     const float* src = W + (size_t)k0 * N + nn;
;     float v[64];
; #pragma unroll
;     for (int kk = 0; kk < 64; ++kk) v[kk] = src[(size_t)kk * N];
.LBB0_609:
	s_andn2_b64 vcc, exec, s[16:17]
	s_cbranch_vccnz .LBB0_611
	s_and_b32 s4, 0xffff, s56
	s_mul_hi_u32 s4, s4, 0x5d1745e
	s_mul_i32 s12, s4, 0x1600
	s_mulk_i32 s4, 0xb00
	v_subrev_u32_e32 v0, s4, v43
	s_mul_i32 s4, s55, 0xba2f
	s_add_i32 s4, s4, 0x2000140
	s_lshr_b32 s4, s4, 21
	s_add_i32 s17, s52, s59
	s_sub_i32 s16, s54, s12
	s_add_i32 s17, s17, 0xfffd4000
	s_mul_i32 s12, s4, 0xb0000
	v_add_u32_e32 v2, s59, v0
	s_add_u32 s20, s37, s12
	s_addc_u32 s21, s40, 0
	v_ashrrev_i32_e32 v3, 31, v2
	v_lshl_add_u64 v[2:3], v[2:3], 2, s[20:21]
	v_add_co_u32_e32 v6, vcc, s61, v2
	s_movk_i32 s12, 0x5000
	s_nop 0
	v_addc_co_u32_e32 v7, vcc, 0, v3, vcc
	global_load_dword v5, v[6:7], off offset:3072 nt
	v_add_co_u32_e32 v6, vcc, s12, v2
	s_mov_b32 s12, 0xb000
	s_nop 0
	v_addc_co_u32_e32 v7, vcc, 0, v3, vcc
	v_add_co_u32_e32 v8, vcc, s88, v2
	global_load_dword v4, v[2:3], off nt
	s_nop 0
	v_addc_co_u32_e32 v9, vcc, 0, v3, vcc
	global_load_dword v6, v[6:7], off offset:2048 nt
	s_lshl_b32 s90, s4, 7
	global_load_dword v7, v[8:9], off offset:1024 nt
	v_add_co_u32_e32 v8, vcc, s12, v2
	s_mov_b32 s12, 0xd000
	s_nop 0
	v_addc_co_u32_e32 v9, vcc, 0, v3, vcc
	v_add_co_u32_e32 v10, vcc, s12, v2
	s_mov_b32 s12, 0x10000
	s_nop 0
	v_addc_co_u32_e32 v11, vcc, 0, v3, vcc
	global_load_dword v8, v[8:9], off nt
	s_nop 0
	global_load_dword v9, v[10:11], off offset:3072 nt
	v_add_co_u32_e32 v10, vcc, s12, v2
	s_mov_b32 s12, 0x13000
	s_nop 0
	v_addc_co_u32_e32 v11, vcc, 0, v3, vcc
	v_add_co_u32_e32 v12, vcc, s12, v2
	s_mov_b32 s12, 0x16000
	s_nop 0
	v_addc_co_u32_e32 v13, vcc, 0, v3, vcc
	global_load_dword v60, v[12:13], off offset:1024 nt
	v_add_co_u32_e32 v12, vcc, s12, v2
	global_load_dword v11, v[10:11], off offset:2048 nt
	s_nop 0
	v_addc_co_u32_e32 v13, vcc, 0, v3, vcc
	global_load_dword v62, v[12:13], off nt
	v_add_co_u32_e32 v12, vcc, s5, v2
	s_mov_b32 s12, 0x1b000
	s_nop 0
	v_addc_co_u32_e32 v13, vcc, 0, v3, vcc
	global_load_dword v64, v[12:13], off offset:3072 nt
	v_add_co_u32_e32 v12, vcc, s12, v2
	s_mov_b32 s12, 0x1e000
	s_nop 0
	v_addc_co_u32_e32 v13, vcc, 0, v3, vcc
	global_load_dword v66, v[12:13], off offset:2048 nt
	v_add_co_u32_e32 v12, vcc, s12, v2
	s_mov_b32 s12, 0x21000
	s_nop 0
	v_addc_co_u32_e32 v13, vcc, 0, v3, vcc
	global_load_dword v68, v[12:13], off offset:1024 nt
	v_add_co_u32_e32 v12, vcc, s12, v2
	s_mov_b32 s12, 0x23000
	s_nop 0
	v_addc_co_u32_e32 v13, vcc, 0, v3, vcc
	global_load_dword v70, v[12:13], off nt
	v_add_co_u32_e32 v12, vcc, s12, v2
	s_mov_b32 s12, 0x26000
	s_nop 0
	v_addc_co_u32_e32 v13, vcc, 0, v3, vcc
	global_load_dword v73, v[12:13], off offset:3072 nt
	v_add_co_u32_e32 v12, vcc, s12, v2
	s_mov_b32 s12, 0x29000
	s_nop 0
	v_addc_co_u32_e32 v13, vcc, 0, v3, vcc
	global_load_dword v84, v[12:13], off offset:2048 nt
	v_add_co_u32_e32 v12, vcc, s12, v2
	s_mov_b32 s12, 0x2c000
	s_nop 0
	v_addc_co_u32_e32 v13, vcc, 0, v3, vcc
	global_load_dword v91, v[12:13], off offset:1024 nt
	v_add_co_u32_e32 v12, vcc, s12, v2
	s_mov_b32 s12, 0x2e000
	s_nop 0
	v_addc_co_u32_e32 v13, vcc, 0, v3, vcc
	global_load_dword v10, v[12:13], off nt
	v_add_co_u32_e32 v12, vcc, s12, v2
	s_mov_b32 s12, 0x31000
	s_nop 0
	v_addc_co_u32_e32 v13, vcc, 0, v3, vcc
	v_add_co_u32_e32 v14, vcc, s12, v2
	s_mov_b32 s12, 0x34000
	s_nop 0
	v_addc_co_u32_e32 v15, vcc, 0, v3, vcc
	global_load_dword v12, v[12:13], off offset:3072 nt
	s_nop 0
	global_load_dword v13, v[14:15], off offset:2048 nt
	v_add_co_u32_e32 v14, vcc, s12, v2
	s_mov_b32 s12, 0x37000
	s_nop 0
	v_addc_co_u32_e32 v15, vcc, 0, v3, vcc
	global_load_dword v58, v[14:15], off offset:1024 nt
	v_add_co_u32_e32 v14, vcc, s12, v2
	s_mov_b32 s12, 0x39000
	s_nop 0
	v_addc_co_u32_e32 v15, vcc, 0, v3, vcc
	global_load_dword v59, v[14:15], off nt
	v_add_co_u32_e32 v14, vcc, s12, v2
	s_mov_b32 s12, 0x3c000
	s_nop 0
	v_addc_co_u32_e32 v15, vcc, 0, v3, vcc
	global_load_dword v61, v[14:15], off offset:3072 nt
	v_add_co_u32_e32 v14, vcc, s12, v2
	s_mov_b32 s12, 0x3f000
	s_nop 0
	v_addc_co_u32_e32 v15, vcc, 0, v3, vcc
	global_load_dword v63, v[14:15], off offset:2048 nt
	v_add_co_u32_e32 v14, vcc, s12, v2
	s_mov_b32 s12, 0x42000
	s_nop 0
	v_addc_co_u32_e32 v15, vcc, 0, v3, vcc
	global_load_dword v72, v[14:15], off offset:1024 nt
	v_add_co_u32_e32 v14, vcc, s12, v2
	s_mov_b32 s12, 0x44000
	s_nop 0
	v_addc_co_u32_e32 v15, vcc, 0, v3, vcc
	global_load_dword v75, v[14:15], off nt
	v_add_co_u32_e32 v14, vcc, s12, v2
	s_mov_b32 s12, 0x47000
	s_nop 0
	v_addc_co_u32_e32 v15, vcc, 0, v3, vcc
	global_load_dword v85, v[14:15], off offset:3072 nt
	v_add_co_u32_e32 v14, vcc, s12, v2
	s_mov_b32 s12, 0x4a000
	s_nop 0
	v_addc_co_u32_e32 v15, vcc, 0, v3, vcc
	global_load_dword v87, v[14:15], off offset:2048 nt
	v_add_co_u32_e32 v14, vcc, s12, v2
	s_mov_b32 s12, 0x4d000
	s_nop 0
	v_addc_co_u32_e32 v15, vcc, 0, v3, vcc
	global_load_dword v89, v[14:15], off offset:1024 nt
	v_add_co_u32_e32 v14, vcc, s12, v2
	s_mov_b32 s12, 0x4f000
	s_nop 0
	v_addc_co_u32_e32 v15, vcc, 0, v3, vcc
	global_load_dword v90, v[14:15], off nt
	v_add_co_u32_e32 v14, vcc, s12, v2
	s_mov_b32 s12, 0x52000
	s_nop 0
	v_addc_co_u32_e32 v15, vcc, 0, v3, vcc
	global_load_dword v92, v[14:15], off offset:3072 nt
	v_add_co_u32_e32 v14, vcc, s12, v2
	s_mov_b32 s12, 0x55000
	s_nop 0
	v_addc_co_u32_e32 v15, vcc, 0, v3, vcc
	global_load_dword v93, v[14:15], off offset:2048 nt
	v_add_co_u32_e32 v14, vcc, s12, v2
	s_mov_b32 s12, 0x58000
	s_nop 0
	v_addc_co_u32_e32 v15, vcc, 0, v3, vcc
	global_load_dword v99, v[14:15], off offset:1024 nt
	v_add_co_u32_e32 v14, vcc, s12, v2
	s_mov_b32 s12, 0x5a000
	s_nop 0
	v_addc_co_u32_e32 v15, vcc, 0, v3, vcc
	global_load_dword v65, v[14:15], off nt
; template <int MODE>
; __device__ __forceinline__ void p0_item(const float* W, int K, int N, bf16u* WT, const float* ks, LAS float* scr, int item, int lane) {
;     ...
;     const float* src = W + (size_t)k0 * N + nn;
;     float v[64];
; #pragma unroll
;     for (int kk = 0; kk < 64; ++kk) v[kk] = src[(size_t)kk * N];
;     if (ks) {
; #pragma unroll
;         for (int kk = 0; kk < 64; ++kk) v[kk] *= ks[k0 + kk];
	v_add_co_u32_e32 v14, vcc, s12, v2
	s_mov_b32 s12, 0x5d000
	s_nop 0
	v_addc_co_u32_e32 v15, vcc, 0, v3, vcc
	global_load_dword v67, v[14:15], off offset:3072 nt
	v_add_co_u32_e32 v14, vcc, s12, v2
	s_mov_b32 s12, 0x60000
	s_nop 0
	v_addc_co_u32_e32 v15, vcc, 0, v3, vcc
	global_load_dword v69, v[14:15], off offset:2048 nt
	v_add_co_u32_e32 v14, vcc, s12, v2
	s_mov_b32 s12, 0x63000
	s_nop 0
	v_addc_co_u32_e32 v15, vcc, 0, v3, vcc
	global_load_dword v71, v[14:15], off offset:1024 nt
	v_add_co_u32_e32 v14, vcc, s12, v2
	s_mov_b32 s12, 0x65000
	s_nop 0
	v_addc_co_u32_e32 v15, vcc, 0, v3, vcc
	global_load_dword v83, v[14:15], off nt
	v_add_co_u32_e32 v14, vcc, s12, v2
	s_mov_b32 s12, 0x68000
	s_nop 0
	v_addc_co_u32_e32 v15, vcc, 0, v3, vcc
	global_load_dword v86, v[14:15], off offset:3072 nt
	v_add_co_u32_e32 v14, vcc, s12, v2
	s_mov_b32 s12, 0x6b000
	s_nop 0
	v_addc_co_u32_e32 v15, vcc, 0, v3, vcc
	global_load_dword v88, v[14:15], off offset:2048 nt
	v_add_co_u32_e32 v14, vcc, s12, v2
	s_mov_b32 s12, 0x6e000
	s_nop 0
	v_addc_co_u32_e32 v15, vcc, 0, v3, vcc
	global_load_dword v94, v[14:15], off offset:1024 nt
	v_add_co_u32_e32 v14, vcc, s12, v2
	s_mov_b32 s12, 0x70000
	s_nop 0
	v_addc_co_u32_e32 v15, vcc, 0, v3, vcc
	global_load_dword v95, v[14:15], off nt
	v_add_co_u32_e32 v14, vcc, s12, v2
	s_mov_b32 s12, 0x73000
	s_nop 0
	v_addc_co_u32_e32 v15, vcc, 0, v3, vcc
	global_load_dword v96, v[14:15], off offset:3072 nt
	v_add_co_u32_e32 v14, vcc, s12, v2
	s_mov_b32 s12, 0x76000
	s_nop 0
	v_addc_co_u32_e32 v15, vcc, 0, v3, vcc
	global_load_dword v97, v[14:15], off offset:2048 nt
	v_add_co_u32_e32 v14, vcc, s12, v2
	s_mov_b32 s12, 0x79000
	s_nop 0
	v_addc_co_u32_e32 v15, vcc, 0, v3, vcc
	global_load_dword v98, v[14:15], off offset:1024 nt
	v_add_co_u32_e32 v14, vcc, s12, v2
	s_mov_b32 s12, 0x7b000
	s_nop 0
	v_addc_co_u32_e32 v15, vcc, 0, v3, vcc
	global_load_dword v100, v[14:15], off nt
	v_add_co_u32_e32 v14, vcc, s12, v2
	s_mov_b32 s12, 0x7e000
	s_nop 0
	v_addc_co_u32_e32 v15, vcc, 0, v3, vcc
	global_load_dword v101, v[14:15], off offset:3072 nt
	v_add_co_u32_e32 v14, vcc, s12, v2
	s_mov_b32 s12, 0x81000
	s_nop 0
	v_addc_co_u32_e32 v15, vcc, 0, v3, vcc
	global_load_dword v102, v[14:15], off offset:2048 nt
	v_add_co_u32_e32 v14, vcc, s12, v2
	s_mov_b32 s12, 0x84000
	s_nop 0
	v_addc_co_u32_e32 v15, vcc, 0, v3, vcc
	global_load_dword v106, v[14:15], off offset:1024 nt
	v_add_co_u32_e32 v14, vcc, s12, v2
	s_mov_b32 s12, 0x86000
	s_nop 0
	v_addc_co_u32_e32 v15, vcc, 0, v3, vcc
	global_load_dword v0, v[14:15], off nt
	v_add_co_u32_e32 v14, vcc, s12, v2
	s_mov_b32 s12, 0x89000
	s_nop 0
	v_addc_co_u32_e32 v15, vcc, 0, v3, vcc
	v_add_co_u32_e32 v16, vcc, s12, v2
	s_mov_b32 s12, 0x8c000
	s_nop 0
	v_addc_co_u32_e32 v17, vcc, 0, v3, vcc
	global_load_dword v14, v[14:15], off offset:3072 nt
	s_nop 0
	global_load_dword v15, v[16:17], off offset:2048 nt
	v_add_co_u32_e32 v16, vcc, s12, v2
	s_mov_b32 s12, 0x8f000
	s_nop 0
	v_addc_co_u32_e32 v17, vcc, 0, v3, vcc
	v_add_co_u32_e32 v48, vcc, s12, v2
	s_mov_b32 s12, 0x91000
	s_nop 0
	v_addc_co_u32_e32 v49, vcc, 0, v3, vcc
	global_load_dword v16, v[16:17], off offset:1024 nt
	s_nop 0
	global_load_dword v17, v[48:49], off nt
	v_add_co_u32_e32 v48, vcc, s12, v2
	s_mov_b32 s12, 0x94000
	s_nop 0
	v_addc_co_u32_e32 v49, vcc, 0, v3, vcc
	global_load_dword v47, v[48:49], off offset:3072 nt
	v_add_co_u32_e32 v48, vcc, s12, v2
	s_mov_b32 s12, 0x97000
	s_nop 0
	v_addc_co_u32_e32 v49, vcc, 0, v3, vcc
	v_add_co_u32_e32 v50, vcc, s12, v2
	s_mov_b32 s12, 0x9a000
	s_nop 0
	v_addc_co_u32_e32 v51, vcc, 0, v3, vcc
	global_load_dword v48, v[48:49], off offset:2048 nt
	s_nop 0
	global_load_dword v49, v[50:51], off offset:1024 nt
	v_add_co_u32_e32 v50, vcc, s12, v2
	s_mov_b32 s12, 0x9c000
	s_nop 0
	v_addc_co_u32_e32 v51, vcc, 0, v3, vcc
	v_add_co_u32_e32 v52, vcc, s12, v2
	s_mov_b32 s12, 0x9f000
	s_nop 0
	v_addc_co_u32_e32 v53, vcc, 0, v3, vcc
	global_load_dword v50, v[50:51], off nt
	s_nop 0
	global_load_dword v51, v[52:53], off offset:3072 nt
	v_add_co_u32_e32 v52, vcc, s12, v2
	s_mov_b32 s12, 0xa2000
	s_nop 0
	v_addc_co_u32_e32 v53, vcc, 0, v3, vcc
	v_add_co_u32_e32 v54, vcc, s12, v2
	s_mov_b32 s12, 0xa5000
	s_nop 0
	v_addc_co_u32_e32 v55, vcc, 0, v3, vcc
	global_load_dword v52, v[52:53], off offset:2048 nt
	s_nop 0
	global_load_dword v53, v[54:55], off offset:1024 nt
	v_add_co_u32_e32 v54, vcc, s12, v2
	s_mov_b32 s12, 0xa7000
	s_nop 0
	v_addc_co_u32_e32 v55, vcc, 0, v3, vcc
	v_add_co_u32_e32 v56, vcc, s12, v2
	s_mov_b32 s12, 0xaa000
	s_nop 0
	v_addc_co_u32_e32 v57, vcc, 0, v3, vcc
	global_load_dword v54, v[54:55], off nt
	s_nop 0
	global_load_dword v55, v[56:57], off offset:3072 nt
	v_add_co_u32_e32 v56, vcc, s12, v2
	s_mov_b32 s12, 0xad000
	s_nop 0
	v_addc_co_u32_e32 v57, vcc, 0, v3, vcc
	v_add_co_u32_e32 v2, vcc, s12, v2
	s_lshl_b32 s12, s4, 8
	s_nop 0
	v_addc_co_u32_e32 v3, vcc, 0, v3, vcc
	v_mov_b32_e32 v107, s12
	global_load_dword v56, v[56:57], off offset:2048 nt
	s_and_b32 s12, s16, 0xffffff00
	global_load_dword v57, v[2:3], off offset:1024 nt
	global_load_dwordx4 v[108:111], v107, s[18:19] offset:48 nt
	global_load_dwordx4 v[112:115], v107, s[18:19] offset:32 nt
	global_load_dwordx4 v[116:119], v107, s[18:19] offset:16 nt
	global_load_dwordx4 v[76:79], v107, s[18:19] nt
	s_and_b32 s16, s17, 64
	s_or_b32 s12, s12, s16
	s_waitcnt vmcnt(0)
; template <int MODE>
; __device__ __forceinline__ void p0_item(const float* W, int K, int N, bf16u* WT, const float* ks, LAS float* scr, int item, int lane) {
;     ...
;     if (ks) {
; #pragma unroll
;         for (int kk = 0; kk < 64; ++kk) v[kk] *= ks[k0 + kk];
;     }
; #pragma unroll
;     for (int kk = 0; kk < 64; ++kk) scr[kk * 65 + lane] = v[kk];
;     asm volatile("s_waitcnt lgkmcnt(0)" ::: "memory");
	v_mul_f32_e32 v68, v68, v115
	v_mul_f32_e32 v80, v9, v117
	v_mul_f32_e32 v74, v4, v76
	v_mul_f32_e32 v76, v5, v77
	v_mul_f32_e32 v77, v6, v78
	v_mul_f32_e32 v79, v7, v79
	v_mul_f32_e32 v78, v8, v116
	v_mul_f32_e32 v82, v60, v119
	v_mul_f32_e32 v60, v62, v112
	v_mul_f32_e32 v62, v64, v113
	v_mul_f32_e32 v64, v66, v114
	v_mul_f32_e32 v66, v70, v108
	v_mul_f32_e32 v70, v73, v109
	v_mul_f32_e32 v73, v84, v110
	v_mul_f32_e32 v84, v91, v111
	global_load_dwordx4 v[2:5], v107, s[18:19] offset:112 nt
	global_load_dwordx4 v[6:9], v107, s[18:19] offset:96 nt
	global_load_dwordx4 v[108:111], v107, s[18:19] offset:80 nt
	global_load_dwordx4 v[112:115], v107, s[18:19] offset:64 nt
	v_mul_f32_e32 v81, v11, v118
	s_waitcnt vmcnt(2)
	v_mul_f32_e32 v89, v89, v9
	s_waitcnt vmcnt(1)
	v_mul_f32_e32 v72, v72, v111
	s_waitcnt vmcnt(0)
	v_mul_f32_e32 v91, v10, v112
	v_mul_f32_e32 v103, v12, v113
	v_mul_f32_e32 v104, v13, v114
	v_mul_f32_e32 v105, v58, v115
	v_mul_f32_e32 v58, v59, v108
	v_mul_f32_e32 v59, v61, v109
	v_mul_f32_e32 v61, v63, v110
	v_mul_f32_e32 v63, v75, v6
	v_mul_f32_e32 v75, v85, v7
	v_mul_f32_e32 v85, v87, v8
	v_mul_f32_e32 v87, v90, v2
	v_mul_f32_e32 v90, v92, v3
	v_mul_f32_e32 v92, v93, v4
	v_mul_f32_e32 v93, v99, v5
	global_load_dwordx4 v[2:5], v107, s[18:19] offset:176 nt
	global_load_dwordx4 v[6:9], v107, s[18:19] offset:160 nt
	global_load_dwordx4 v[10:13], v107, s[18:19] offset:144 nt
	global_load_dwordx4 v[108:111], v107, s[18:19] offset:128 nt
	s_waitcnt vmcnt(3)
	v_mul_f32_e32 v100, v100, v2
	s_waitcnt vmcnt(2)
	v_mul_f32_e32 v98, v98, v9
	s_waitcnt vmcnt(1)
	v_mul_f32_e32 v83, v83, v10
	s_waitcnt vmcnt(0)
	v_mul_f32_e32 v65, v65, v108
	v_mul_f32_e32 v67, v67, v109
	v_mul_f32_e32 v69, v69, v110
	v_mul_f32_e32 v86, v86, v11
	v_mul_f32_e32 v88, v88, v12
	v_mul_f32_e32 v99, v94, v13
	v_mul_f32_e32 v108, v95, v6
	v_mul_f32_e32 v109, v96, v7
	v_mul_f32_e32 v110, v97, v8
	v_mul_f32_e32 v101, v101, v3
	v_mul_f32_e32 v102, v102, v4
	v_mul_f32_e32 v106, v106, v5
	global_load_dwordx4 v[2:5], v107, s[18:19] offset:240 nt
	global_load_dwordx4 v[6:9], v107, s[18:19] offset:224 nt
	global_load_dwordx4 v[10:13], v107, s[18:19] offset:208 nt
	global_load_dwordx4 v[94:97], v107, s[18:19] offset:192 nt
	ds_write2_b32 v31, v74, v76 offset1:65
	ds_write2_b32 v31, v77, v79 offset0:130 offset1:195
	v_mul_f32_e32 v71, v71, v111
	s_waitcnt vmcnt(3)
	v_mul_f32_e32 v2, v54, v2
	s_waitcnt vmcnt(2)
	v_mul_f32_e32 v6, v50, v6
	s_waitcnt vmcnt(1)
	v_mul_f32_e32 v10, v17, v10
	v_add_u32_e32 v17, 0x400, v31
	ds_write2_b32 v17, v78, v80 offset0:4 offset1:69
	ds_write2_b32 v17, v81, v82 offset0:134 offset1:199
	v_add_u32_e32 v17, 0x800, v31
	ds_write2_b32 v17, v60, v62 offset0:8 offset1:73
	ds_write2_b32 v17, v64, v68 offset0:138 offset1:203
	v_add_u32_e32 v17, 0xc00, v31
	ds_write2_b32 v17, v66, v70 offset0:12 offset1:77
	ds_write2_b32 v17, v73, v84 offset0:142 offset1:207
	v_add_u32_e32 v17, 0x1000, v31
	ds_write2_b32 v17, v91, v103 offset0:16 offset1:81
	ds_write2_b32 v17, v104, v105 offset0:146 offset1:211
	v_add_u32_e32 v17, 0x1400, v31
	ds_write2_b32 v17, v58, v59 offset0:20 offset1:85
	ds_write2_b32 v17, v61, v72 offset0:150 offset1:215
	v_add_u32_e32 v17, 0x1800, v31
	ds_write2_b32 v17, v63, v75 offset0:24 offset1:89
	ds_write2_b32 v17, v85, v89 offset0:154 offset1:219
	v_add_u32_e32 v17, 0x1c00, v31
	ds_write2_b32 v17, v87, v90 offset0:28 offset1:93
	ds_write2_b32 v17, v92, v93 offset0:158 offset1:223
	v_add_u32_e32 v17, 0x2000, v31
	ds_write2_b32 v17, v65, v67 offset0:32 offset1:97
	ds_write2_b32 v17, v69, v71 offset0:162 offset1:227
	v_add_u32_e32 v17, 0x2400, v31
	ds_write2_b32 v17, v83, v86 offset0:36 offset1:101
	ds_write2_b32 v17, v88, v99 offset0:166 offset1:231
	v_add_u32_e32 v17, 0x2800, v31
	ds_write2_b32 v17, v108, v109 offset0:40 offset1:105
	ds_write2_b32 v17, v110, v98 offset0:170 offset1:235
	v_add_u32_e32 v17, 0x2c00, v31
	s_waitcnt vmcnt(0)
	v_mul_f32_e32 v0, v0, v94
	v_mul_f32_e32 v14, v14, v95
	ds_write2_b32 v17, v100, v101 offset0:44 offset1:109
	ds_write2_b32 v17, v102, v106 offset0:174 offset1:239
	v_add_u32_e32 v17, 0x3000, v31
	v_mul_f32_e32 v15, v15, v96
	v_mul_f32_e32 v16, v16, v97
	v_mul_f32_e32 v11, v47, v11
	ds_write2_b32 v17, v0, v14 offset0:48 offset1:113
	ds_write2_b32 v17, v15, v16 offset0:178 offset1:243
	v_add_u32_e32 v0, 0x3400, v31
	v_mul_f32_e32 v12, v48, v12
	v_mul_f32_e32 v13, v49, v13
	v_mul_f32_e32 v7, v51, v7
	ds_write2_b32 v0, v10, v11 offset0:52 offset1:117
	ds_write2_b32 v0, v12, v13 offset0:182 offset1:247
	v_add_u32_e32 v0, 0x3800, v31
	v_mul_f32_e32 v8, v52, v8
	v_mul_f32_e32 v9, v53, v9
	v_mul_f32_e32 v3, v55, v3
	ds_write2_b32 v0, v6, v7 offset0:56 offset1:121
	ds_write2_b32 v0, v8, v9 offset0:186 offset1:251
	v_add_u32_e32 v0, 0x3c00, v31
	v_mul_f32_e32 v4, v56, v4
	v_mul_f32_e32 v5, v57, v5
	ds_write2_b32 v0, v2, v3 offset0:60 offset1:125
	ds_write2_b32 v0, v4, v5 offset0:190 offset1:255
	s_waitcnt lgkmcnt(0)
; #define LAS __attribute__((address_space(3)))
; __device__ __forceinline__ unsigned pk2(float lo, float hi) { return pg8::cvt_pk_bf16(lo, hi); }
; template <int MODE>
; __device__ __forceinline__ void p0_item(const float* W, int K, int N, bf16u* WT, const float* ks, LAS float* scr, int item, int lane) {
;     ...
;     const int c = lane & 7;
; #pragma unroll
;     for (int j = 0; j < 8; ++j) { const int n = (lane >> 3) + 8 * j; const LAS float* s = scr + (8 * c) * 65 + n;
;         v4u o; o.x = pk2(s[0 * 65], s[1 * 65]); o.y = pk2(s[2 * 65], s[3 * 65]); o.z = pk2(s[4 * 65], s[5 * 65]); o.w = pk2(s[6 * 65], s[7 * 65]);
;         *(v4u*)(WT + (size_t)(drow + n) * K + k0 + 8 * c) = o; }
;     asm volatile("s_waitcnt lgkmcnt(0)" ::: "memory");
	v_add_u32_e32 v0, 0x400, v33
	ds_read2_b32 v[8:9], v33 offset0:65 offset1:73
	ds_read2_b32 v[10:11], v33 offset1:8
	ds_read2_b32 v[12:13], v33 offset0:130 offset1:138
	ds_read2_b32 v[14:15], v33 offset0:195 offset1:203
	ds_read2_b32 v[16:17], v0 offset0:4 offset1:12
	ds_read2_b32 v[48:49], v0 offset0:69 offset1:77
	ds_read2_b32 v[50:51], v0 offset0:134 offset1:142
	ds_read2_b32 v[52:53], v0 offset0:199 offset1:207
	v_or_b32_e32 v54, s12, v32
	v_ashrrev_i32_e32 v55, 31, v54
	v_lshl_add_u64 v[2:3], v[22:23], 0, s[90:91]
	v_lshlrev_b64 v[54:55], 11, v[54:55]
	s_waitcnt lgkmcnt(6)
	v_cvt_pk_bf16_f32 v4, v10, v8
	s_waitcnt lgkmcnt(4)
	v_cvt_pk_bf16_f32 v5, v12, v14
	s_waitcnt lgkmcnt(2)
	v_cvt_pk_bf16_f32 v6, v16, v48
	s_waitcnt lgkmcnt(0)
	v_cvt_pk_bf16_f32 v7, v50, v52
	v_lshl_add_u64 v[54:55], v[2:3], 0, v[54:55]
	v_or_b32_e32 v8, s12, v34
	global_store_dwordx4 v[54:55], v[4:7], off sc1
	v_or_b32_e32 v54, s12, v35
	v_ashrrev_i32_e32 v55, 31, v54
	v_cvt_pk_bf16_f32 v4, v11, v9
	v_ashrrev_i32_e32 v9, 31, v8
	v_lshlrev_b64 v[8:9], 11, v[8:9]
	v_cvt_pk_bf16_f32 v5, v13, v15
	v_cvt_pk_bf16_f32 v6, v17, v49
	v_cvt_pk_bf16_f32 v7, v51, v53
	v_lshl_add_u64 v[8:9], v[2:3], 0, v[8:9]
	global_store_dwordx4 v[8:9], v[4:7], off sc1
	ds_read2_b32 v[8:9], v33 offset0:81 offset1:89
	ds_read2_b32 v[10:11], v33 offset0:16 offset1:24
	ds_read2_b32 v[12:13], v33 offset0:146 offset1:154
	ds_read2_b32 v[14:15], v33 offset0:211 offset1:219
	ds_read2_b32 v[16:17], v0 offset0:20 offset1:28
	ds_read2_b32 v[48:49], v0 offset0:85 offset1:93
	ds_read2_b32 v[50:51], v0 offset0:150 offset1:158
	ds_read2_b32 v[52:53], v0 offset0:215 offset1:223
	v_lshlrev_b64 v[54:55], 11, v[54:55]
	s_waitcnt lgkmcnt(6)
	v_cvt_pk_bf16_f32 v4, v10, v8
	s_waitcnt lgkmcnt(4)
	v_cvt_pk_bf16_f32 v5, v12, v14
	s_waitcnt lgkmcnt(2)
	v_cvt_pk_bf16_f32 v6, v16, v48
	s_waitcnt lgkmcnt(0)
	v_cvt_pk_bf16_f32 v7, v50, v52
	v_lshl_add_u64 v[54:55], v[2:3], 0, v[54:55]
	v_or_b32_e32 v8, s12, v36
	global_store_dwordx4 v[54:55], v[4:7], off sc1
	v_or_b32_e32 v54, s12, v37
	v_ashrrev_i32_e32 v55, 31, v54
	v_cvt_pk_bf16_f32 v4, v11, v9
	v_ashrrev_i32_e32 v9, 31, v8
	v_lshlrev_b64 v[8:9], 11, v[8:9]
	v_cvt_pk_bf16_f32 v5, v13, v15
	v_cvt_pk_bf16_f32 v6, v17, v49
	v_cvt_pk_bf16_f32 v7, v51, v53
	v_lshl_add_u64 v[8:9], v[2:3], 0, v[8:9]
	global_store_dwordx4 v[8:9], v[4:7], off sc1
	ds_read2_b32 v[8:9], v33 offset0:32 offset1:40
	ds_read2_b32 v[10:11], v33 offset0:97 offset1:105
	ds_read2_b32 v[12:13], v33 offset0:162 offset1:170
	ds_read2_b32 v[14:15], v33 offset0:227 offset1:235
	ds_read2_b32 v[16:17], v0 offset0:36 offset1:44
	ds_read2_b32 v[48:49], v0 offset0:101 offset1:109
	ds_read2_b32 v[50:51], v0 offset0:166 offset1:174
	ds_read2_b32 v[52:53], v0 offset0:231 offset1:239
	v_lshlrev_b64 v[54:55], 11, v[54:55]
	s_waitcnt lgkmcnt(6)
	v_cvt_pk_bf16_f32 v4, v8, v10
	s_waitcnt lgkmcnt(4)
	v_cvt_pk_bf16_f32 v5, v12, v14
	s_waitcnt lgkmcnt(2)
	v_cvt_pk_bf16_f32 v6, v16, v48
	s_waitcnt lgkmcnt(0)
	v_cvt_pk_bf16_f32 v7, v50, v52
	v_lshl_add_u64 v[54:55], v[2:3], 0, v[54:55]
	v_or_b32_e32 v8, s12, v38
	global_store_dwordx4 v[54:55], v[4:7], off sc1
	v_or_b32_e32 v54, s12, v39
	v_ashrrev_i32_e32 v55, 31, v54
	v_cvt_pk_bf16_f32 v4, v9, v11
	v_ashrrev_i32_e32 v9, 31, v8
	v_lshlrev_b64 v[8:9], 11, v[8:9]
	v_cvt_pk_bf16_f32 v5, v13, v15
	v_cvt_pk_bf16_f32 v6, v17, v49
	v_cvt_pk_bf16_f32 v7, v51, v53
	v_lshl_add_u64 v[8:9], v[2:3], 0, v[8:9]
	global_store_dwordx4 v[8:9], v[4:7], off sc1
	ds_read2_b32 v[8:9], v33 offset0:48 offset1:56
	ds_read2_b32 v[10:11], v33 offset0:113 offset1:121
	ds_read2_b32 v[12:13], v33 offset0:178 offset1:186
	ds_read2_b32 v[14:15], v33 offset0:243 offset1:251
	ds_read2_b32 v[16:17], v0 offset0:52 offset1:60
	ds_read2_b32 v[48:49], v0 offset0:117 offset1:125
	ds_read2_b32 v[50:51], v0 offset0:182 offset1:190
	ds_read2_b32 v[52:53], v0 offset0:247 offset1:255
	v_lshlrev_b64 v[54:55], 11, v[54:55]
	s_waitcnt lgkmcnt(6)
	v_cvt_pk_bf16_f32 v4, v8, v10
	s_waitcnt lgkmcnt(4)
	v_cvt_pk_bf16_f32 v5, v12, v14
	s_waitcnt lgkmcnt(2)
	v_cvt_pk_bf16_f32 v6, v16, v48
	s_waitcnt lgkmcnt(0)
	v_cvt_pk_bf16_f32 v7, v50, v52
	v_lshl_add_u64 v[54:55], v[2:3], 0, v[54:55]
	v_or_b32_e32 v8, s12, v40
	global_store_dwordx4 v[54:55], v[4:7], off sc1
	s_nop 1
	v_cvt_pk_bf16_f32 v4, v9, v11
	v_ashrrev_i32_e32 v9, 31, v8
	v_lshlrev_b64 v[8:9], 11, v[8:9]
	v_cvt_pk_bf16_f32 v5, v13, v15
	v_cvt_pk_bf16_f32 v6, v17, v49
	v_cvt_pk_bf16_f32 v7, v51, v53
	v_lshl_add_u64 v[2:3], v[2:3], 0, v[8:9]
	global_store_dwordx4 v[2:3], v[4:7], off sc1
	s_waitcnt lgkmcnt(0)

; template <int MODE>
; __device__ __forceinline__ void p0_item(const float* W, int K, int N, bf16u* WT, const float* ks, LAS float* scr, int item, int lane) {
;     const int nblk = N / 64, kb = item / nblk, nb = item - kb * nblk, k0 = 64 * kb, n0 = 64 * nb;
;     int nn = n0 + lane;
;     if (MODE == 1) {
;         if (nn < 2048) { const int p = nn & 63; if (p < 16) nn = (nn & ~15) | (p & 3) | ((p & 4) << 1) | ((p & 8) >> 1); }
;         else if (nn >= 4096) { const int sec = nn >= 6144 ? 6144 : 4096, r = nn - sec, q = r & 255; nn = sec + ((q >> 7) << 10) + 128 * (r >> 8) + (q & 127); }
;     }
;     int drow = n0;
;     if (MODE == 2) drow = 256 * (n0 >> 7) + (n0 & 127);
;     if (MODE == 3) drow = 256 * (n0 >> 7) + 128 + (n0 & 127);
;     const float* src = W + (size_t)k0 * N + nn;
;     float v[64];
; #pragma unroll
;     for (int kk = 0; kk < 64; ++kk) v[kk] = src[(size_t)kk * N];
.LBB0_612:
	s_andn2_b64 vcc, exec, s[16:17]
	s_cbranch_vccnz .LBB0_614
	s_add_i32 s4, s53, 0xffffd800
	s_and_b32 s12, s4, 0xfc0
	s_add_i32 s4, s52, s59
	s_add_i32 s4, s4, 0xfffd8000
	s_and_b32 s4, s4, 0x3c0
	s_lshl_b32 s16, s12, 12
	v_or_b32_e32 v0, s4, v30
	s_add_u32 s16, s41, s16
	s_addc_u32 s17, s42, 0
	v_lshlrev_b32_e32 v0, 2, v0
	v_lshl_add_u64 v[2:3], s[16:17], 0, v[0:1]
	v_add_co_u32_e32 v4, vcc, s61, v2
	global_load_dword v0, v0, s[16:17] nt
	s_nop 0
	v_addc_co_u32_e32 v5, vcc, 0, v3, vcc
	s_movk_i32 s16, 0x4000
	global_load_dword v6, v[4:5], off offset:-4096 nt
	global_load_dword v7, v[4:5], off nt
	v_add_co_u32_e32 v4, vcc, s16, v2
	s_movk_i32 s16, 0x6000
	s_nop 0
	v_addc_co_u32_e32 v5, vcc, 0, v3, vcc
	global_load_dword v8, v[4:5], off offset:-4096 nt
	global_load_dword v9, v[4:5], off nt
	v_add_co_u32_e32 v4, vcc, s16, v2
	s_mov_b32 s16, 0xe000
	s_nop 0
	v_addc_co_u32_e32 v5, vcc, 0, v3, vcc
	global_load_dword v10, v[4:5], off offset:-4096 nt
	global_load_dword v11, v[4:5], off nt
	v_add_co_u32_e32 v4, vcc, s88, v2
	s_lshl_b32 s90, s12, 1
	s_nop 0
	v_addc_co_u32_e32 v5, vcc, 0, v3, vcc
	global_load_dword v12, v[4:5], off offset:-4096 nt
	global_load_dword v13, v[4:5], off nt
	v_add_co_u32_e32 v4, vcc, s27, v2
	s_nop 1
	v_addc_co_u32_e32 v5, vcc, 0, v3, vcc
	global_load_dword v14, v[4:5], off offset:-4096 nt
	global_load_dword v15, v[4:5], off nt
	v_add_co_u32_e32 v4, vcc, s26, v2
	s_nop 1
	v_addc_co_u32_e32 v5, vcc, 0, v3, vcc
	global_load_dword v16, v[4:5], off offset:-4096 nt
	global_load_dword v17, v[4:5], off nt
	v_add_co_u32_e32 v4, vcc, s16, v2
	s_mov_b32 s16, 0x10000
	s_nop 0
	v_addc_co_u32_e32 v5, vcc, 0, v3, vcc
	global_load_dword v47, v[4:5], off offset:-4096 nt
	global_load_dword v48, v[4:5], off nt
	v_add_co_u32_e32 v4, vcc, s16, v2
	s_mov_b32 s16, 0x14000
	s_nop 0
	v_addc_co_u32_e32 v5, vcc, 0, v3, vcc
	global_load_dword v49, v[4:5], off offset:-4096 nt
	global_load_dword v50, v[4:5], off nt
	v_add_co_u32_e32 v4, vcc, s22, v2
	s_nop 1
	v_addc_co_u32_e32 v5, vcc, 0, v3, vcc
	global_load_dword v51, v[4:5], off offset:-4096 nt
	global_load_dword v52, v[4:5], off nt
	v_add_co_u32_e32 v4, vcc, s16, v2
	s_mov_b32 s16, 0x16000
	s_nop 0
	v_addc_co_u32_e32 v5, vcc, 0, v3, vcc
	global_load_dword v53, v[4:5], off offset:-4096 nt
	global_load_dword v54, v[4:5], off nt
	v_add_co_u32_e32 v4, vcc, s16, v2
	s_mov_b32 s16, 0x1a000
	s_nop 0
	v_addc_co_u32_e32 v5, vcc, 0, v3, vcc
	global_load_dword v55, v[4:5], off offset:-4096 nt
	global_load_dword v56, v[4:5], off nt
	v_add_co_u32_e32 v4, vcc, s5, v2
	s_nop 1
	v_addc_co_u32_e32 v5, vcc, 0, v3, vcc
	global_load_dword v57, v[4:5], off offset:-4096 nt
	global_load_dword v58, v[4:5], off nt
	v_add_co_u32_e32 v4, vcc, s16, v2
	s_mov_b32 s16, 0x1c000
	s_nop 0
	v_addc_co_u32_e32 v5, vcc, 0, v3, vcc
	global_load_dword v59, v[4:5], off offset:-4096 nt
	global_load_dword v60, v[4:5], off nt
	v_add_co_u32_e32 v4, vcc, s16, v2
	s_mov_b32 s16, 0x1e000
	s_nop 0
	v_addc_co_u32_e32 v5, vcc, 0, v3, vcc
	global_load_dword v61, v[4:5], off offset:-4096 nt
	global_load_dword v62, v[4:5], off nt
	v_add_co_u32_e32 v4, vcc, s16, v2
	s_mov_b32 s16, 0x20000
	s_nop 0
	v_addc_co_u32_e32 v5, vcc, 0, v3, vcc
	global_load_dword v63, v[4:5], off offset:-4096 nt
	global_load_dword v64, v[4:5], off nt
	v_add_co_u32_e32 v4, vcc, s16, v2
	s_mov_b32 s16, 0x22000
	s_nop 0
	v_addc_co_u32_e32 v5, vcc, 0, v3, vcc
	global_load_dword v65, v[4:5], off offset:-4096 nt
	global_load_dword v66, v[4:5], off nt
	v_add_co_u32_e32 v4, vcc, s16, v2
	s_mov_b32 s16, 0x24000
	s_nop 0
	v_addc_co_u32_e32 v5, vcc, 0, v3, vcc
	global_load_dword v67, v[4:5], off offset:-4096 nt
	global_load_dword v68, v[4:5], off nt
	v_add_co_u32_e32 v4, vcc, s16, v2
	s_mov_b32 s16, 0x26000
	s_nop 0
	v_addc_co_u32_e32 v5, vcc, 0, v3, vcc
	global_load_dword v69, v[4:5], off offset:-4096 nt
	global_load_dword v70, v[4:5], off nt
	v_add_co_u32_e32 v4, vcc, s16, v2
	s_mov_b32 s16, 0x28000
	s_nop 0
	v_addc_co_u32_e32 v5, vcc, 0, v3, vcc
	global_load_dword v71, v[4:5], off offset:-4096 nt
	global_load_dword v72, v[4:5], off nt
	v_add_co_u32_e32 v4, vcc, s16, v2
	s_mov_b32 s16, 0x2a000
	s_nop 0
	v_addc_co_u32_e32 v5, vcc, 0, v3, vcc
	global_load_dword v73, v[4:5], off offset:-4096 nt
	global_load_dword v74, v[4:5], off nt
	v_add_co_u32_e32 v4, vcc, s16, v2
	s_mov_b32 s16, 0x2c000
	s_nop 0
	v_addc_co_u32_e32 v5, vcc, 0, v3, vcc
	global_load_dword v75, v[4:5], off offset:-4096 nt
	global_load_dword v76, v[4:5], off nt
	v_add_co_u32_e32 v4, vcc, s16, v2
	s_mov_b32 s16, 0x2e000
	s_nop 0
	v_addc_co_u32_e32 v5, vcc, 0, v3, vcc
	global_load_dword v77, v[4:5], off offset:-4096 nt
	global_load_dword v78, v[4:5], off nt
	v_add_co_u32_e32 v4, vcc, s16, v2
	s_mov_b32 s16, 0x30000
	s_nop 0
	v_addc_co_u32_e32 v5, vcc, 0, v3, vcc
	global_load_dword v79, v[4:5], off offset:-4096 nt
	global_load_dword v80, v[4:5], off nt
	v_add_co_u32_e32 v4, vcc, s16, v2
	s_mov_b32 s16, 0x32000
	s_nop 0
	v_addc_co_u32_e32 v5, vcc, 0, v3, vcc
	global_load_dword v81, v[4:5], off offset:-4096 nt
	global_load_dword v82, v[4:5], off nt
	v_add_co_u32_e32 v4, vcc, s16, v2
	s_mov_b32 s16, 0x34000
	s_nop 0
	v_addc_co_u32_e32 v5, vcc, 0, v3, vcc
	global_load_dword v83, v[4:5], off offset:-4096 nt
	global_load_dword v84, v[4:5], off nt
	v_add_co_u32_e32 v4, vcc, s16, v2
	s_mov_b32 s16, 0x36000
	s_nop 0
	v_addc_co_u32_e32 v5, vcc, 0, v3, vcc
	global_load_dword v85, v[4:5], off offset:-4096 nt
	global_load_dword v86, v[4:5], off nt
	v_add_co_u32_e32 v4, vcc, s16, v2
	s_mov_b32 s16, 0x38000
	s_nop 0
	v_addc_co_u32_e32 v5, vcc, 0, v3, vcc
	global_load_dword v87, v[4:5], off offset:-4096 nt
	global_load_dword v88, v[4:5], off nt
	v_add_co_u32_e32 v4, vcc, s16, v2
	s_mov_b32 s16, 0x3a000
	s_nop 0
	v_addc_co_u32_e32 v5, vcc, 0, v3, vcc
	global_load_dword v89, v[4:5], off offset:-4096 nt
	global_load_dword v90, v[4:5], off nt
	v_add_co_u32_e32 v4, vcc, s16, v2
	s_mov_b32 s16, 0x3c000
	s_nop 0
	v_addc_co_u32_e32 v5, vcc, 0, v3, vcc
	global_load_dword v91, v[4:5], off offset:-4096 nt
	global_load_dword v92, v[4:5], off nt
	v_add_co_u32_e32 v4, vcc, s16, v2
	s_mov_b32 s16, 0x3e000
	s_nop 0
	v_addc_co_u32_e32 v5, vcc, 0, v3, vcc
	global_load_dword v93, v[4:5], off offset:-4096 nt
	global_load_dword v94, v[4:5], off nt
	v_add_co_u32_e32 v4, vcc, s16, v2
	s_mov_b32 s16, 0x3f000
	s_nop 0
	v_addc_co_u32_e32 v5, vcc, 0, v3, vcc
	v_add_co_u32_e32 v2, vcc, s16, v2
	global_load_dword v95, v[4:5], off offset:-4096 nt
	s_nop 0
	global_load_dword v4, v[4:5], off nt
	v_addc_co_u32_e32 v3, vcc, 0, v3, vcc
	global_load_dword v2, v[2:3], off nt
	s_waitcnt vmcnt(0)
; #define LAS __attribute__((address_space(3)))
; __device__ __forceinline__ unsigned pk2(float lo, float hi) { return pg8::cvt_pk_bf16(lo, hi); }
; template <int MODE>
; __device__ __forceinline__ void p0_item(const float* W, int K, int N, bf16u* WT, const float* ks, LAS float* scr, int item, int lane) {
;     ...
;     for (int kk = 0; kk < 64; ++kk) scr[kk * 65 + lane] = v[kk];
;     asm volatile("s_waitcnt lgkmcnt(0)" ::: "memory");
;     const int c = lane & 7;
; #pragma unroll
;     for (int j = 0; j < 8; ++j) { const int n = (lane >> 3) + 8 * j; const LAS float* s = scr + (8 * c) * 65 + n;
;         v4u o; o.x = pk2(s[0 * 65], s[1 * 65]); o.y = pk2(s[2 * 65], s[3 * 65]); o.z = pk2(s[4 * 65], s[5 * 65]); o.w = pk2(s[6 * 65], s[7 * 65]);
;         *(v4u*)(WT + (size_t)(drow + n) * K + k0 + 8 * c) = o; }
;     asm volatile("s_waitcnt lgkmcnt(0)" ::: "memory");
	ds_write2_b32 v31, v0, v6 offset1:65
	ds_write2_b32 v31, v7, v8 offset0:130 offset1:195
	v_add_u32_e32 v0, 0x400, v31
	ds_write2_b32 v0, v9, v10 offset0:4 offset1:69
	ds_write2_b32 v0, v11, v12 offset0:134 offset1:199
	v_add_u32_e32 v0, 0x800, v31
	ds_write2_b32 v0, v13, v14 offset0:8 offset1:73
	ds_write2_b32 v0, v15, v16 offset0:138 offset1:203
	v_add_u32_e32 v0, 0xc00, v31
	ds_write2_b32 v0, v17, v47 offset0:12 offset1:77
	ds_write2_b32 v0, v48, v49 offset0:142 offset1:207
	v_add_u32_e32 v0, 0x1000, v31
	ds_write2_b32 v0, v50, v51 offset0:16 offset1:81
	ds_write2_b32 v0, v52, v53 offset0:146 offset1:211
	v_add_u32_e32 v0, 0x1400, v31
	ds_write2_b32 v0, v54, v55 offset0:20 offset1:85
	ds_write2_b32 v0, v56, v57 offset0:150 offset1:215
	v_add_u32_e32 v0, 0x1800, v31
	ds_write2_b32 v0, v58, v59 offset0:24 offset1:89
	ds_write2_b32 v0, v60, v61 offset0:154 offset1:219
	v_add_u32_e32 v0, 0x1c00, v31
	ds_write2_b32 v0, v62, v63 offset0:28 offset1:93
	ds_write2_b32 v0, v64, v65 offset0:158 offset1:223
	v_add_u32_e32 v0, 0x2000, v31
	ds_write2_b32 v0, v66, v67 offset0:32 offset1:97
	ds_write2_b32 v0, v68, v69 offset0:162 offset1:227
	v_add_u32_e32 v0, 0x2400, v31
	ds_write2_b32 v0, v70, v71 offset0:36 offset1:101
	ds_write2_b32 v0, v72, v73 offset0:166 offset1:231
	v_add_u32_e32 v0, 0x2800, v31
	ds_write2_b32 v0, v74, v75 offset0:40 offset1:105
	ds_write2_b32 v0, v76, v77 offset0:170 offset1:235
	v_add_u32_e32 v0, 0x2c00, v31
	ds_write2_b32 v0, v78, v79 offset0:44 offset1:109
	ds_write2_b32 v0, v80, v81 offset0:174 offset1:239
	v_add_u32_e32 v0, 0x3000, v31
	ds_write2_b32 v0, v82, v83 offset0:48 offset1:113
	ds_write2_b32 v0, v84, v85 offset0:178 offset1:243
	v_add_u32_e32 v0, 0x3400, v31
	ds_write2_b32 v0, v86, v87 offset0:52 offset1:117
	ds_write2_b32 v0, v88, v89 offset0:182 offset1:247
	v_add_u32_e32 v0, 0x3800, v31
	ds_write2_b32 v0, v90, v91 offset0:56 offset1:121
	ds_write2_b32 v0, v92, v93 offset0:186 offset1:251
	v_add_u32_e32 v0, 0x3c00, v31
	ds_write2_b32 v0, v94, v95 offset0:60 offset1:125
	ds_write2_b32 v0, v4, v2 offset0:190 offset1:255
	s_waitcnt lgkmcnt(0)
	v_add_u32_e32 v47, 0x400, v33
	ds_read2_b32 v[8:9], v33 offset0:65 offset1:73
	ds_read2_b32 v[10:11], v33 offset1:8
	ds_read2_b32 v[12:13], v33 offset0:130 offset1:138
	ds_read2_b32 v[14:15], v33 offset0:195 offset1:203
	ds_read2_b32 v[16:17], v47 offset0:4 offset1:12
	ds_read2_b32 v[48:49], v47 offset0:69 offset1:77
	ds_read2_b32 v[50:51], v47 offset0:134 offset1:142
	ds_read2_b32 v[52:53], v47 offset0:199 offset1:207
	v_or_b32_e32 v0, s4, v32
	v_lshl_add_u64 v[2:3], v[24:25], 0, s[90:91]
	v_lshlrev_b32_e32 v0, 11, v0
	v_lshl_add_u64 v[54:55], v[2:3], 0, v[0:1]
	v_or_b32_e32 v0, s4, v34
	s_waitcnt lgkmcnt(6)
	v_cvt_pk_bf16_f32 v4, v10, v8
	s_waitcnt lgkmcnt(4)
	v_cvt_pk_bf16_f32 v5, v12, v14
	s_waitcnt lgkmcnt(2)
	v_cvt_pk_bf16_f32 v6, v16, v48
	s_waitcnt lgkmcnt(0)
	v_cvt_pk_bf16_f32 v7, v50, v52
	v_lshlrev_b32_e32 v0, 11, v0
	global_store_dwordx4 v[54:55], v[4:7], off sc1
	s_nop 1
	v_cvt_pk_bf16_f32 v4, v11, v9
	v_cvt_pk_bf16_f32 v5, v13, v15
	v_cvt_pk_bf16_f32 v6, v17, v49
	v_cvt_pk_bf16_f32 v7, v51, v53
	v_lshl_add_u64 v[8:9], v[2:3], 0, v[0:1]
	global_store_dwordx4 v[8:9], v[4:7], off sc1
	ds_read2_b32 v[8:9], v33 offset0:81 offset1:89
	ds_read2_b32 v[10:11], v33 offset0:16 offset1:24
	ds_read2_b32 v[12:13], v33 offset0:146 offset1:154
	ds_read2_b32 v[14:15], v33 offset0:211 offset1:219
	ds_read2_b32 v[16:17], v47 offset0:20 offset1:28
	ds_read2_b32 v[48:49], v47 offset0:85 offset1:93
	ds_read2_b32 v[50:51], v47 offset0:150 offset1:158
	ds_read2_b32 v[52:53], v47 offset0:215 offset1:223
	v_or_b32_e32 v0, s4, v35
	v_lshlrev_b32_e32 v0, 11, v0
	v_lshl_add_u64 v[54:55], v[2:3], 0, v[0:1]
	v_or_b32_e32 v0, s4, v36
	s_waitcnt lgkmcnt(6)
	v_cvt_pk_bf16_f32 v4, v10, v8
	s_waitcnt lgkmcnt(4)
	v_cvt_pk_bf16_f32 v5, v12, v14
	s_waitcnt lgkmcnt(2)
	v_cvt_pk_bf16_f32 v6, v16, v48
	s_waitcnt lgkmcnt(0)
	v_cvt_pk_bf16_f32 v7, v50, v52
	v_lshlrev_b32_e32 v0, 11, v0
	global_store_dwordx4 v[54:55], v[4:7], off sc1
	s_nop 1
	v_cvt_pk_bf16_f32 v4, v11, v9
	v_cvt_pk_bf16_f32 v5, v13, v15
	v_cvt_pk_bf16_f32 v6, v17, v49
	v_cvt_pk_bf16_f32 v7, v51, v53
	v_lshl_add_u64 v[8:9], v[2:3], 0, v[0:1]
	global_store_dwordx4 v[8:9], v[4:7], off sc1
	ds_read2_b32 v[8:9], v33 offset0:32 offset1:40
	ds_read2_b32 v[10:11], v33 offset0:97 offset1:105
	ds_read2_b32 v[12:13], v33 offset0:162 offset1:170
	ds_read2_b32 v[14:15], v33 offset0:227 offset1:235
	ds_read2_b32 v[16:17], v47 offset0:36 offset1:44
	ds_read2_b32 v[48:49], v47 offset0:101 offset1:109
	ds_read2_b32 v[50:51], v47 offset0:166 offset1:174
	ds_read2_b32 v[52:53], v47 offset0:231 offset1:239
	v_or_b32_e32 v0, s4, v37
	v_lshlrev_b32_e32 v0, 11, v0
	v_lshl_add_u64 v[54:55], v[2:3], 0, v[0:1]
	v_or_b32_e32 v0, s4, v38
	s_waitcnt lgkmcnt(6)
	v_cvt_pk_bf16_f32 v4, v8, v10
	s_waitcnt lgkmcnt(4)
	v_cvt_pk_bf16_f32 v5, v12, v14
	s_waitcnt lgkmcnt(2)
	v_cvt_pk_bf16_f32 v6, v16, v48
	s_waitcnt lgkmcnt(0)
	v_cvt_pk_bf16_f32 v7, v50, v52
	v_lshlrev_b32_e32 v0, 11, v0
	global_store_dwordx4 v[54:55], v[4:7], off sc1
	s_nop 1
	v_cvt_pk_bf16_f32 v4, v9, v11
	v_cvt_pk_bf16_f32 v5, v13, v15
	v_cvt_pk_bf16_f32 v6, v17, v49
	v_cvt_pk_bf16_f32 v7, v51, v53
	v_lshl_add_u64 v[8:9], v[2:3], 0, v[0:1]
	global_store_dwordx4 v[8:9], v[4:7], off sc1
	ds_read2_b32 v[8:9], v33 offset0:48 offset1:56
	ds_read2_b32 v[10:11], v33 offset0:113 offset1:121
	ds_read2_b32 v[12:13], v33 offset0:178 offset1:186
	ds_read2_b32 v[14:15], v33 offset0:243 offset1:251
	ds_read2_b32 v[16:17], v47 offset0:52 offset1:60
	ds_read2_b32 v[48:49], v47 offset0:117 offset1:125
	ds_read2_b32 v[50:51], v47 offset0:182 offset1:190
	ds_read2_b32 v[52:53], v47 offset0:247 offset1:255
	v_or_b32_e32 v0, s4, v39
	v_lshlrev_b32_e32 v0, 11, v0
	v_lshl_add_u64 v[54:55], v[2:3], 0, v[0:1]
	v_or_b32_e32 v0, s4, v40
	s_waitcnt lgkmcnt(6)
	v_cvt_pk_bf16_f32 v4, v8, v10
	s_waitcnt lgkmcnt(4)
	v_cvt_pk_bf16_f32 v5, v12, v14
	s_waitcnt lgkmcnt(2)
	v_cvt_pk_bf16_f32 v6, v16, v48
	s_waitcnt lgkmcnt(0)
	v_cvt_pk_bf16_f32 v7, v50, v52
	v_lshlrev_b32_e32 v0, 11, v0
	global_store_dwordx4 v[54:55], v[4:7], off sc1
	v_lshl_add_u64 v[2:3], v[2:3], 0, v[0:1]
	s_nop 0
	v_cvt_pk_bf16_f32 v4, v9, v11
	v_cvt_pk_bf16_f32 v5, v13, v15
	v_cvt_pk_bf16_f32 v6, v17, v49
	v_cvt_pk_bf16_f32 v7, v51, v53
	global_store_dwordx4 v[2:3], v[4:7], off sc1
	s_waitcnt lgkmcnt(0)

; template <int MODE>
; __device__ __forceinline__ void p0_item(const float* W, int K, int N, bf16u* WT, const float* ks, LAS float* scr, int item, int lane) {
;     const int nblk = N / 64, kb = item / nblk, nb = item - kb * nblk, k0 = 64 * kb, n0 = 64 * nb;
;     int nn = n0 + lane;
;     if (MODE == 1) {
;         if (nn < 2048) { const int p = nn & 63; if (p < 16) nn = (nn & ~15) | (p & 3) | ((p & 4) << 1) | ((p & 8) >> 1); }
;         else if (nn >= 4096) { const int sec = nn >= 6144 ? 6144 : 4096, r = nn - sec, q = r & 255; nn = sec + ((q >> 7) << 10) + 128 * (r >> 8) + (q & 127); }
;     }
;     int drow = n0;
;     if (MODE == 2) drow = 256 * (n0 >> 7) + (n0 & 127);
;     if (MODE == 3) drow = 256 * (n0 >> 7) + 128 + (n0 & 127);
;     const float* src = W + (size_t)k0 * N + nn;
;     float v[64];
; #pragma unroll
;     for (int kk = 0; kk < 64; ++kk) v[kk] = src[(size_t)kk * N];
.LBB0_615:
	s_andn2_b64 vcc, exec, s[16:17]
	s_cbranch_vccnz .LBB0_617
	s_add_i32 s4, s53, 0xffffdc00
	s_and_b32 s12, s4, 0xfc0
	s_add_i32 s4, s52, s59
	s_add_i32 s4, s4, 0xfffdc000
	s_and_b32 s4, s4, 0x3c0
	s_lshl_b32 s16, s12, 12
	v_or_b32_e32 v0, s4, v30
	s_add_u32 s16, s43, s16
	s_addc_u32 s17, s46, 0
	v_lshlrev_b32_e32 v0, 2, v0
	v_lshl_add_u64 v[2:3], s[16:17], 0, v[0:1]
	v_add_co_u32_e32 v4, vcc, s61, v2
	global_load_dword v0, v0, s[16:17] nt
	s_nop 0
	v_addc_co_u32_e32 v5, vcc, 0, v3, vcc
	s_movk_i32 s16, 0x4000
	global_load_dword v6, v[4:5], off offset:-4096 nt
	global_load_dword v7, v[4:5], off nt
	v_add_co_u32_e32 v4, vcc, s16, v2
	s_movk_i32 s16, 0x6000
	s_nop 0
	v_addc_co_u32_e32 v5, vcc, 0, v3, vcc
	global_load_dword v8, v[4:5], off offset:-4096 nt
	global_load_dword v9, v[4:5], off nt
	v_add_co_u32_e32 v4, vcc, s16, v2
	s_mov_b32 s16, 0xe000
	s_nop 0
	v_addc_co_u32_e32 v5, vcc, 0, v3, vcc
	global_load_dword v10, v[4:5], off offset:-4096 nt
	global_load_dword v11, v[4:5], off nt
	v_add_co_u32_e32 v4, vcc, s88, v2
	s_lshl_b32 s90, s12, 1
	s_nop 0
	v_addc_co_u32_e32 v5, vcc, 0, v3, vcc
	global_load_dword v12, v[4:5], off offset:-4096 nt
	global_load_dword v13, v[4:5], off nt
	v_add_co_u32_e32 v4, vcc, s27, v2
	s_nop 1
	v_addc_co_u32_e32 v5, vcc, 0, v3, vcc
	global_load_dword v14, v[4:5], off offset:-4096 nt
	global_load_dword v15, v[4:5], off nt
	v_add_co_u32_e32 v4, vcc, s26, v2
	s_nop 1
	v_addc_co_u32_e32 v5, vcc, 0, v3, vcc
	global_load_dword v16, v[4:5], off offset:-4096 nt
	global_load_dword v17, v[4:5], off nt
	v_add_co_u32_e32 v4, vcc, s16, v2
	s_mov_b32 s16, 0x10000
	s_nop 0
	v_addc_co_u32_e32 v5, vcc, 0, v3, vcc
	global_load_dword v47, v[4:5], off offset:-4096 nt
	global_load_dword v48, v[4:5], off nt
	v_add_co_u32_e32 v4, vcc, s16, v2
	s_mov_b32 s16, 0x14000
	s_nop 0
	v_addc_co_u32_e32 v5, vcc, 0, v3, vcc
	global_load_dword v49, v[4:5], off offset:-4096 nt
	global_load_dword v50, v[4:5], off nt
	v_add_co_u32_e32 v4, vcc, s22, v2
	s_nop 1
	v_addc_co_u32_e32 v5, vcc, 0, v3, vcc
	global_load_dword v51, v[4:5], off offset:-4096 nt
	global_load_dword v52, v[4:5], off nt
	v_add_co_u32_e32 v4, vcc, s16, v2
	s_mov_b32 s16, 0x16000
	s_nop 0
	v_addc_co_u32_e32 v5, vcc, 0, v3, vcc
	global_load_dword v53, v[4:5], off offset:-4096 nt
	global_load_dword v54, v[4:5], off nt
	v_add_co_u32_e32 v4, vcc, s16, v2
	s_mov_b32 s16, 0x1a000
	s_nop 0
	v_addc_co_u32_e32 v5, vcc, 0, v3, vcc
	global_load_dword v55, v[4:5], off offset:-4096 nt
	global_load_dword v56, v[4:5], off nt
	v_add_co_u32_e32 v4, vcc, s5, v2
	s_nop 1
	v_addc_co_u32_e32 v5, vcc, 0, v3, vcc
	global_load_dword v57, v[4:5], off offset:-4096 nt
	global_load_dword v58, v[4:5], off nt
	v_add_co_u32_e32 v4, vcc, s16, v2
	s_mov_b32 s16, 0x1c000
	s_nop 0
	v_addc_co_u32_e32 v5, vcc, 0, v3, vcc
	global_load_dword v59, v[4:5], off offset:-4096 nt
	global_load_dword v60, v[4:5], off nt
	v_add_co_u32_e32 v4, vcc, s16, v2
	s_mov_b32 s16, 0x1e000
	s_nop 0
	v_addc_co_u32_e32 v5, vcc, 0, v3, vcc
	global_load_dword v61, v[4:5], off offset:-4096 nt
	global_load_dword v62, v[4:5], off nt
	v_add_co_u32_e32 v4, vcc, s16, v2
	s_mov_b32 s16, 0x20000
	s_nop 0
	v_addc_co_u32_e32 v5, vcc, 0, v3, vcc
	global_load_dword v63, v[4:5], off offset:-4096 nt
	global_load_dword v64, v[4:5], off nt
	v_add_co_u32_e32 v4, vcc, s16, v2
	s_mov_b32 s16, 0x22000
	s_nop 0
	v_addc_co_u32_e32 v5, vcc, 0, v3, vcc
	global_load_dword v65, v[4:5], off offset:-4096 nt
	global_load_dword v66, v[4:5], off nt
	v_add_co_u32_e32 v4, vcc, s16, v2
	s_mov_b32 s16, 0x24000
	s_nop 0
	v_addc_co_u32_e32 v5, vcc, 0, v3, vcc
	global_load_dword v67, v[4:5], off offset:-4096 nt
	global_load_dword v68, v[4:5], off nt
	v_add_co_u32_e32 v4, vcc, s16, v2
	s_mov_b32 s16, 0x26000
	s_nop 0
	v_addc_co_u32_e32 v5, vcc, 0, v3, vcc
	global_load_dword v69, v[4:5], off offset:-4096 nt
	global_load_dword v70, v[4:5], off nt
	v_add_co_u32_e32 v4, vcc, s16, v2
	s_mov_b32 s16, 0x28000
	s_nop 0
	v_addc_co_u32_e32 v5, vcc, 0, v3, vcc
	global_load_dword v71, v[4:5], off offset:-4096 nt
	global_load_dword v72, v[4:5], off nt
	v_add_co_u32_e32 v4, vcc, s16, v2
	s_mov_b32 s16, 0x2a000
	s_nop 0
	v_addc_co_u32_e32 v5, vcc, 0, v3, vcc
	global_load_dword v73, v[4:5], off offset:-4096 nt
	global_load_dword v74, v[4:5], off nt
	v_add_co_u32_e32 v4, vcc, s16, v2
	s_mov_b32 s16, 0x2c000
	s_nop 0
	v_addc_co_u32_e32 v5, vcc, 0, v3, vcc
	global_load_dword v75, v[4:5], off offset:-4096 nt
	global_load_dword v76, v[4:5], off nt
	v_add_co_u32_e32 v4, vcc, s16, v2
	s_mov_b32 s16, 0x2e000
	s_nop 0
	v_addc_co_u32_e32 v5, vcc, 0, v3, vcc
	global_load_dword v77, v[4:5], off offset:-4096 nt
	global_load_dword v78, v[4:5], off nt
	v_add_co_u32_e32 v4, vcc, s16, v2
	s_mov_b32 s16, 0x30000
	s_nop 0
	v_addc_co_u32_e32 v5, vcc, 0, v3, vcc
	global_load_dword v79, v[4:5], off offset:-4096 nt
	global_load_dword v80, v[4:5], off nt
	v_add_co_u32_e32 v4, vcc, s16, v2
	s_mov_b32 s16, 0x32000
	s_nop 0
	v_addc_co_u32_e32 v5, vcc, 0, v3, vcc
	global_load_dword v81, v[4:5], off offset:-4096 nt
	global_load_dword v82, v[4:5], off nt
	v_add_co_u32_e32 v4, vcc, s16, v2
	s_mov_b32 s16, 0x34000
	s_nop 0
	v_addc_co_u32_e32 v5, vcc, 0, v3, vcc
	global_load_dword v83, v[4:5], off offset:-4096 nt
	global_load_dword v84, v[4:5], off nt
	v_add_co_u32_e32 v4, vcc, s16, v2
	s_mov_b32 s16, 0x36000
	s_nop 0
	v_addc_co_u32_e32 v5, vcc, 0, v3, vcc
	global_load_dword v85, v[4:5], off offset:-4096 nt
	global_load_dword v86, v[4:5], off nt
	v_add_co_u32_e32 v4, vcc, s16, v2
	s_mov_b32 s16, 0x38000
	s_nop 0
	v_addc_co_u32_e32 v5, vcc, 0, v3, vcc
	global_load_dword v87, v[4:5], off offset:-4096 nt
	global_load_dword v88, v[4:5], off nt
	v_add_co_u32_e32 v4, vcc, s16, v2
	s_mov_b32 s16, 0x3a000
	s_nop 0
	v_addc_co_u32_e32 v5, vcc, 0, v3, vcc
	global_load_dword v89, v[4:5], off offset:-4096 nt
	global_load_dword v90, v[4:5], off nt
	v_add_co_u32_e32 v4, vcc, s16, v2
	s_mov_b32 s16, 0x3c000
	s_nop 0
	v_addc_co_u32_e32 v5, vcc, 0, v3, vcc
	global_load_dword v91, v[4:5], off offset:-4096 nt
	global_load_dword v92, v[4:5], off nt
	v_add_co_u32_e32 v4, vcc, s16, v2
	s_mov_b32 s16, 0x3e000
	s_nop 0
	v_addc_co_u32_e32 v5, vcc, 0, v3, vcc
	global_load_dword v93, v[4:5], off offset:-4096 nt
	global_load_dword v94, v[4:5], off nt
	v_add_co_u32_e32 v4, vcc, s16, v2
	s_mov_b32 s16, 0x3f000
	s_nop 0
	v_addc_co_u32_e32 v5, vcc, 0, v3, vcc
	v_add_co_u32_e32 v2, vcc, s16, v2
	global_load_dword v95, v[4:5], off offset:-4096 nt
	s_nop 0
	global_load_dword v4, v[4:5], off nt
	v_addc_co_u32_e32 v3, vcc, 0, v3, vcc
	global_load_dword v2, v[2:3], off nt
	s_waitcnt vmcnt(0)
; #define LAS __attribute__((address_space(3)))
; __device__ __forceinline__ unsigned pk2(float lo, float hi) { return pg8::cvt_pk_bf16(lo, hi); }
; template <int MODE>
; __device__ __forceinline__ void p0_item(const float* W, int K, int N, bf16u* WT, const float* ks, LAS float* scr, int item, int lane) {
;     ...
;     for (int kk = 0; kk < 64; ++kk) scr[kk * 65 + lane] = v[kk];
;     asm volatile("s_waitcnt lgkmcnt(0)" ::: "memory");
;     const int c = lane & 7;
; #pragma unroll
;     for (int j = 0; j < 8; ++j) { const int n = (lane >> 3) + 8 * j; const LAS float* s = scr + (8 * c) * 65 + n;
;         v4u o; o.x = pk2(s[0 * 65], s[1 * 65]); o.y = pk2(s[2 * 65], s[3 * 65]); o.z = pk2(s[4 * 65], s[5 * 65]); o.w = pk2(s[6 * 65], s[7 * 65]);
;         *(v4u*)(WT + (size_t)(drow + n) * K + k0 + 8 * c) = o; }
;     asm volatile("s_waitcnt lgkmcnt(0)" ::: "memory");
	ds_write2_b32 v31, v0, v6 offset1:65
	ds_write2_b32 v31, v7, v8 offset0:130 offset1:195
	v_add_u32_e32 v0, 0x400, v31
	ds_write2_b32 v0, v9, v10 offset0:4 offset1:69
	ds_write2_b32 v0, v11, v12 offset0:134 offset1:199
	v_add_u32_e32 v0, 0x800, v31
	ds_write2_b32 v0, v13, v14 offset0:8 offset1:73
	ds_write2_b32 v0, v15, v16 offset0:138 offset1:203
	v_add_u32_e32 v0, 0xc00, v31
	ds_write2_b32 v0, v17, v47 offset0:12 offset1:77
	ds_write2_b32 v0, v48, v49 offset0:142 offset1:207
	v_add_u32_e32 v0, 0x1000, v31
	ds_write2_b32 v0, v50, v51 offset0:16 offset1:81
	ds_write2_b32 v0, v52, v53 offset0:146 offset1:211
	v_add_u32_e32 v0, 0x1400, v31
	ds_write2_b32 v0, v54, v55 offset0:20 offset1:85
	ds_write2_b32 v0, v56, v57 offset0:150 offset1:215
	v_add_u32_e32 v0, 0x1800, v31
	ds_write2_b32 v0, v58, v59 offset0:24 offset1:89
	ds_write2_b32 v0, v60, v61 offset0:154 offset1:219
	v_add_u32_e32 v0, 0x1c00, v31
	ds_write2_b32 v0, v62, v63 offset0:28 offset1:93
	ds_write2_b32 v0, v64, v65 offset0:158 offset1:223
	v_add_u32_e32 v0, 0x2000, v31
	ds_write2_b32 v0, v66, v67 offset0:32 offset1:97
	ds_write2_b32 v0, v68, v69 offset0:162 offset1:227
	v_add_u32_e32 v0, 0x2400, v31
	ds_write2_b32 v0, v70, v71 offset0:36 offset1:101
	ds_write2_b32 v0, v72, v73 offset0:166 offset1:231
	v_add_u32_e32 v0, 0x2800, v31
	ds_write2_b32 v0, v74, v75 offset0:40 offset1:105
	ds_write2_b32 v0, v76, v77 offset0:170 offset1:235
	v_add_u32_e32 v0, 0x2c00, v31
	ds_write2_b32 v0, v78, v79 offset0:44 offset1:109
	ds_write2_b32 v0, v80, v81 offset0:174 offset1:239
	v_add_u32_e32 v0, 0x3000, v31
	ds_write2_b32 v0, v82, v83 offset0:48 offset1:113
	ds_write2_b32 v0, v84, v85 offset0:178 offset1:243
	v_add_u32_e32 v0, 0x3400, v31
	ds_write2_b32 v0, v86, v87 offset0:52 offset1:117
	ds_write2_b32 v0, v88, v89 offset0:182 offset1:247
	v_add_u32_e32 v0, 0x3800, v31
	ds_write2_b32 v0, v90, v91 offset0:56 offset1:121
	ds_write2_b32 v0, v92, v93 offset0:186 offset1:251
	v_add_u32_e32 v0, 0x3c00, v31
	ds_write2_b32 v0, v94, v95 offset0:60 offset1:125
	ds_write2_b32 v0, v4, v2 offset0:190 offset1:255
	s_waitcnt lgkmcnt(0)
	v_add_u32_e32 v47, 0x400, v33
	ds_read2_b32 v[8:9], v33 offset0:65 offset1:73
	ds_read2_b32 v[10:11], v33 offset1:8
	ds_read2_b32 v[12:13], v33 offset0:130 offset1:138
	ds_read2_b32 v[14:15], v33 offset0:195 offset1:203
	ds_read2_b32 v[16:17], v47 offset0:4 offset1:12
	ds_read2_b32 v[48:49], v47 offset0:69 offset1:77
	ds_read2_b32 v[50:51], v47 offset0:134 offset1:142
	ds_read2_b32 v[52:53], v47 offset0:199 offset1:207
	v_or_b32_e32 v0, s4, v32
	v_lshl_add_u64 v[2:3], v[26:27], 0, s[90:91]
	v_lshlrev_b32_e32 v0, 11, v0
	v_lshl_add_u64 v[54:55], v[2:3], 0, v[0:1]
	v_or_b32_e32 v0, s4, v34
	s_waitcnt lgkmcnt(6)
	v_cvt_pk_bf16_f32 v4, v10, v8
	s_waitcnt lgkmcnt(4)
	v_cvt_pk_bf16_f32 v5, v12, v14
	s_waitcnt lgkmcnt(2)
	v_cvt_pk_bf16_f32 v6, v16, v48
	s_waitcnt lgkmcnt(0)
	v_cvt_pk_bf16_f32 v7, v50, v52
	v_lshlrev_b32_e32 v0, 11, v0
	global_store_dwordx4 v[54:55], v[4:7], off sc1
	s_nop 1
	v_cvt_pk_bf16_f32 v4, v11, v9
	v_cvt_pk_bf16_f32 v5, v13, v15
	v_cvt_pk_bf16_f32 v6, v17, v49
	v_cvt_pk_bf16_f32 v7, v51, v53
	v_lshl_add_u64 v[8:9], v[2:3], 0, v[0:1]
	global_store_dwordx4 v[8:9], v[4:7], off sc1
	ds_read2_b32 v[8:9], v33 offset0:81 offset1:89
	ds_read2_b32 v[10:11], v33 offset0:16 offset1:24
	ds_read2_b32 v[12:13], v33 offset0:146 offset1:154
	ds_read2_b32 v[14:15], v33 offset0:211 offset1:219
	ds_read2_b32 v[16:17], v47 offset0:20 offset1:28
	ds_read2_b32 v[48:49], v47 offset0:85 offset1:93
	ds_read2_b32 v[50:51], v47 offset0:150 offset1:158
	ds_read2_b32 v[52:53], v47 offset0:215 offset1:223
	v_or_b32_e32 v0, s4, v35
	v_lshlrev_b32_e32 v0, 11, v0
	v_lshl_add_u64 v[54:55], v[2:3], 0, v[0:1]
	v_or_b32_e32 v0, s4, v36
	s_waitcnt lgkmcnt(6)
	v_cvt_pk_bf16_f32 v4, v10, v8
	s_waitcnt lgkmcnt(4)
	v_cvt_pk_bf16_f32 v5, v12, v14
	s_waitcnt lgkmcnt(2)
	v_cvt_pk_bf16_f32 v6, v16, v48
	s_waitcnt lgkmcnt(0)
	v_cvt_pk_bf16_f32 v7, v50, v52
	v_lshlrev_b32_e32 v0, 11, v0
	global_store_dwordx4 v[54:55], v[4:7], off sc1
	s_nop 1
	v_cvt_pk_bf16_f32 v4, v11, v9
	v_cvt_pk_bf16_f32 v5, v13, v15
	v_cvt_pk_bf16_f32 v6, v17, v49
	v_cvt_pk_bf16_f32 v7, v51, v53
	v_lshl_add_u64 v[8:9], v[2:3], 0, v[0:1]
	global_store_dwordx4 v[8:9], v[4:7], off sc1
	ds_read2_b32 v[8:9], v33 offset0:32 offset1:40
	ds_read2_b32 v[10:11], v33 offset0:97 offset1:105
	ds_read2_b32 v[12:13], v33 offset0:162 offset1:170
	ds_read2_b32 v[14:15], v33 offset0:227 offset1:235
	ds_read2_b32 v[16:17], v47 offset0:36 offset1:44
	ds_read2_b32 v[48:49], v47 offset0:101 offset1:109
	ds_read2_b32 v[50:51], v47 offset0:166 offset1:174
	ds_read2_b32 v[52:53], v47 offset0:231 offset1:239
	v_or_b32_e32 v0, s4, v37
	v_lshlrev_b32_e32 v0, 11, v0
	v_lshl_add_u64 v[54:55], v[2:3], 0, v[0:1]
	v_or_b32_e32 v0, s4, v38
	s_waitcnt lgkmcnt(6)
	v_cvt_pk_bf16_f32 v4, v8, v10
	s_waitcnt lgkmcnt(4)
	v_cvt_pk_bf16_f32 v5, v12, v14
	s_waitcnt lgkmcnt(2)
	v_cvt_pk_bf16_f32 v6, v16, v48
	s_waitcnt lgkmcnt(0)
	v_cvt_pk_bf16_f32 v7, v50, v52
	v_lshlrev_b32_e32 v0, 11, v0
	global_store_dwordx4 v[54:55], v[4:7], off sc1
	s_nop 1
	v_cvt_pk_bf16_f32 v4, v9, v11
	v_cvt_pk_bf16_f32 v5, v13, v15
	v_cvt_pk_bf16_f32 v6, v17, v49
	v_cvt_pk_bf16_f32 v7, v51, v53
	v_lshl_add_u64 v[8:9], v[2:3], 0, v[0:1]
	global_store_dwordx4 v[8:9], v[4:7], off sc1
	ds_read2_b32 v[8:9], v33 offset0:48 offset1:56
	ds_read2_b32 v[10:11], v33 offset0:113 offset1:121
	ds_read2_b32 v[12:13], v33 offset0:178 offset1:186
	ds_read2_b32 v[14:15], v33 offset0:243 offset1:251
	ds_read2_b32 v[16:17], v47 offset0:52 offset1:60
	ds_read2_b32 v[48:49], v47 offset0:117 offset1:125
	ds_read2_b32 v[50:51], v47 offset0:182 offset1:190
	ds_read2_b32 v[52:53], v47 offset0:247 offset1:255
	v_or_b32_e32 v0, s4, v39
	v_lshlrev_b32_e32 v0, 11, v0
	v_lshl_add_u64 v[54:55], v[2:3], 0, v[0:1]
	v_or_b32_e32 v0, s4, v40
	s_waitcnt lgkmcnt(6)
	v_cvt_pk_bf16_f32 v4, v8, v10
	s_waitcnt lgkmcnt(4)
	v_cvt_pk_bf16_f32 v5, v12, v14
	s_waitcnt lgkmcnt(2)
	v_cvt_pk_bf16_f32 v6, v16, v48
	s_waitcnt lgkmcnt(0)
	v_cvt_pk_bf16_f32 v7, v50, v52
	v_lshlrev_b32_e32 v0, 11, v0
	global_store_dwordx4 v[54:55], v[4:7], off sc1
	v_lshl_add_u64 v[2:3], v[2:3], 0, v[0:1]
	s_nop 0
	v_cvt_pk_bf16_f32 v4, v9, v11
	v_cvt_pk_bf16_f32 v5, v13, v15
	v_cvt_pk_bf16_f32 v6, v17, v49
	v_cvt_pk_bf16_f32 v7, v51, v53
	global_store_dwordx4 v[2:3], v[4:7], off sc1
	s_waitcnt lgkmcnt(0)

; template <int MODE>
; __device__ __forceinline__ void p0_item(const float* W, int K, int N, bf16u* WT, const float* ks, LAS float* scr, int item, int lane) {
;     const int nblk = N / 64, kb = item / nblk, nb = item - kb * nblk, k0 = 64 * kb, n0 = 64 * nb;
;     int nn = n0 + lane;
;     if (MODE == 1) {
;         if (nn < 2048) { const int p = nn & 63; if (p < 16) nn = (nn & ~15) | (p & 3) | ((p & 4) << 1) | ((p & 8) >> 1); }
;         else if (nn >= 4096) { const int sec = nn >= 6144 ? 6144 : 4096, r = nn - sec, q = r & 255; nn = sec + ((q >> 7) << 10) + 128 * (r >> 8) + (q & 127); }
;     }
;     int drow = n0;
;     if (MODE == 2) drow = 256 * (n0 >> 7) + (n0 & 127);
;     if (MODE == 3) drow = 256 * (n0 >> 7) + 128 + (n0 & 127);
;     const float* src = W + (size_t)k0 * N + nn;
;     float v[64];
; #pragma unroll
;     for (int kk = 0; kk < 64; ++kk) v[kk] = src[(size_t)kk * N];
.LBB0_618:
	s_andn2_b64 vcc, exec, s[16:17]
	s_cbranch_vccnz .LBB0_620
	s_add_i32 s4, s53, 0xffffe000
	s_and_b32 s12, s4, 0xfc0
	s_add_i32 s4, s52, s59
	s_add_i32 s4, s4, 0xfffe0000
	s_and_b32 s4, s4, 0x3c0
	s_lshl_b32 s16, s12, 12
	v_or_b32_e32 v0, s4, v30
	s_add_u32 s16, s47, s16
	s_addc_u32 s17, s24, 0
	v_lshlrev_b32_e32 v0, 2, v0
	v_lshl_add_u64 v[2:3], s[16:17], 0, v[0:1]
	v_add_co_u32_e32 v4, vcc, s61, v2
	global_load_dword v0, v0, s[16:17] nt
	s_nop 0
	v_addc_co_u32_e32 v5, vcc, 0, v3, vcc
	s_movk_i32 s16, 0x4000
	global_load_dword v6, v[4:5], off offset:-4096 nt
	global_load_dword v7, v[4:5], off nt
	v_add_co_u32_e32 v4, vcc, s16, v2
	s_movk_i32 s16, 0x6000
	s_nop 0
	v_addc_co_u32_e32 v5, vcc, 0, v3, vcc
	global_load_dword v8, v[4:5], off offset:-4096 nt
	global_load_dword v9, v[4:5], off nt
	v_add_co_u32_e32 v4, vcc, s16, v2
	s_mov_b32 s16, 0xe000
	s_nop 0
	v_addc_co_u32_e32 v5, vcc, 0, v3, vcc
	global_load_dword v10, v[4:5], off offset:-4096 nt
	global_load_dword v11, v[4:5], off nt
	v_add_co_u32_e32 v4, vcc, s88, v2
	s_lshl_b32 s90, s12, 1
	s_nop 0
	v_addc_co_u32_e32 v5, vcc, 0, v3, vcc
	global_load_dword v12, v[4:5], off offset:-4096 nt
	global_load_dword v13, v[4:5], off nt
	v_add_co_u32_e32 v4, vcc, s27, v2
	s_nop 1
	v_addc_co_u32_e32 v5, vcc, 0, v3, vcc
	global_load_dword v14, v[4:5], off offset:-4096 nt
	global_load_dword v15, v[4:5], off nt
	v_add_co_u32_e32 v4, vcc, s26, v2
	s_nop 1
	v_addc_co_u32_e32 v5, vcc, 0, v3, vcc
	global_load_dword v16, v[4:5], off offset:-4096 nt
	global_load_dword v17, v[4:5], off nt
	v_add_co_u32_e32 v4, vcc, s16, v2
	s_mov_b32 s16, 0x10000
	s_nop 0
	v_addc_co_u32_e32 v5, vcc, 0, v3, vcc
	global_load_dword v47, v[4:5], off offset:-4096 nt
	global_load_dword v48, v[4:5], off nt
	v_add_co_u32_e32 v4, vcc, s16, v2
	s_mov_b32 s16, 0x14000
	s_nop 0
	v_addc_co_u32_e32 v5, vcc, 0, v3, vcc
	global_load_dword v49, v[4:5], off offset:-4096 nt
	global_load_dword v50, v[4:5], off nt
	v_add_co_u32_e32 v4, vcc, s22, v2
	s_nop 1
	v_addc_co_u32_e32 v5, vcc, 0, v3, vcc
	global_load_dword v51, v[4:5], off offset:-4096 nt
	global_load_dword v52, v[4:5], off nt
	v_add_co_u32_e32 v4, vcc, s16, v2
	s_mov_b32 s16, 0x16000
	s_nop 0
	v_addc_co_u32_e32 v5, vcc, 0, v3, vcc
	global_load_dword v53, v[4:5], off offset:-4096 nt
	global_load_dword v54, v[4:5], off nt
	v_add_co_u32_e32 v4, vcc, s16, v2
	s_mov_b32 s16, 0x1a000
	s_nop 0
	v_addc_co_u32_e32 v5, vcc, 0, v3, vcc
	global_load_dword v55, v[4:5], off offset:-4096 nt
	global_load_dword v56, v[4:5], off nt
	v_add_co_u32_e32 v4, vcc, s5, v2
	s_nop 1
	v_addc_co_u32_e32 v5, vcc, 0, v3, vcc
	global_load_dword v57, v[4:5], off offset:-4096 nt
	global_load_dword v58, v[4:5], off nt
	v_add_co_u32_e32 v4, vcc, s16, v2
	s_mov_b32 s16, 0x1c000
	s_nop 0
	v_addc_co_u32_e32 v5, vcc, 0, v3, vcc
	global_load_dword v59, v[4:5], off offset:-4096 nt
	global_load_dword v60, v[4:5], off nt
	v_add_co_u32_e32 v4, vcc, s16, v2
	s_mov_b32 s16, 0x1e000
	s_nop 0
	v_addc_co_u32_e32 v5, vcc, 0, v3, vcc
	global_load_dword v61, v[4:5], off offset:-4096 nt
	global_load_dword v62, v[4:5], off nt
	v_add_co_u32_e32 v4, vcc, s16, v2
	s_mov_b32 s16, 0x20000
	s_nop 0
	v_addc_co_u32_e32 v5, vcc, 0, v3, vcc
	global_load_dword v63, v[4:5], off offset:-4096 nt
	global_load_dword v64, v[4:5], off nt
	v_add_co_u32_e32 v4, vcc, s16, v2
	s_mov_b32 s16, 0x22000
	s_nop 0
	v_addc_co_u32_e32 v5, vcc, 0, v3, vcc
	global_load_dword v65, v[4:5], off offset:-4096 nt
	global_load_dword v66, v[4:5], off nt
	v_add_co_u32_e32 v4, vcc, s16, v2
	s_mov_b32 s16, 0x24000
	s_nop 0
	v_addc_co_u32_e32 v5, vcc, 0, v3, vcc
	global_load_dword v67, v[4:5], off offset:-4096 nt
	global_load_dword v68, v[4:5], off nt
	v_add_co_u32_e32 v4, vcc, s16, v2
	s_mov_b32 s16, 0x26000
	s_nop 0
	v_addc_co_u32_e32 v5, vcc, 0, v3, vcc
	global_load_dword v69, v[4:5], off offset:-4096 nt
	global_load_dword v70, v[4:5], off nt
	v_add_co_u32_e32 v4, vcc, s16, v2
	s_mov_b32 s16, 0x28000
	s_nop 0
	v_addc_co_u32_e32 v5, vcc, 0, v3, vcc
	global_load_dword v71, v[4:5], off offset:-4096 nt
	global_load_dword v72, v[4:5], off nt
	v_add_co_u32_e32 v4, vcc, s16, v2
	s_mov_b32 s16, 0x2a000
	s_nop 0
	v_addc_co_u32_e32 v5, vcc, 0, v3, vcc
	global_load_dword v73, v[4:5], off offset:-4096 nt
	global_load_dword v74, v[4:5], off nt
	v_add_co_u32_e32 v4, vcc, s16, v2
	s_mov_b32 s16, 0x2c000
	s_nop 0
	v_addc_co_u32_e32 v5, vcc, 0, v3, vcc
	global_load_dword v75, v[4:5], off offset:-4096 nt
	global_load_dword v76, v[4:5], off nt
	v_add_co_u32_e32 v4, vcc, s16, v2
	s_mov_b32 s16, 0x2e000
	s_nop 0
	v_addc_co_u32_e32 v5, vcc, 0, v3, vcc
	global_load_dword v77, v[4:5], off offset:-4096 nt
	global_load_dword v78, v[4:5], off nt
	v_add_co_u32_e32 v4, vcc, s16, v2
	s_mov_b32 s16, 0x30000
	s_nop 0
	v_addc_co_u32_e32 v5, vcc, 0, v3, vcc
	global_load_dword v79, v[4:5], off offset:-4096 nt
	global_load_dword v80, v[4:5], off nt
	v_add_co_u32_e32 v4, vcc, s16, v2
	s_mov_b32 s16, 0x32000
	s_nop 0
	v_addc_co_u32_e32 v5, vcc, 0, v3, vcc
	global_load_dword v81, v[4:5], off offset:-4096 nt
	global_load_dword v82, v[4:5], off nt
	v_add_co_u32_e32 v4, vcc, s16, v2
	s_mov_b32 s16, 0x34000
	s_nop 0
	v_addc_co_u32_e32 v5, vcc, 0, v3, vcc
	global_load_dword v83, v[4:5], off offset:-4096 nt
	global_load_dword v84, v[4:5], off nt
	v_add_co_u32_e32 v4, vcc, s16, v2
	s_mov_b32 s16, 0x36000
	s_nop 0
	v_addc_co_u32_e32 v5, vcc, 0, v3, vcc
	global_load_dword v85, v[4:5], off offset:-4096 nt
	global_load_dword v86, v[4:5], off nt
	v_add_co_u32_e32 v4, vcc, s16, v2
	s_mov_b32 s16, 0x38000
	s_nop 0
	v_addc_co_u32_e32 v5, vcc, 0, v3, vcc
	global_load_dword v87, v[4:5], off offset:-4096 nt
	global_load_dword v88, v[4:5], off nt
	v_add_co_u32_e32 v4, vcc, s16, v2
	s_mov_b32 s16, 0x3a000
	s_nop 0
	v_addc_co_u32_e32 v5, vcc, 0, v3, vcc
	global_load_dword v89, v[4:5], off offset:-4096 nt
	global_load_dword v90, v[4:5], off nt
	v_add_co_u32_e32 v4, vcc, s16, v2
	s_mov_b32 s16, 0x3c000
	s_nop 0
	v_addc_co_u32_e32 v5, vcc, 0, v3, vcc
	global_load_dword v91, v[4:5], off offset:-4096 nt
	global_load_dword v92, v[4:5], off nt
	v_add_co_u32_e32 v4, vcc, s16, v2
	s_mov_b32 s16, 0x3e000
	s_nop 0
	v_addc_co_u32_e32 v5, vcc, 0, v3, vcc
	global_load_dword v93, v[4:5], off offset:-4096 nt
	global_load_dword v94, v[4:5], off nt
	v_add_co_u32_e32 v4, vcc, s16, v2
	s_mov_b32 s16, 0x3f000
	s_nop 0
	v_addc_co_u32_e32 v5, vcc, 0, v3, vcc
	v_add_co_u32_e32 v2, vcc, s16, v2
	global_load_dword v95, v[4:5], off offset:-4096 nt
	s_nop 0
	global_load_dword v4, v[4:5], off nt
	v_addc_co_u32_e32 v3, vcc, 0, v3, vcc
	global_load_dword v2, v[2:3], off nt
	s_waitcnt vmcnt(0)
; #define LAS __attribute__((address_space(3)))
; __device__ __forceinline__ unsigned pk2(float lo, float hi) { return pg8::cvt_pk_bf16(lo, hi); }
; template <int MODE>
; __device__ __forceinline__ void p0_item(const float* W, int K, int N, bf16u* WT, const float* ks, LAS float* scr, int item, int lane) {
;     ...
;     for (int kk = 0; kk < 64; ++kk) scr[kk * 65 + lane] = v[kk];
;     asm volatile("s_waitcnt lgkmcnt(0)" ::: "memory");
;     const int c = lane & 7;
; #pragma unroll
;     for (int j = 0; j < 8; ++j) { const int n = (lane >> 3) + 8 * j; const LAS float* s = scr + (8 * c) * 65 + n;
;         v4u o; o.x = pk2(s[0 * 65], s[1 * 65]); o.y = pk2(s[2 * 65], s[3 * 65]); o.z = pk2(s[4 * 65], s[5 * 65]); o.w = pk2(s[6 * 65], s[7 * 65]);
;         *(v4u*)(WT + (size_t)(drow + n) * K + k0 + 8 * c) = o; }
;     asm volatile("s_waitcnt lgkmcnt(0)" ::: "memory");
	ds_write2_b32 v31, v0, v6 offset1:65
	ds_write2_b32 v31, v7, v8 offset0:130 offset1:195
	v_add_u32_e32 v0, 0x400, v31
	ds_write2_b32 v0, v9, v10 offset0:4 offset1:69
	ds_write2_b32 v0, v11, v12 offset0:134 offset1:199
	v_add_u32_e32 v0, 0x800, v31
	ds_write2_b32 v0, v13, v14 offset0:8 offset1:73
	ds_write2_b32 v0, v15, v16 offset0:138 offset1:203
	v_add_u32_e32 v0, 0xc00, v31
	ds_write2_b32 v0, v17, v47 offset0:12 offset1:77
	ds_write2_b32 v0, v48, v49 offset0:142 offset1:207
	v_add_u32_e32 v0, 0x1000, v31
	ds_write2_b32 v0, v50, v51 offset0:16 offset1:81
	ds_write2_b32 v0, v52, v53 offset0:146 offset1:211
	v_add_u32_e32 v0, 0x1400, v31
	ds_write2_b32 v0, v54, v55 offset0:20 offset1:85
	ds_write2_b32 v0, v56, v57 offset0:150 offset1:215
	v_add_u32_e32 v0, 0x1800, v31
	ds_write2_b32 v0, v58, v59 offset0:24 offset1:89
	ds_write2_b32 v0, v60, v61 offset0:154 offset1:219
	v_add_u32_e32 v0, 0x1c00, v31
	ds_write2_b32 v0, v62, v63 offset0:28 offset1:93
	ds_write2_b32 v0, v64, v65 offset0:158 offset1:223
	v_add_u32_e32 v0, 0x2000, v31
	ds_write2_b32 v0, v66, v67 offset0:32 offset1:97
	ds_write2_b32 v0, v68, v69 offset0:162 offset1:227
	v_add_u32_e32 v0, 0x2400, v31
	ds_write2_b32 v0, v70, v71 offset0:36 offset1:101
	ds_write2_b32 v0, v72, v73 offset0:166 offset1:231
	v_add_u32_e32 v0, 0x2800, v31
	ds_write2_b32 v0, v74, v75 offset0:40 offset1:105
	ds_write2_b32 v0, v76, v77 offset0:170 offset1:235
	v_add_u32_e32 v0, 0x2c00, v31
	ds_write2_b32 v0, v78, v79 offset0:44 offset1:109
	ds_write2_b32 v0, v80, v81 offset0:174 offset1:239
	v_add_u32_e32 v0, 0x3000, v31
	ds_write2_b32 v0, v82, v83 offset0:48 offset1:113
	ds_write2_b32 v0, v84, v85 offset0:178 offset1:243
	v_add_u32_e32 v0, 0x3400, v31
	ds_write2_b32 v0, v86, v87 offset0:52 offset1:117
	ds_write2_b32 v0, v88, v89 offset0:182 offset1:247
	v_add_u32_e32 v0, 0x3800, v31
	ds_write2_b32 v0, v90, v91 offset0:56 offset1:121
	ds_write2_b32 v0, v92, v93 offset0:186 offset1:251
	v_add_u32_e32 v0, 0x3c00, v31
	ds_write2_b32 v0, v94, v95 offset0:60 offset1:125
	ds_write2_b32 v0, v4, v2 offset0:190 offset1:255
	s_waitcnt lgkmcnt(0)
	v_add_u32_e32 v47, 0x400, v33
	ds_read2_b32 v[8:9], v33 offset0:65 offset1:73
	ds_read2_b32 v[10:11], v33 offset1:8
	ds_read2_b32 v[12:13], v33 offset0:130 offset1:138
	ds_read2_b32 v[14:15], v33 offset0:195 offset1:203
	ds_read2_b32 v[16:17], v47 offset0:4 offset1:12
	ds_read2_b32 v[48:49], v47 offset0:69 offset1:77
	ds_read2_b32 v[50:51], v47 offset0:134 offset1:142
	ds_read2_b32 v[52:53], v47 offset0:199 offset1:207
	v_or_b32_e32 v0, s4, v32
	v_lshl_add_u64 v[2:3], v[28:29], 0, s[90:91]
	v_lshlrev_b32_e32 v0, 11, v0
	v_lshl_add_u64 v[54:55], v[2:3], 0, v[0:1]
	v_or_b32_e32 v0, s4, v34
	s_waitcnt lgkmcnt(6)
	v_cvt_pk_bf16_f32 v4, v10, v8
	s_waitcnt lgkmcnt(4)
	v_cvt_pk_bf16_f32 v5, v12, v14
	s_waitcnt lgkmcnt(2)
	v_cvt_pk_bf16_f32 v6, v16, v48
	s_waitcnt lgkmcnt(0)
	v_cvt_pk_bf16_f32 v7, v50, v52
	v_lshlrev_b32_e32 v0, 11, v0
	global_store_dwordx4 v[54:55], v[4:7], off sc1
	s_nop 1
	v_cvt_pk_bf16_f32 v4, v11, v9
	v_cvt_pk_bf16_f32 v5, v13, v15
	v_cvt_pk_bf16_f32 v6, v17, v49
	v_cvt_pk_bf16_f32 v7, v51, v53
	v_lshl_add_u64 v[8:9], v[2:3], 0, v[0:1]
	global_store_dwordx4 v[8:9], v[4:7], off sc1
	ds_read2_b32 v[8:9], v33 offset0:81 offset1:89
	ds_read2_b32 v[10:11], v33 offset0:16 offset1:24
	ds_read2_b32 v[12:13], v33 offset0:146 offset1:154
	ds_read2_b32 v[14:15], v33 offset0:211 offset1:219
	ds_read2_b32 v[16:17], v47 offset0:20 offset1:28
	ds_read2_b32 v[48:49], v47 offset0:85 offset1:93
	ds_read2_b32 v[50:51], v47 offset0:150 offset1:158
	ds_read2_b32 v[52:53], v47 offset0:215 offset1:223
	v_or_b32_e32 v0, s4, v35
	v_lshlrev_b32_e32 v0, 11, v0
	v_lshl_add_u64 v[54:55], v[2:3], 0, v[0:1]
	v_or_b32_e32 v0, s4, v36
	s_waitcnt lgkmcnt(6)
	v_cvt_pk_bf16_f32 v4, v10, v8
	s_waitcnt lgkmcnt(4)
	v_cvt_pk_bf16_f32 v5, v12, v14
	s_waitcnt lgkmcnt(2)
	v_cvt_pk_bf16_f32 v6, v16, v48
	s_waitcnt lgkmcnt(0)
	v_cvt_pk_bf16_f32 v7, v50, v52
	v_lshlrev_b32_e32 v0, 11, v0
	global_store_dwordx4 v[54:55], v[4:7], off sc1
	s_nop 1
	v_cvt_pk_bf16_f32 v4, v11, v9
	v_cvt_pk_bf16_f32 v5, v13, v15
	v_cvt_pk_bf16_f32 v6, v17, v49
	v_cvt_pk_bf16_f32 v7, v51, v53
	v_lshl_add_u64 v[8:9], v[2:3], 0, v[0:1]
	global_store_dwordx4 v[8:9], v[4:7], off sc1
	ds_read2_b32 v[8:9], v33 offset0:32 offset1:40
	ds_read2_b32 v[10:11], v33 offset0:97 offset1:105
	ds_read2_b32 v[12:13], v33 offset0:162 offset1:170
	ds_read2_b32 v[14:15], v33 offset0:227 offset1:235
	ds_read2_b32 v[16:17], v47 offset0:36 offset1:44
	ds_read2_b32 v[48:49], v47 offset0:101 offset1:109
	ds_read2_b32 v[50:51], v47 offset0:166 offset1:174
	ds_read2_b32 v[52:53], v47 offset0:231 offset1:239
	v_or_b32_e32 v0, s4, v37
	v_lshlrev_b32_e32 v0, 11, v0
	v_lshl_add_u64 v[54:55], v[2:3], 0, v[0:1]
	v_or_b32_e32 v0, s4, v38
	s_waitcnt lgkmcnt(6)
	v_cvt_pk_bf16_f32 v4, v8, v10
	s_waitcnt lgkmcnt(4)
	v_cvt_pk_bf16_f32 v5, v12, v14
	s_waitcnt lgkmcnt(2)
	v_cvt_pk_bf16_f32 v6, v16, v48
	s_waitcnt lgkmcnt(0)
	v_cvt_pk_bf16_f32 v7, v50, v52
	v_lshlrev_b32_e32 v0, 11, v0
	global_store_dwordx4 v[54:55], v[4:7], off sc1
	s_nop 1
	v_cvt_pk_bf16_f32 v4, v9, v11
	v_cvt_pk_bf16_f32 v5, v13, v15
	v_cvt_pk_bf16_f32 v6, v17, v49
	v_cvt_pk_bf16_f32 v7, v51, v53
	v_lshl_add_u64 v[8:9], v[2:3], 0, v[0:1]
	global_store_dwordx4 v[8:9], v[4:7], off sc1
	ds_read2_b32 v[8:9], v33 offset0:48 offset1:56
	ds_read2_b32 v[10:11], v33 offset0:113 offset1:121
	ds_read2_b32 v[12:13], v33 offset0:178 offset1:186
	ds_read2_b32 v[14:15], v33 offset0:243 offset1:251
	ds_read2_b32 v[16:17], v47 offset0:52 offset1:60
	ds_read2_b32 v[48:49], v47 offset0:117 offset1:125
	ds_read2_b32 v[50:51], v47 offset0:182 offset1:190
	ds_read2_b32 v[52:53], v47 offset0:247 offset1:255
	v_or_b32_e32 v0, s4, v39
	v_lshlrev_b32_e32 v0, 11, v0
	v_lshl_add_u64 v[54:55], v[2:3], 0, v[0:1]
	v_or_b32_e32 v0, s4, v40
	s_waitcnt lgkmcnt(6)
	v_cvt_pk_bf16_f32 v4, v8, v10
	s_waitcnt lgkmcnt(4)
	v_cvt_pk_bf16_f32 v5, v12, v14
	s_waitcnt lgkmcnt(2)
	v_cvt_pk_bf16_f32 v6, v16, v48
	s_waitcnt lgkmcnt(0)
	v_cvt_pk_bf16_f32 v7, v50, v52
	v_lshlrev_b32_e32 v0, 11, v0
	global_store_dwordx4 v[54:55], v[4:7], off sc1
	v_lshl_add_u64 v[2:3], v[2:3], 0, v[0:1]
	s_nop 0
	v_cvt_pk_bf16_f32 v4, v9, v11
	v_cvt_pk_bf16_f32 v5, v13, v15
	v_cvt_pk_bf16_f32 v6, v17, v49
	v_cvt_pk_bf16_f32 v7, v51, v53
	global_store_dwordx4 v[2:3], v[4:7], off sc1
	s_waitcnt lgkmcnt(0)
